# removed 28 provably redundant s_waitcnt lgkmcnt(0) between s_setprio 1 and the first MFMA of each GEMM super-phase (same wait already executed before the barrier, no LDS op in between)
# baseline (speedup 1.0000x reference)
; #define PG8_STAGE(bufoff, gbase, voff) do { _Pragma("unroll") for (int _i = 0; _i < 2; ++_i) \
;         __builtin_amdgcn_global_load_lds((const unsigned*)((const char*)(gbase) + (voff)[_i]), (PG8_LAS unsigned*)(lds + (bufoff) + ldsw + _i * 8192), 16, 0, 0); } while (0)
; #define PG8_LDA(dst, b, h) do { _Pragma("unroll") for (int m = 0; m < 4; ++m) _Pragma("unroll") for (int k = 0; k < 2; ++k) dst[m][k] = *(const PG8_LAS bf16x8*)(lds + PG8_SA(b, h) + aoff + m * 2048 + k * 1024); } while (0)
; #define PG8_LDB(dst, b, h) do { _Pragma("unroll") for (int n = 0; n < 2; ++n) _Pragma("unroll") for (int k = 0; k < 2; ++k) dst[n][k] = *(const PG8_LAS bf16x8*)(lds + PG8_SB(b, h) + boff + n * 2048 + k * 1024); } while (0)
; #define PG8_MMA(ai, bj, At, Bt) do { __builtin_amdgcn_s_setprio(1); _Pragma("unroll") for (int m = 0; m < 4; ++m) _Pragma("unroll") for (int n = 0; n < 2; ++n) _Pragma("unroll") for (int k = 0; k < 2; ++k) \
;         acc[ai][bj][m][n] = __builtin_amdgcn_mfma_f32_16x16x32_bf16(Bt[n][k], At[m][k], acc[ai][bj][m][n], 0, 0, 0); __builtin_amdgcn_s_setprio(0); } while (0)
; #define PG8_WAIT_V(n) asm volatile("s_waitcnt vmcnt(" #n ")" ::: "memory")
; #define PG8_BAR __builtin_amdgcn_s_barrier()
; template <class Epi, class Sched, bool ALIGN_EPI = false, bool SP2 = false>
; __device__ __forceinline__ void gemm_phase(PG8_LAS unsigned char* lds, const Gemm g, const Sched& S, const Epi& E) {
;     ...
;         for (int t = 0; t < nt; t += 2) {
;             const bool last = (t == nt - 2);
;             const char* a1 = cA + (size_t)(t + 1) * kstep;
;             const char* a2 = last ? nA : cA + (size_t)(t + 2) * kstep; const char* b2 = last ? nB : cB + (size_t)(t + 2) * kstep;
;             const char* a3 = a2 + kstep; const char* b3 = b2 + kstep;
;             if (last && has_next) S.a_ready(nxt);
;             if constexpr (SP2) {
;             PG8_LDB(B0, 0, 0); PG8_LDB(B1, 0, 1); PG8_SCHED; PG8_LDA(At, 0, 0); PG8_STAGE(PG8_SA(1, 1), a1 + hstep, voffA);
;             PG8_WAIT_V(8); PG8_WAIT_L(0); PG8_BAR; PG8_MMA(0, 0, At, B0); PG8_MMA(0, 1, At, B1); PG8_BAR; PG8_SCHED;
;             PG8_LDA(At, 0, 1); PG8_STAGE(PG8_SB(0, 0), b2, voffB); PG8_STAGE(PG8_SB(0, 1), b2 + hstep, voffB); PG8_STAGE(PG8_SA(0, 0), a2, voffA);
;             PG8_WAIT_V(8); PG8_WAIT_L(0); PG8_BAR; PG8_MMA(1, 0, At, B0); PG8_MMA(1, 1, At, B1); PG8_BAR; PG8_SCHED;
.LBB0_301:
	s_add_u32 s26, s24, 0xfffc0080
	s_addc_u32 s27, s25, -1
	s_add_i32 s48, 0, 0x10000
	s_cmp_eq_u32 s47, 12
	s_cselect_b32 s29, s13, s27
	s_cselect_b32 s28, s21, s26
	v_add_u32_e32 v154, s48, v156
	s_cselect_b32 s27, s11, s46
	s_cselect_b32 s26, s44, s45
	s_add_i32 s50, 0, 0x14000
	ds_read_b128 v[94:97], v154
	ds_read_b128 v[134:137], v154 offset:1024
	ds_read_b128 v[158:161], v154 offset:2048
	ds_read_b128 v[162:165], v154 offset:3072
	v_add_u32_e32 v154, s50, v156
	ds_read_b128 v[166:169], v154
	ds_read_b128 v[170:173], v154 offset:1024
	ds_read_b128 v[174:177], v154 offset:2048
	ds_read_b128 v[186:189], v154 offset:3072
	v_lshl_add_u64 v[154:155], s[24:25], 0, v[150:151]
	s_add_i32 m0, s23, 0xc000
	ds_read_b128 v[190:193], v157
	ds_read_b128 v[194:197], v157 offset:1024
	ds_read_b128 v[198:201], v157 offset:2048
	ds_read_b128 v[202:205], v157 offset:3072
	ds_read_b128 v[206:209], v157 offset:4096
	ds_read_b128 v[210:213], v157 offset:5120
	ds_read_b128 v[214:217], v157 offset:6144
	ds_read_b128 v[218:221], v157 offset:7168
	global_load_lds_dwordx4 v[154:155], off
	v_lshl_add_u64 v[154:155], s[24:25], 0, v[152:153]
	s_add_i32 m0, s23, 0xe000
	s_nop 0
	global_load_lds_dwordx4 v[154:155], off
	s_waitcnt vmcnt(8)
	s_waitcnt lgkmcnt(0)
	s_barrier
	s_setprio 1
	v_mfma_f32_16x16x32_bf16 v[130:133], v[94:97], v[190:193], v[130:133]
	v_mfma_f32_16x16x32_bf16 v[126:129], v[158:161], v[190:193], v[126:129]
	v_mfma_f32_16x16x32_bf16 v[114:117], v[94:97], v[198:201], v[114:117]
	v_mfma_f32_16x16x32_bf16 v[110:113], v[158:161], v[198:201], v[110:113]
	v_mfma_f32_16x16x32_bf16 v[98:101], v[94:97], v[206:209], v[98:101]
	v_mfma_f32_16x16x32_bf16 v[90:93], v[158:161], v[206:209], v[90:93]
	v_mfma_f32_16x16x32_bf16 v[78:81], v[94:97], v[214:217], v[78:81]
	v_mfma_f32_16x16x32_bf16 v[74:77], v[158:161], v[214:217], v[74:77]
	v_mfma_f32_16x16x32_bf16 v[130:133], v[134:137], v[194:197], v[130:133]
	v_mfma_f32_16x16x32_bf16 v[126:129], v[162:165], v[194:197], v[126:129]
	v_mfma_f32_16x16x32_bf16 v[114:117], v[134:137], v[202:205], v[114:117]
	v_mfma_f32_16x16x32_bf16 v[110:113], v[162:165], v[202:205], v[110:113]
	v_mfma_f32_16x16x32_bf16 v[98:101], v[134:137], v[210:213], v[98:101]
	v_mfma_f32_16x16x32_bf16 v[90:93], v[162:165], v[210:213], v[90:93]
	v_mfma_f32_16x16x32_bf16 v[78:81], v[134:137], v[218:221], v[78:81]
	v_mfma_f32_16x16x32_bf16 v[74:77], v[162:165], v[218:221], v[74:77]
	s_setprio 0
	s_setprio 1
	v_mfma_f32_16x16x32_bf16 v[122:125], v[166:169], v[190:193], v[122:125]
	v_mfma_f32_16x16x32_bf16 v[118:121], v[174:177], v[190:193], v[118:121]
	v_mfma_f32_16x16x32_bf16 v[106:109], v[166:169], v[198:201], v[106:109]
	v_mfma_f32_16x16x32_bf16 v[102:105], v[174:177], v[198:201], v[102:105]
	v_mfma_f32_16x16x32_bf16 v[86:89], v[166:169], v[206:209], v[86:89]
	v_mfma_f32_16x16x32_bf16 v[82:85], v[174:177], v[206:209], v[82:85]
	v_mfma_f32_16x16x32_bf16 v[70:73], v[166:169], v[214:217], v[70:73]
	v_mfma_f32_16x16x32_bf16 v[66:69], v[174:177], v[214:217], v[66:69]
	v_mfma_f32_16x16x32_bf16 v[122:125], v[170:173], v[194:197], v[122:125]
	v_mfma_f32_16x16x32_bf16 v[118:121], v[186:189], v[194:197], v[118:121]
	v_mfma_f32_16x16x32_bf16 v[106:109], v[170:173], v[202:205], v[106:109]
	v_mfma_f32_16x16x32_bf16 v[102:105], v[186:189], v[202:205], v[102:105]
	v_mfma_f32_16x16x32_bf16 v[86:89], v[170:173], v[210:213], v[86:89]
	v_mfma_f32_16x16x32_bf16 v[82:85], v[186:189], v[210:213], v[82:85]
	v_mfma_f32_16x16x32_bf16 v[70:73], v[170:173], v[218:221], v[70:73]
	v_mfma_f32_16x16x32_bf16 v[66:69], v[186:189], v[218:221], v[66:69]
	s_setprio 0
	s_barrier
	s_add_i32 s48, s48, s35
	v_lshl_add_u64 v[154:155], s[26:27], 0, v[142:143]
	s_mov_b32 m0, s48
	ds_read_b128 v[190:193], v157 offset:16384
	ds_read_b128 v[194:197], v157 offset:17408
	ds_read_b128 v[198:201], v157 offset:18432
	ds_read_b128 v[202:205], v157 offset:19456
	ds_read_b128 v[206:209], v157 offset:20480
	ds_read_b128 v[210:213], v157 offset:21504
	ds_read_b128 v[214:217], v157 offset:22528
	ds_read_b128 v[218:221], v157 offset:23552
	global_load_lds_dwordx4 v[154:155], off
	s_add_i32 m0, s48, 0x2000
	s_add_u32 s48, s26, 0x40000
	v_lshl_add_u64 v[180:181], s[26:27], 0, v[138:139]
	s_addc_u32 s49, s27, 0
	s_add_i32 s50, s50, s35
	global_load_lds_dwordx4 v[180:181], off
	v_lshl_add_u64 v[182:183], s[48:49], 0, v[142:143]
	s_mov_b32 m0, s50
	v_lshl_add_u64 v[222:223], s[28:29], 0, v[140:141]
	global_load_lds_dwordx4 v[182:183], off
	v_lshl_add_u64 v[182:183], s[48:49], 0, v[138:139]
	s_add_i32 m0, s50, 0x2000
	s_nop 0
	global_load_lds_dwordx4 v[182:183], off
	v_lshl_add_u64 v[182:183], s[28:29], 0, v[144:145]
	s_mov_b32 m0, s23
	s_nop 0
	global_load_lds_dwordx4 v[182:183], off
	s_mov_b32 m0, s37
	s_nop 0
	global_load_lds_dwordx4 v[222:223], off
	s_waitcnt vmcnt(8)
	s_waitcnt lgkmcnt(0)
	s_barrier
; #define PG8_STAGE(bufoff, gbase, voff) do { _Pragma("unroll") for (int _i = 0; _i < 2; ++_i) \
;         __builtin_amdgcn_global_load_lds((const unsigned*)((const char*)(gbase) + (voff)[_i]), (PG8_LAS unsigned*)(lds + (bufoff) + ldsw + _i * 8192), 16, 0, 0); } while (0)
; #define PG8_LDA(dst, b, h) do { _Pragma("unroll") for (int m = 0; m < 4; ++m) _Pragma("unroll") for (int k = 0; k < 2; ++k) dst[m][k] = *(const PG8_LAS bf16x8*)(lds + PG8_SA(b, h) + aoff + m * 2048 + k * 1024); } while (0)
; #define PG8_LDB(dst, b, h) do { _Pragma("unroll") for (int n = 0; n < 2; ++n) _Pragma("unroll") for (int k = 0; k < 2; ++k) dst[n][k] = *(const PG8_LAS bf16x8*)(lds + PG8_SB(b, h) + boff + n * 2048 + k * 1024); } while (0)
; #define PG8_MMA(ai, bj, At, Bt) do { __builtin_amdgcn_s_setprio(1); _Pragma("unroll") for (int m = 0; m < 4; ++m) _Pragma("unroll") for (int n = 0; n < 2; ++n) _Pragma("unroll") for (int k = 0; k < 2; ++k) \
;         acc[ai][bj][m][n] = __builtin_amdgcn_mfma_f32_16x16x32_bf16(Bt[n][k], At[m][k], acc[ai][bj][m][n], 0, 0, 0); __builtin_amdgcn_s_setprio(0); } while (0)
; #define PG8_WAIT_V(n) asm volatile("s_waitcnt vmcnt(" #n ")" ::: "memory")
; #define PG8_WAIT_L(n) asm volatile("s_waitcnt lgkmcnt(" #n ")" ::: "memory")
; #define PG8_BAR __builtin_amdgcn_s_barrier()
; #define PG8_SCHED __builtin_amdgcn_sched_barrier(0)
; template <class Epi, class Sched, bool ALIGN_EPI = false, bool SP2 = false>
; __device__ __forceinline__ void gemm_phase(PG8_LAS unsigned char* lds, const Gemm g, const Sched& S, const Epi& E) {
;     ...
;             PG8_WAIT_V(8); PG8_WAIT_L(0); PG8_BAR; PG8_MMA(1, 0, At, B0); PG8_MMA(1, 1, At, B1); PG8_BAR; PG8_SCHED;
;             PG8_LDB(B0, 1, 0); PG8_LDB(B1, 1, 1); PG8_SCHED; PG8_LDA(At, 1, 0); PG8_STAGE(PG8_SA(0, 1), a2 + hstep, voffA);
;             PG8_WAIT_V(8); PG8_WAIT_L(0); PG8_BAR; PG8_MMA(0, 0, At, B0); PG8_MMA(0, 1, At, B1); PG8_BAR; PG8_SCHED;
	s_setprio 1
	v_mfma_f32_16x16x32_bf16 v[62:65], v[94:97], v[190:193], v[62:65]
	v_mfma_f32_16x16x32_bf16 v[58:61], v[158:161], v[190:193], v[58:61]
	v_mfma_f32_16x16x32_bf16 v[50:53], v[94:97], v[198:201], v[50:53]
	v_mfma_f32_16x16x32_bf16 v[42:45], v[158:161], v[198:201], v[42:45]
	v_mfma_f32_16x16x32_bf16 v[34:37], v[94:97], v[206:209], v[34:37]
	v_mfma_f32_16x16x32_bf16 v[26:29], v[158:161], v[206:209], v[26:29]
	v_mfma_f32_16x16x32_bf16 v[18:21], v[94:97], v[214:217], v[18:21]
	v_mfma_f32_16x16x32_bf16 v[10:13], v[158:161], v[214:217], v[10:13]
	v_mfma_f32_16x16x32_bf16 v[62:65], v[134:137], v[194:197], v[62:65]
	v_mfma_f32_16x16x32_bf16 v[58:61], v[162:165], v[194:197], v[58:61]
	v_mfma_f32_16x16x32_bf16 v[50:53], v[134:137], v[202:205], v[50:53]
	v_mfma_f32_16x16x32_bf16 v[42:45], v[162:165], v[202:205], v[42:45]
	v_mfma_f32_16x16x32_bf16 v[34:37], v[134:137], v[210:213], v[34:37]
	v_mfma_f32_16x16x32_bf16 v[26:29], v[162:165], v[210:213], v[26:29]
	v_mfma_f32_16x16x32_bf16 v[18:21], v[134:137], v[218:221], v[18:21]
	v_mfma_f32_16x16x32_bf16 v[10:13], v[162:165], v[218:221], v[10:13]
	s_setprio 0
	s_setprio 1
	v_mfma_f32_16x16x32_bf16 v[54:57], v[166:169], v[190:193], v[54:57]
	v_mfma_f32_16x16x32_bf16 v[46:49], v[174:177], v[190:193], v[46:49]
	v_mfma_f32_16x16x32_bf16 v[38:41], v[166:169], v[198:201], v[38:41]
	v_mfma_f32_16x16x32_bf16 v[30:33], v[174:177], v[198:201], v[30:33]
	v_mfma_f32_16x16x32_bf16 v[22:25], v[166:169], v[206:209], v[22:25]
	v_mfma_f32_16x16x32_bf16 v[14:17], v[174:177], v[206:209], v[14:17]
	v_mfma_f32_16x16x32_bf16 v[6:9], v[166:169], v[214:217], v[6:9]
	v_mfma_f32_16x16x32_bf16 v[2:5], v[174:177], v[214:217], v[2:5]
	v_mfma_f32_16x16x32_bf16 v[54:57], v[170:173], v[194:197], v[54:57]
	v_mfma_f32_16x16x32_bf16 v[46:49], v[186:189], v[194:197], v[46:49]
	v_mfma_f32_16x16x32_bf16 v[38:41], v[170:173], v[202:205], v[38:41]
	v_mfma_f32_16x16x32_bf16 v[30:33], v[186:189], v[202:205], v[30:33]
	v_mfma_f32_16x16x32_bf16 v[22:25], v[170:173], v[210:213], v[22:25]
	v_mfma_f32_16x16x32_bf16 v[14:17], v[186:189], v[210:213], v[14:17]
	v_mfma_f32_16x16x32_bf16 v[6:9], v[170:173], v[218:221], v[6:9]
	v_mfma_f32_16x16x32_bf16 v[2:5], v[186:189], v[218:221], v[2:5]
	s_setprio 0
	s_barrier
	s_add_i32 s48, 0, 0x18000
	s_add_i32 s49, 0, 0x1c000
	v_add_u32_e32 v162, s48, v156
	v_add_u32_e32 v179, s49, v156
	ds_read_b128 v[94:97], v162
	ds_read_b128 v[134:137], v162 offset:1024
	ds_read_b128 v[158:161], v162 offset:2048
	ds_read_b128 v[162:165], v162 offset:3072
	ds_read_b128 v[166:169], v179
	ds_read_b128 v[170:173], v179 offset:1024
	ds_read_b128 v[174:177], v179 offset:2048
	ds_read_b128 v[186:189], v179 offset:3072
	s_add_u32 s28, s28, 0x40000
	s_addc_u32 s29, s29, 0
	s_mov_b32 m0, s38
	v_lshl_add_u64 v[240:241], s[28:29], 0, v[144:145]
	ds_read_b128 v[190:193], v157 offset:32768
	ds_read_b128 v[194:197], v157 offset:33792
	ds_read_b128 v[198:201], v157 offset:34816
	ds_read_b128 v[202:205], v157 offset:35840
	ds_read_b128 v[206:209], v157 offset:36864
	ds_read_b128 v[210:213], v157 offset:37888
	ds_read_b128 v[214:217], v157 offset:38912
	ds_read_b128 v[218:221], v157 offset:39936
	global_load_lds_dwordx4 v[240:241], off
	v_lshl_add_u64 v[240:241], s[28:29], 0, v[140:141]
	s_mov_b32 m0, s39
	s_nop 0
	global_load_lds_dwordx4 v[240:241], off
	s_waitcnt vmcnt(8)
	s_waitcnt lgkmcnt(0)
	s_barrier
	s_setprio 1
	v_mfma_f32_16x16x32_bf16 v[130:133], v[94:97], v[190:193], v[130:133]
	v_mfma_f32_16x16x32_bf16 v[126:129], v[158:161], v[190:193], v[126:129]
	v_mfma_f32_16x16x32_bf16 v[114:117], v[94:97], v[198:201], v[114:117]
	v_mfma_f32_16x16x32_bf16 v[110:113], v[158:161], v[198:201], v[110:113]
	v_mfma_f32_16x16x32_bf16 v[98:101], v[94:97], v[206:209], v[98:101]
	v_mfma_f32_16x16x32_bf16 v[90:93], v[158:161], v[206:209], v[90:93]
	v_mfma_f32_16x16x32_bf16 v[78:81], v[94:97], v[214:217], v[78:81]
	v_mfma_f32_16x16x32_bf16 v[74:77], v[158:161], v[214:217], v[74:77]
	v_mfma_f32_16x16x32_bf16 v[130:133], v[134:137], v[194:197], v[130:133]
	v_mfma_f32_16x16x32_bf16 v[126:129], v[162:165], v[194:197], v[126:129]
	v_mfma_f32_16x16x32_bf16 v[114:117], v[134:137], v[202:205], v[114:117]
	v_mfma_f32_16x16x32_bf16 v[110:113], v[162:165], v[202:205], v[110:113]
	v_mfma_f32_16x16x32_bf16 v[98:101], v[134:137], v[210:213], v[98:101]
	v_mfma_f32_16x16x32_bf16 v[90:93], v[162:165], v[210:213], v[90:93]
	v_mfma_f32_16x16x32_bf16 v[78:81], v[134:137], v[218:221], v[78:81]
	v_mfma_f32_16x16x32_bf16 v[74:77], v[162:165], v[218:221], v[74:77]
	s_setprio 0
	s_setprio 1
	v_mfma_f32_16x16x32_bf16 v[122:125], v[166:169], v[190:193], v[122:125]
	v_mfma_f32_16x16x32_bf16 v[118:121], v[174:177], v[190:193], v[118:121]
	v_mfma_f32_16x16x32_bf16 v[106:109], v[166:169], v[198:201], v[106:109]
	v_mfma_f32_16x16x32_bf16 v[102:105], v[174:177], v[198:201], v[102:105]
	v_mfma_f32_16x16x32_bf16 v[86:89], v[166:169], v[206:209], v[86:89]
	v_mfma_f32_16x16x32_bf16 v[82:85], v[174:177], v[206:209], v[82:85]
	v_mfma_f32_16x16x32_bf16 v[70:73], v[166:169], v[214:217], v[70:73]
	v_mfma_f32_16x16x32_bf16 v[66:69], v[174:177], v[214:217], v[66:69]
	v_mfma_f32_16x16x32_bf16 v[122:125], v[170:173], v[194:197], v[122:125]
	v_mfma_f32_16x16x32_bf16 v[118:121], v[186:189], v[194:197], v[118:121]
	v_mfma_f32_16x16x32_bf16 v[106:109], v[170:173], v[202:205], v[106:109]
	v_mfma_f32_16x16x32_bf16 v[102:105], v[186:189], v[202:205], v[102:105]
	v_mfma_f32_16x16x32_bf16 v[86:89], v[170:173], v[210:213], v[86:89]
	v_mfma_f32_16x16x32_bf16 v[82:85], v[186:189], v[210:213], v[82:85]
	v_mfma_f32_16x16x32_bf16 v[70:73], v[170:173], v[218:221], v[70:73]
	v_mfma_f32_16x16x32_bf16 v[66:69], v[186:189], v[218:221], v[66:69]
	s_setprio 0
	s_barrier
; #define PG8_STAGE(bufoff, gbase, voff) do { _Pragma("unroll") for (int _i = 0; _i < 2; ++_i) \
;         __builtin_amdgcn_global_load_lds((const unsigned*)((const char*)(gbase) + (voff)[_i]), (PG8_LAS unsigned*)(lds + (bufoff) + ldsw + _i * 8192), 16, 0, 0); } while (0)
; #define PG8_WAIT_V(n) asm volatile("s_waitcnt vmcnt(" #n ")" ::: "memory")
; #define PG8_WAIT_L(n) asm volatile("s_waitcnt lgkmcnt(" #n ")" ::: "memory")
; template <class Epi, class Sched, bool ALIGN_EPI = false, bool SP2 = false>
; __device__ __forceinline__ void gemm_phase(PG8_LAS unsigned char* lds, const Gemm g, const Sched& S, const Epi& E) {
;     ...
;             PG8_LDA(At, 1, 1); PG8_STAGE(PG8_SB(1, 0), b3, voffB); PG8_STAGE(PG8_SB(1, 1), b3 + hstep, voffB); PG8_STAGE(PG8_SA(1, 0), a3, voffA);
;             PG8_WAIT_V(8); PG8_WAIT_L(0); PG8_BAR; PG8_MMA(1, 0, At, B0); PG8_MMA(1, 1, At, B1); PG8_BAR; PG8_SCHED;
;             } else {
;             PG8_LDB(B0, 0, 0); PG8_SCHED; PG8_LDA(At, 0, 0); PG8_STAGE(PG8_SA(1, 1), a1 + hstep, voffA);
;             PG8_WAIT_L(8); PG8_BAR; PG8_WAIT_L(0); PG8_MMA(0, 0, At, B0); PG8_BAR; PG8_SCHED;
;             PG8_LDB(B1, 0, 1); PG8_STAGE(PG8_SB(0, 0), b2, voffB);
;             PG8_BAR; PG8_WAIT_L(0); PG8_MMA(0, 1, At, B1); PG8_BAR;
;             PG8_LDA(At, 0, 1); PG8_STAGE(PG8_SA(0, 0), a2, voffA);
;             PG8_BAR; PG8_WAIT_L(0); PG8_MMA(1, 0, At, B0); PG8_BAR; PG8_SCHED;
;             PG8_STAGE(PG8_SB(0, 1), b2 + hstep, voffB);
;             PG8_WAIT_V(6); PG8_BAR; PG8_MMA(1, 1, At, B1); PG8_BAR;
;             PG8_LDB(B0, 1, 0); PG8_SCHED; PG8_LDA(At, 1, 0); PG8_STAGE(PG8_SA(0, 1), a2 + hstep, voffA);
;             PG8_WAIT_L(8); PG8_BAR; PG8_WAIT_L(0); PG8_MMA(0, 0, At, B0); PG8_BAR; PG8_SCHED;
;             PG8_LDB(B1, 1, 1); PG8_STAGE(PG8_SB(1, 0), b3, voffB);
;             PG8_BAR; PG8_WAIT_L(0); PG8_MMA(0, 1, At, B1); PG8_BAR;
;             PG8_LDA(At, 1, 1); PG8_STAGE(PG8_SA(1, 0), a3, voffA);
;             PG8_BAR; PG8_WAIT_L(0); PG8_MMA(1, 0, At, B0); PG8_BAR; PG8_SCHED;
;             PG8_STAGE(PG8_SB(1, 1), b3 + hstep, voffB);
;             PG8_WAIT_V(6); PG8_BAR; PG8_MMA(1, 1, At, B1); PG8_BAR;
;             }
;         }
;         if constexpr (ALIGN_EPI) { if (wr == 0) PG8_BAR; }
;         if constexpr (!Epi::AFTER_DRAIN) { E(acc, cur, wr, wc, fr, fq); S.done(cur); }
;         if (!has_next) break;
	s_add_i32 s28, s48, s35
	v_lshl_add_u64 v[154:155], v[154:155], 0, s[80:81]
	s_mov_b32 m0, s28
	ds_read_b128 v[190:193], v157 offset:49152
	ds_read_b128 v[194:197], v157 offset:50176
	ds_read_b128 v[198:201], v157 offset:51200
	ds_read_b128 v[202:205], v157 offset:52224
	ds_read_b128 v[206:209], v157 offset:53248
	ds_read_b128 v[210:213], v157 offset:54272
	ds_read_b128 v[214:217], v157 offset:55296
	ds_read_b128 v[218:221], v157 offset:56320
	global_load_lds_dwordx4 v[154:155], off
	s_add_i32 m0, s28, 0x2000
	s_add_u32 s26, s26, 0x40080
	v_lshl_add_u64 v[154:155], v[180:181], 0, s[80:81]
	s_addc_u32 s27, s27, 0
	s_add_i32 s28, s49, s35
	global_load_lds_dwordx4 v[154:155], off
	v_lshl_add_u64 v[154:155], s[26:27], 0, v[142:143]
	s_mov_b32 m0, s28
	s_nop 0
	global_load_lds_dwordx4 v[154:155], off
	v_lshl_add_u64 v[154:155], s[26:27], 0, v[138:139]
	s_add_i32 m0, s28, 0x2000
	s_nop 0
	global_load_lds_dwordx4 v[154:155], off
	v_lshl_add_u64 v[154:155], v[182:183], 0, s[80:81]
	s_mov_b32 m0, s40
	s_nop 0
	global_load_lds_dwordx4 v[154:155], off
	v_lshl_add_u64 v[154:155], v[222:223], 0, s[80:81]
	s_mov_b32 m0, s41
	s_nop 0
	global_load_lds_dwordx4 v[154:155], off
	s_waitcnt vmcnt(8)
	s_waitcnt lgkmcnt(0)
	s_barrier
	s_setprio 1
	v_mfma_f32_16x16x32_bf16 v[62:65], v[94:97], v[190:193], v[62:65]
	v_mfma_f32_16x16x32_bf16 v[58:61], v[158:161], v[190:193], v[58:61]
	v_mfma_f32_16x16x32_bf16 v[50:53], v[94:97], v[198:201], v[50:53]
	v_mfma_f32_16x16x32_bf16 v[42:45], v[158:161], v[198:201], v[42:45]
	v_mfma_f32_16x16x32_bf16 v[34:37], v[94:97], v[206:209], v[34:37]
	v_mfma_f32_16x16x32_bf16 v[26:29], v[158:161], v[206:209], v[26:29]
	v_mfma_f32_16x16x32_bf16 v[18:21], v[94:97], v[214:217], v[18:21]
	v_mfma_f32_16x16x32_bf16 v[10:13], v[158:161], v[214:217], v[10:13]
	v_mfma_f32_16x16x32_bf16 v[62:65], v[134:137], v[194:197], v[62:65]
	v_mfma_f32_16x16x32_bf16 v[58:61], v[162:165], v[194:197], v[58:61]
	v_mfma_f32_16x16x32_bf16 v[50:53], v[134:137], v[202:205], v[50:53]
	v_mfma_f32_16x16x32_bf16 v[42:45], v[162:165], v[202:205], v[42:45]
	v_mfma_f32_16x16x32_bf16 v[34:37], v[134:137], v[210:213], v[34:37]
	v_mfma_f32_16x16x32_bf16 v[26:29], v[162:165], v[210:213], v[26:29]
	v_mfma_f32_16x16x32_bf16 v[18:21], v[134:137], v[218:221], v[18:21]
	v_mfma_f32_16x16x32_bf16 v[10:13], v[162:165], v[218:221], v[10:13]
	s_setprio 0
	s_setprio 1
	v_mfma_f32_16x16x32_bf16 v[54:57], v[166:169], v[190:193], v[54:57]
	v_mfma_f32_16x16x32_bf16 v[46:49], v[174:177], v[190:193], v[46:49]
	v_mfma_f32_16x16x32_bf16 v[38:41], v[166:169], v[198:201], v[38:41]
	v_mfma_f32_16x16x32_bf16 v[30:33], v[174:177], v[198:201], v[30:33]
	v_mfma_f32_16x16x32_bf16 v[22:25], v[166:169], v[206:209], v[22:25]
	v_mfma_f32_16x16x32_bf16 v[14:17], v[174:177], v[206:209], v[14:17]
	v_mfma_f32_16x16x32_bf16 v[6:9], v[166:169], v[214:217], v[6:9]
	v_mfma_f32_16x16x32_bf16 v[2:5], v[174:177], v[214:217], v[2:5]
	v_mfma_f32_16x16x32_bf16 v[54:57], v[170:173], v[194:197], v[54:57]
	v_mfma_f32_16x16x32_bf16 v[46:49], v[186:189], v[194:197], v[46:49]
	v_mfma_f32_16x16x32_bf16 v[38:41], v[170:173], v[202:205], v[38:41]
	v_mfma_f32_16x16x32_bf16 v[30:33], v[186:189], v[202:205], v[30:33]
	v_mfma_f32_16x16x32_bf16 v[22:25], v[170:173], v[210:213], v[22:25]
	v_mfma_f32_16x16x32_bf16 v[14:17], v[186:189], v[210:213], v[14:17]
	v_mfma_f32_16x16x32_bf16 v[6:9], v[170:173], v[218:221], v[6:9]
	v_mfma_f32_16x16x32_bf16 v[2:5], v[186:189], v[218:221], v[2:5]
	s_setprio 0
	s_barrier
	s_add_i32 s47, s47, 2
	s_add_u32 s24, s24, 0x100
	s_addc_u32 s25, s25, 0
	s_add_u32 s45, s45, 0x100
	s_addc_u32 s46, s46, 0
	s_cmp_gt_u32 s47, 13
	s_cbranch_scc0 .LBB0_301
	s_and_b64 vcc, exec, s[8:9]
	s_cbranch_vccz .LBB0_304
	s_barrier

; #define PG8_STAGE(bufoff, gbase, voff) do { _Pragma("unroll") for (int _i = 0; _i < 2; ++_i) \
;         __builtin_amdgcn_global_load_lds((const unsigned*)((const char*)(gbase) + (voff)[_i]), (PG8_LAS unsigned*)(lds + (bufoff) + ldsw + _i * 8192), 16, 0, 0); } while (0)
; #define PG8_LDA(dst, b, h) do { _Pragma("unroll") for (int m = 0; m < 4; ++m) _Pragma("unroll") for (int k = 0; k < 2; ++k) dst[m][k] = *(const PG8_LAS bf16x8*)(lds + PG8_SA(b, h) + aoff + m * 2048 + k * 1024); } while (0)
; #define PG8_LDB(dst, b, h) do { _Pragma("unroll") for (int n = 0; n < 2; ++n) _Pragma("unroll") for (int k = 0; k < 2; ++k) dst[n][k] = *(const PG8_LAS bf16x8*)(lds + PG8_SB(b, h) + boff + n * 2048 + k * 1024); } while (0)
; #define PG8_MMA(ai, bj, At, Bt) do { __builtin_amdgcn_s_setprio(1); _Pragma("unroll") for (int m = 0; m < 4; ++m) _Pragma("unroll") for (int n = 0; n < 2; ++n) _Pragma("unroll") for (int k = 0; k < 2; ++k) \
;         acc[ai][bj][m][n] = __builtin_amdgcn_mfma_f32_16x16x32_bf16(Bt[n][k], At[m][k], acc[ai][bj][m][n], 0, 0, 0); __builtin_amdgcn_s_setprio(0); } while (0)
; #define PG8_WAIT_V(n) asm volatile("s_waitcnt vmcnt(" #n ")" ::: "memory")
; #define PG8_BAR __builtin_amdgcn_s_barrier()
; template <class Epi, class Sched, bool ALIGN_EPI = false, bool SP2 = false>
; __device__ __forceinline__ void gemm_phase(PG8_LAS unsigned char* lds, const Gemm g, const Sched& S, const Epi& E) {
;     ...
;         for (int t = 0; t < nt; t += 2) {
;             const bool last = (t == nt - 2);
;             const char* a1 = cA + (size_t)(t + 1) * kstep;
;             const char* a2 = last ? nA : cA + (size_t)(t + 2) * kstep; const char* b2 = last ? nB : cB + (size_t)(t + 2) * kstep;
;             const char* a3 = a2 + kstep; const char* b3 = b2 + kstep;
;             if (last && has_next) S.a_ready(nxt);
;             if constexpr (SP2) {
;             PG8_LDB(B0, 0, 0); PG8_LDB(B1, 0, 1); PG8_SCHED; PG8_LDA(At, 0, 0); PG8_STAGE(PG8_SA(1, 1), a1 + hstep, voffA);
;             PG8_WAIT_V(8); PG8_WAIT_L(0); PG8_BAR; PG8_MMA(0, 0, At, B0); PG8_MMA(0, 1, At, B1); PG8_BAR; PG8_SCHED;
;             PG8_LDA(At, 0, 1); PG8_STAGE(PG8_SB(0, 0), b2, voffB); PG8_STAGE(PG8_SB(0, 1), b2 + hstep, voffB); PG8_STAGE(PG8_SA(0, 0), a2, voffA);
;             PG8_WAIT_V(8); PG8_WAIT_L(0); PG8_BAR; PG8_MMA(1, 0, At, B0); PG8_MMA(1, 1, At, B1); PG8_BAR; PG8_SCHED;
.LBB0_318:
	s_add_u32 s26, s24, 0xfffc0080
	s_addc_u32 s27, s25, -1
	s_add_i32 s48, 0, 0x10000
	s_cmp_eq_u32 s47, 12
	s_cselect_b32 s29, s13, s27
	s_cselect_b32 s28, s21, s26
	v_add_u32_e32 v154, s48, v156
	s_cselect_b32 s27, s11, s46
	s_cselect_b32 s26, s44, s45
	s_add_i32 s50, 0, 0x14000
	ds_read_b128 v[94:97], v154
	ds_read_b128 v[134:137], v154 offset:1024
	ds_read_b128 v[158:161], v154 offset:2048
	ds_read_b128 v[162:165], v154 offset:3072
	v_add_u32_e32 v154, s50, v156
	ds_read_b128 v[166:169], v154
	ds_read_b128 v[170:173], v154 offset:1024
	ds_read_b128 v[174:177], v154 offset:2048
	ds_read_b128 v[186:189], v154 offset:3072
	v_lshl_add_u64 v[154:155], s[24:25], 0, v[150:151]
	s_add_i32 m0, s23, 0xc000
	ds_read_b128 v[190:193], v157
	ds_read_b128 v[194:197], v157 offset:1024
	ds_read_b128 v[198:201], v157 offset:2048
	ds_read_b128 v[202:205], v157 offset:3072
	ds_read_b128 v[206:209], v157 offset:4096
	ds_read_b128 v[210:213], v157 offset:5120
	ds_read_b128 v[214:217], v157 offset:6144
	ds_read_b128 v[218:221], v157 offset:7168
	global_load_lds_dwordx4 v[154:155], off
	v_lshl_add_u64 v[154:155], s[24:25], 0, v[152:153]
	s_add_i32 m0, s23, 0xe000
	s_nop 0
	global_load_lds_dwordx4 v[154:155], off
	s_waitcnt vmcnt(8)
	s_waitcnt lgkmcnt(0)
	s_barrier
	s_setprio 1
	v_mfma_f32_16x16x32_bf16 v[130:133], v[94:97], v[190:193], v[130:133]
	v_mfma_f32_16x16x32_bf16 v[126:129], v[158:161], v[190:193], v[126:129]
	v_mfma_f32_16x16x32_bf16 v[114:117], v[94:97], v[198:201], v[114:117]
	v_mfma_f32_16x16x32_bf16 v[110:113], v[158:161], v[198:201], v[110:113]
	v_mfma_f32_16x16x32_bf16 v[98:101], v[94:97], v[206:209], v[98:101]
	v_mfma_f32_16x16x32_bf16 v[90:93], v[158:161], v[206:209], v[90:93]
	v_mfma_f32_16x16x32_bf16 v[78:81], v[94:97], v[214:217], v[78:81]
	v_mfma_f32_16x16x32_bf16 v[74:77], v[158:161], v[214:217], v[74:77]
	v_mfma_f32_16x16x32_bf16 v[130:133], v[134:137], v[194:197], v[130:133]
	v_mfma_f32_16x16x32_bf16 v[126:129], v[162:165], v[194:197], v[126:129]
	v_mfma_f32_16x16x32_bf16 v[114:117], v[134:137], v[202:205], v[114:117]
	v_mfma_f32_16x16x32_bf16 v[110:113], v[162:165], v[202:205], v[110:113]
	v_mfma_f32_16x16x32_bf16 v[98:101], v[134:137], v[210:213], v[98:101]
	v_mfma_f32_16x16x32_bf16 v[90:93], v[162:165], v[210:213], v[90:93]
	v_mfma_f32_16x16x32_bf16 v[78:81], v[134:137], v[218:221], v[78:81]
	v_mfma_f32_16x16x32_bf16 v[74:77], v[162:165], v[218:221], v[74:77]
	s_setprio 0
	s_setprio 1
	v_mfma_f32_16x16x32_bf16 v[122:125], v[166:169], v[190:193], v[122:125]
	v_mfma_f32_16x16x32_bf16 v[118:121], v[174:177], v[190:193], v[118:121]
	v_mfma_f32_16x16x32_bf16 v[106:109], v[166:169], v[198:201], v[106:109]
	v_mfma_f32_16x16x32_bf16 v[102:105], v[174:177], v[198:201], v[102:105]
	v_mfma_f32_16x16x32_bf16 v[86:89], v[166:169], v[206:209], v[86:89]
	v_mfma_f32_16x16x32_bf16 v[82:85], v[174:177], v[206:209], v[82:85]
	v_mfma_f32_16x16x32_bf16 v[70:73], v[166:169], v[214:217], v[70:73]
	v_mfma_f32_16x16x32_bf16 v[66:69], v[174:177], v[214:217], v[66:69]
	v_mfma_f32_16x16x32_bf16 v[122:125], v[170:173], v[194:197], v[122:125]
	v_mfma_f32_16x16x32_bf16 v[118:121], v[186:189], v[194:197], v[118:121]
	v_mfma_f32_16x16x32_bf16 v[106:109], v[170:173], v[202:205], v[106:109]
	v_mfma_f32_16x16x32_bf16 v[102:105], v[186:189], v[202:205], v[102:105]
	v_mfma_f32_16x16x32_bf16 v[86:89], v[170:173], v[210:213], v[86:89]
	v_mfma_f32_16x16x32_bf16 v[82:85], v[186:189], v[210:213], v[82:85]
	v_mfma_f32_16x16x32_bf16 v[70:73], v[170:173], v[218:221], v[70:73]
	v_mfma_f32_16x16x32_bf16 v[66:69], v[186:189], v[218:221], v[66:69]
	s_setprio 0
	s_barrier
	s_add_i32 s48, s48, s35
	v_lshl_add_u64 v[154:155], s[26:27], 0, v[142:143]
	s_mov_b32 m0, s48
	ds_read_b128 v[190:193], v157 offset:16384
	ds_read_b128 v[194:197], v157 offset:17408
	ds_read_b128 v[198:201], v157 offset:18432
	ds_read_b128 v[202:205], v157 offset:19456
	ds_read_b128 v[206:209], v157 offset:20480
	ds_read_b128 v[210:213], v157 offset:21504
	ds_read_b128 v[214:217], v157 offset:22528
	ds_read_b128 v[218:221], v157 offset:23552
	global_load_lds_dwordx4 v[154:155], off
	s_add_i32 m0, s48, 0x2000
	s_add_u32 s48, s26, 0x40000
	v_lshl_add_u64 v[180:181], s[26:27], 0, v[138:139]
	s_addc_u32 s49, s27, 0
	s_add_i32 s50, s50, s35
	global_load_lds_dwordx4 v[180:181], off
	v_lshl_add_u64 v[182:183], s[48:49], 0, v[142:143]
	s_mov_b32 m0, s50
	v_lshl_add_u64 v[222:223], s[28:29], 0, v[140:141]
	global_load_lds_dwordx4 v[182:183], off
	v_lshl_add_u64 v[182:183], s[48:49], 0, v[138:139]
	s_add_i32 m0, s50, 0x2000
	s_nop 0
	global_load_lds_dwordx4 v[182:183], off
	v_lshl_add_u64 v[182:183], s[28:29], 0, v[144:145]
	s_mov_b32 m0, s23
	s_nop 0
	global_load_lds_dwordx4 v[182:183], off
	s_mov_b32 m0, s37
	s_nop 0
	global_load_lds_dwordx4 v[222:223], off
	s_waitcnt vmcnt(8)
	s_waitcnt lgkmcnt(0)
	s_barrier
; #define PG8_STAGE(bufoff, gbase, voff) do { _Pragma("unroll") for (int _i = 0; _i < 2; ++_i) \
;         __builtin_amdgcn_global_load_lds((const unsigned*)((const char*)(gbase) + (voff)[_i]), (PG8_LAS unsigned*)(lds + (bufoff) + ldsw + _i * 8192), 16, 0, 0); } while (0)
; #define PG8_LDA(dst, b, h) do { _Pragma("unroll") for (int m = 0; m < 4; ++m) _Pragma("unroll") for (int k = 0; k < 2; ++k) dst[m][k] = *(const PG8_LAS bf16x8*)(lds + PG8_SA(b, h) + aoff + m * 2048 + k * 1024); } while (0)
; #define PG8_LDB(dst, b, h) do { _Pragma("unroll") for (int n = 0; n < 2; ++n) _Pragma("unroll") for (int k = 0; k < 2; ++k) dst[n][k] = *(const PG8_LAS bf16x8*)(lds + PG8_SB(b, h) + boff + n * 2048 + k * 1024); } while (0)
; #define PG8_MMA(ai, bj, At, Bt) do { __builtin_amdgcn_s_setprio(1); _Pragma("unroll") for (int m = 0; m < 4; ++m) _Pragma("unroll") for (int n = 0; n < 2; ++n) _Pragma("unroll") for (int k = 0; k < 2; ++k) \
;         acc[ai][bj][m][n] = __builtin_amdgcn_mfma_f32_16x16x32_bf16(Bt[n][k], At[m][k], acc[ai][bj][m][n], 0, 0, 0); __builtin_amdgcn_s_setprio(0); } while (0)
; #define PG8_WAIT_V(n) asm volatile("s_waitcnt vmcnt(" #n ")" ::: "memory")
; #define PG8_WAIT_L(n) asm volatile("s_waitcnt lgkmcnt(" #n ")" ::: "memory")
; #define PG8_BAR __builtin_amdgcn_s_barrier()
; #define PG8_SCHED __builtin_amdgcn_sched_barrier(0)
; template <class Epi, class Sched, bool ALIGN_EPI = false, bool SP2 = false>
; __device__ __forceinline__ void gemm_phase(PG8_LAS unsigned char* lds, const Gemm g, const Sched& S, const Epi& E) {
;     ...
;             PG8_WAIT_V(8); PG8_WAIT_L(0); PG8_BAR; PG8_MMA(1, 0, At, B0); PG8_MMA(1, 1, At, B1); PG8_BAR; PG8_SCHED;
;             PG8_LDB(B0, 1, 0); PG8_LDB(B1, 1, 1); PG8_SCHED; PG8_LDA(At, 1, 0); PG8_STAGE(PG8_SA(0, 1), a2 + hstep, voffA);
;             PG8_WAIT_V(8); PG8_WAIT_L(0); PG8_BAR; PG8_MMA(0, 0, At, B0); PG8_MMA(0, 1, At, B1); PG8_BAR; PG8_SCHED;
	s_setprio 1
	v_mfma_f32_16x16x32_bf16 v[62:65], v[94:97], v[190:193], v[62:65]
	v_mfma_f32_16x16x32_bf16 v[58:61], v[158:161], v[190:193], v[58:61]
	v_mfma_f32_16x16x32_bf16 v[50:53], v[94:97], v[198:201], v[50:53]
	v_mfma_f32_16x16x32_bf16 v[42:45], v[158:161], v[198:201], v[42:45]
	v_mfma_f32_16x16x32_bf16 v[34:37], v[94:97], v[206:209], v[34:37]
	v_mfma_f32_16x16x32_bf16 v[26:29], v[158:161], v[206:209], v[26:29]
	v_mfma_f32_16x16x32_bf16 v[18:21], v[94:97], v[214:217], v[18:21]
	v_mfma_f32_16x16x32_bf16 v[10:13], v[158:161], v[214:217], v[10:13]
	v_mfma_f32_16x16x32_bf16 v[62:65], v[134:137], v[194:197], v[62:65]
	v_mfma_f32_16x16x32_bf16 v[58:61], v[162:165], v[194:197], v[58:61]
	v_mfma_f32_16x16x32_bf16 v[50:53], v[134:137], v[202:205], v[50:53]
	v_mfma_f32_16x16x32_bf16 v[42:45], v[162:165], v[202:205], v[42:45]
	v_mfma_f32_16x16x32_bf16 v[34:37], v[134:137], v[210:213], v[34:37]
	v_mfma_f32_16x16x32_bf16 v[26:29], v[162:165], v[210:213], v[26:29]
	v_mfma_f32_16x16x32_bf16 v[18:21], v[134:137], v[218:221], v[18:21]
	v_mfma_f32_16x16x32_bf16 v[10:13], v[162:165], v[218:221], v[10:13]
	s_setprio 0
	s_setprio 1
	v_mfma_f32_16x16x32_bf16 v[54:57], v[166:169], v[190:193], v[54:57]
	v_mfma_f32_16x16x32_bf16 v[46:49], v[174:177], v[190:193], v[46:49]
	v_mfma_f32_16x16x32_bf16 v[38:41], v[166:169], v[198:201], v[38:41]
	v_mfma_f32_16x16x32_bf16 v[30:33], v[174:177], v[198:201], v[30:33]
	v_mfma_f32_16x16x32_bf16 v[22:25], v[166:169], v[206:209], v[22:25]
	v_mfma_f32_16x16x32_bf16 v[14:17], v[174:177], v[206:209], v[14:17]
	v_mfma_f32_16x16x32_bf16 v[6:9], v[166:169], v[214:217], v[6:9]
	v_mfma_f32_16x16x32_bf16 v[2:5], v[174:177], v[214:217], v[2:5]
	v_mfma_f32_16x16x32_bf16 v[54:57], v[170:173], v[194:197], v[54:57]
	v_mfma_f32_16x16x32_bf16 v[46:49], v[186:189], v[194:197], v[46:49]
	v_mfma_f32_16x16x32_bf16 v[38:41], v[170:173], v[202:205], v[38:41]
	v_mfma_f32_16x16x32_bf16 v[30:33], v[186:189], v[202:205], v[30:33]
	v_mfma_f32_16x16x32_bf16 v[22:25], v[170:173], v[210:213], v[22:25]
	v_mfma_f32_16x16x32_bf16 v[14:17], v[186:189], v[210:213], v[14:17]
	v_mfma_f32_16x16x32_bf16 v[6:9], v[170:173], v[218:221], v[6:9]
	v_mfma_f32_16x16x32_bf16 v[2:5], v[186:189], v[218:221], v[2:5]
	s_setprio 0
	s_barrier
	s_add_i32 s48, 0, 0x18000
	s_add_i32 s49, 0, 0x1c000
	v_add_u32_e32 v162, s48, v156
	v_add_u32_e32 v179, s49, v156
	ds_read_b128 v[94:97], v162
	ds_read_b128 v[134:137], v162 offset:1024
	ds_read_b128 v[158:161], v162 offset:2048
	ds_read_b128 v[162:165], v162 offset:3072
	ds_read_b128 v[166:169], v179
	ds_read_b128 v[170:173], v179 offset:1024
	ds_read_b128 v[174:177], v179 offset:2048
	ds_read_b128 v[186:189], v179 offset:3072
	s_add_u32 s28, s28, 0x40000
	s_addc_u32 s29, s29, 0
	s_mov_b32 m0, s38
	v_lshl_add_u64 v[240:241], s[28:29], 0, v[144:145]
	ds_read_b128 v[190:193], v157 offset:32768
	ds_read_b128 v[194:197], v157 offset:33792
	ds_read_b128 v[198:201], v157 offset:34816
	ds_read_b128 v[202:205], v157 offset:35840
	ds_read_b128 v[206:209], v157 offset:36864
	ds_read_b128 v[210:213], v157 offset:37888
	ds_read_b128 v[214:217], v157 offset:38912
	ds_read_b128 v[218:221], v157 offset:39936
	global_load_lds_dwordx4 v[240:241], off
	v_lshl_add_u64 v[240:241], s[28:29], 0, v[140:141]
	s_mov_b32 m0, s39
	s_nop 0
	global_load_lds_dwordx4 v[240:241], off
	s_waitcnt vmcnt(8)
	s_waitcnt lgkmcnt(0)
	s_barrier
	s_setprio 1
	v_mfma_f32_16x16x32_bf16 v[130:133], v[94:97], v[190:193], v[130:133]
	v_mfma_f32_16x16x32_bf16 v[126:129], v[158:161], v[190:193], v[126:129]
	v_mfma_f32_16x16x32_bf16 v[114:117], v[94:97], v[198:201], v[114:117]
	v_mfma_f32_16x16x32_bf16 v[110:113], v[158:161], v[198:201], v[110:113]
	v_mfma_f32_16x16x32_bf16 v[98:101], v[94:97], v[206:209], v[98:101]
	v_mfma_f32_16x16x32_bf16 v[90:93], v[158:161], v[206:209], v[90:93]
	v_mfma_f32_16x16x32_bf16 v[78:81], v[94:97], v[214:217], v[78:81]
	v_mfma_f32_16x16x32_bf16 v[74:77], v[158:161], v[214:217], v[74:77]
	v_mfma_f32_16x16x32_bf16 v[130:133], v[134:137], v[194:197], v[130:133]
	v_mfma_f32_16x16x32_bf16 v[126:129], v[162:165], v[194:197], v[126:129]
	v_mfma_f32_16x16x32_bf16 v[114:117], v[134:137], v[202:205], v[114:117]
	v_mfma_f32_16x16x32_bf16 v[110:113], v[162:165], v[202:205], v[110:113]
	v_mfma_f32_16x16x32_bf16 v[98:101], v[134:137], v[210:213], v[98:101]
	v_mfma_f32_16x16x32_bf16 v[90:93], v[162:165], v[210:213], v[90:93]
	v_mfma_f32_16x16x32_bf16 v[78:81], v[134:137], v[218:221], v[78:81]
	v_mfma_f32_16x16x32_bf16 v[74:77], v[162:165], v[218:221], v[74:77]
	s_setprio 0
	s_setprio 1
	v_mfma_f32_16x16x32_bf16 v[122:125], v[166:169], v[190:193], v[122:125]
	v_mfma_f32_16x16x32_bf16 v[118:121], v[174:177], v[190:193], v[118:121]
	v_mfma_f32_16x16x32_bf16 v[106:109], v[166:169], v[198:201], v[106:109]
	v_mfma_f32_16x16x32_bf16 v[102:105], v[174:177], v[198:201], v[102:105]
	v_mfma_f32_16x16x32_bf16 v[86:89], v[166:169], v[206:209], v[86:89]
	v_mfma_f32_16x16x32_bf16 v[82:85], v[174:177], v[206:209], v[82:85]
	v_mfma_f32_16x16x32_bf16 v[70:73], v[166:169], v[214:217], v[70:73]
	v_mfma_f32_16x16x32_bf16 v[66:69], v[174:177], v[214:217], v[66:69]
	v_mfma_f32_16x16x32_bf16 v[122:125], v[170:173], v[194:197], v[122:125]
	v_mfma_f32_16x16x32_bf16 v[118:121], v[186:189], v[194:197], v[118:121]
	v_mfma_f32_16x16x32_bf16 v[106:109], v[170:173], v[202:205], v[106:109]
	v_mfma_f32_16x16x32_bf16 v[102:105], v[186:189], v[202:205], v[102:105]
	v_mfma_f32_16x16x32_bf16 v[86:89], v[170:173], v[210:213], v[86:89]
	v_mfma_f32_16x16x32_bf16 v[82:85], v[186:189], v[210:213], v[82:85]
	v_mfma_f32_16x16x32_bf16 v[70:73], v[170:173], v[218:221], v[70:73]
	v_mfma_f32_16x16x32_bf16 v[66:69], v[186:189], v[218:221], v[66:69]
	s_setprio 0
	s_barrier
; #define PG8_STAGE(bufoff, gbase, voff) do { _Pragma("unroll") for (int _i = 0; _i < 2; ++_i) \
;         __builtin_amdgcn_global_load_lds((const unsigned*)((const char*)(gbase) + (voff)[_i]), (PG8_LAS unsigned*)(lds + (bufoff) + ldsw + _i * 8192), 16, 0, 0); } while (0)
; #define PG8_WAIT_V(n) asm volatile("s_waitcnt vmcnt(" #n ")" ::: "memory")
; #define PG8_WAIT_L(n) asm volatile("s_waitcnt lgkmcnt(" #n ")" ::: "memory")
; template <class Epi, class Sched, bool ALIGN_EPI = false, bool SP2 = false>
; __device__ __forceinline__ void gemm_phase(PG8_LAS unsigned char* lds, const Gemm g, const Sched& S, const Epi& E) {
;     ...
;             PG8_LDA(At, 1, 1); PG8_STAGE(PG8_SB(1, 0), b3, voffB); PG8_STAGE(PG8_SB(1, 1), b3 + hstep, voffB); PG8_STAGE(PG8_SA(1, 0), a3, voffA);
;             PG8_WAIT_V(8); PG8_WAIT_L(0); PG8_BAR; PG8_MMA(1, 0, At, B0); PG8_MMA(1, 1, At, B1); PG8_BAR; PG8_SCHED;
;             } else {
;             PG8_LDB(B0, 0, 0); PG8_SCHED; PG8_LDA(At, 0, 0); PG8_STAGE(PG8_SA(1, 1), a1 + hstep, voffA);
;             PG8_WAIT_L(8); PG8_BAR; PG8_WAIT_L(0); PG8_MMA(0, 0, At, B0); PG8_BAR; PG8_SCHED;
;             PG8_LDB(B1, 0, 1); PG8_STAGE(PG8_SB(0, 0), b2, voffB);
;             PG8_BAR; PG8_WAIT_L(0); PG8_MMA(0, 1, At, B1); PG8_BAR;
;             PG8_LDA(At, 0, 1); PG8_STAGE(PG8_SA(0, 0), a2, voffA);
;             PG8_BAR; PG8_WAIT_L(0); PG8_MMA(1, 0, At, B0); PG8_BAR; PG8_SCHED;
;             PG8_STAGE(PG8_SB(0, 1), b2 + hstep, voffB);
;             PG8_WAIT_V(6); PG8_BAR; PG8_MMA(1, 1, At, B1); PG8_BAR;
;             PG8_LDB(B0, 1, 0); PG8_SCHED; PG8_LDA(At, 1, 0); PG8_STAGE(PG8_SA(0, 1), a2 + hstep, voffA);
;             PG8_WAIT_L(8); PG8_BAR; PG8_WAIT_L(0); PG8_MMA(0, 0, At, B0); PG8_BAR; PG8_SCHED;
;             PG8_LDB(B1, 1, 1); PG8_STAGE(PG8_SB(1, 0), b3, voffB);
;             PG8_BAR; PG8_WAIT_L(0); PG8_MMA(0, 1, At, B1); PG8_BAR;
;             PG8_LDA(At, 1, 1); PG8_STAGE(PG8_SA(1, 0), a3, voffA);
;             PG8_BAR; PG8_WAIT_L(0); PG8_MMA(1, 0, At, B0); PG8_BAR; PG8_SCHED;
;             PG8_STAGE(PG8_SB(1, 1), b3 + hstep, voffB);
;             PG8_WAIT_V(6); PG8_BAR; PG8_MMA(1, 1, At, B1); PG8_BAR;
;             }
;         }
;         if constexpr (ALIGN_EPI) { if (wr == 0) PG8_BAR; }
;         if constexpr (!Epi::AFTER_DRAIN) { E(acc, cur, wr, wc, fr, fq); S.done(cur); }
;         if (!has_next) break;
	s_add_i32 s28, s48, s35
	v_lshl_add_u64 v[154:155], v[154:155], 0, s[80:81]
	s_mov_b32 m0, s28
	ds_read_b128 v[190:193], v157 offset:49152
	ds_read_b128 v[194:197], v157 offset:50176
	ds_read_b128 v[198:201], v157 offset:51200
	ds_read_b128 v[202:205], v157 offset:52224
	ds_read_b128 v[206:209], v157 offset:53248
	ds_read_b128 v[210:213], v157 offset:54272
	ds_read_b128 v[214:217], v157 offset:55296
	ds_read_b128 v[218:221], v157 offset:56320
	global_load_lds_dwordx4 v[154:155], off
	s_add_i32 m0, s28, 0x2000
	s_add_u32 s26, s26, 0x40080
	v_lshl_add_u64 v[154:155], v[180:181], 0, s[80:81]
	s_addc_u32 s27, s27, 0
	s_add_i32 s28, s49, s35
	global_load_lds_dwordx4 v[154:155], off
	v_lshl_add_u64 v[154:155], s[26:27], 0, v[142:143]
	s_mov_b32 m0, s28
	s_nop 0
	global_load_lds_dwordx4 v[154:155], off
	v_lshl_add_u64 v[154:155], s[26:27], 0, v[138:139]
	s_add_i32 m0, s28, 0x2000
	s_nop 0
	global_load_lds_dwordx4 v[154:155], off
	v_lshl_add_u64 v[154:155], v[182:183], 0, s[80:81]
	s_mov_b32 m0, s40
	s_nop 0
	global_load_lds_dwordx4 v[154:155], off
	v_lshl_add_u64 v[154:155], v[222:223], 0, s[80:81]
	s_mov_b32 m0, s41
	s_nop 0
	global_load_lds_dwordx4 v[154:155], off
	s_waitcnt vmcnt(8)
	s_waitcnt lgkmcnt(0)
	s_barrier
	s_setprio 1
	v_mfma_f32_16x16x32_bf16 v[62:65], v[94:97], v[190:193], v[62:65]
	v_mfma_f32_16x16x32_bf16 v[58:61], v[158:161], v[190:193], v[58:61]
	v_mfma_f32_16x16x32_bf16 v[50:53], v[94:97], v[198:201], v[50:53]
	v_mfma_f32_16x16x32_bf16 v[42:45], v[158:161], v[198:201], v[42:45]
	v_mfma_f32_16x16x32_bf16 v[34:37], v[94:97], v[206:209], v[34:37]
	v_mfma_f32_16x16x32_bf16 v[26:29], v[158:161], v[206:209], v[26:29]
	v_mfma_f32_16x16x32_bf16 v[18:21], v[94:97], v[214:217], v[18:21]
	v_mfma_f32_16x16x32_bf16 v[10:13], v[158:161], v[214:217], v[10:13]
	v_mfma_f32_16x16x32_bf16 v[62:65], v[134:137], v[194:197], v[62:65]
	v_mfma_f32_16x16x32_bf16 v[58:61], v[162:165], v[194:197], v[58:61]
	v_mfma_f32_16x16x32_bf16 v[50:53], v[134:137], v[202:205], v[50:53]
	v_mfma_f32_16x16x32_bf16 v[42:45], v[162:165], v[202:205], v[42:45]
	v_mfma_f32_16x16x32_bf16 v[34:37], v[134:137], v[210:213], v[34:37]
	v_mfma_f32_16x16x32_bf16 v[26:29], v[162:165], v[210:213], v[26:29]
	v_mfma_f32_16x16x32_bf16 v[18:21], v[134:137], v[218:221], v[18:21]
	v_mfma_f32_16x16x32_bf16 v[10:13], v[162:165], v[218:221], v[10:13]
	s_setprio 0
	s_setprio 1
	v_mfma_f32_16x16x32_bf16 v[54:57], v[166:169], v[190:193], v[54:57]
	v_mfma_f32_16x16x32_bf16 v[46:49], v[174:177], v[190:193], v[46:49]
	v_mfma_f32_16x16x32_bf16 v[38:41], v[166:169], v[198:201], v[38:41]
	v_mfma_f32_16x16x32_bf16 v[30:33], v[174:177], v[198:201], v[30:33]
	v_mfma_f32_16x16x32_bf16 v[22:25], v[166:169], v[206:209], v[22:25]
	v_mfma_f32_16x16x32_bf16 v[14:17], v[174:177], v[206:209], v[14:17]
	v_mfma_f32_16x16x32_bf16 v[6:9], v[166:169], v[214:217], v[6:9]
	v_mfma_f32_16x16x32_bf16 v[2:5], v[174:177], v[214:217], v[2:5]
	v_mfma_f32_16x16x32_bf16 v[54:57], v[170:173], v[194:197], v[54:57]
	v_mfma_f32_16x16x32_bf16 v[46:49], v[186:189], v[194:197], v[46:49]
	v_mfma_f32_16x16x32_bf16 v[38:41], v[170:173], v[202:205], v[38:41]
	v_mfma_f32_16x16x32_bf16 v[30:33], v[186:189], v[202:205], v[30:33]
	v_mfma_f32_16x16x32_bf16 v[22:25], v[170:173], v[210:213], v[22:25]
	v_mfma_f32_16x16x32_bf16 v[14:17], v[186:189], v[210:213], v[14:17]
	v_mfma_f32_16x16x32_bf16 v[6:9], v[170:173], v[218:221], v[6:9]
	v_mfma_f32_16x16x32_bf16 v[2:5], v[186:189], v[218:221], v[2:5]
	s_setprio 0
	s_barrier
	s_add_i32 s47, s47, 2
	s_add_u32 s24, s24, 0x100
	s_addc_u32 s25, s25, 0
	s_add_u32 s45, s45, 0x100
	s_addc_u32 s46, s46, 0
	s_cmp_gt_u32 s47, 13
	s_cbranch_scc0 .LBB0_318
	s_and_b64 vcc, exec, s[6:7]
	s_cbranch_vccz .LBB0_321
	s_barrier

; #define FY_STORE(bb) do { *(u32x4*)((bb) + kr0 * FX_KROW + kc * 16) = kreg[0]; *(u32x4*)((bb) + (kr0 + 32) * FX_KROW + kc * 16) = kreg[1]; \
;         *(u32x4*)((bb) + FX_KBYTES + vd0 * FX_VROW + vc * 16) = vreg[0]; *(u32x4*)((bb) + FX_KBYTES + (vd0 + 64) * FX_VROW + vc * 16) = vreg[1]; \
;         ((float*)((bb) + FX_KBYTES + FX_VBYTES))[lane] = breg; } while (0)
; __device__ __forceinline__ void fox_unit2(ArgsP a, int bh, int qb, unsigned char* lds) {
;     ...
;     __syncthreads();
;     FY_LOAD(0); FY_STORE(lds);
;     FY_LOAD(1); FY_STORE(lds + FX_BUF);
;     __syncthreads();
;     f32x16 sc[2], sn[2]; bf16x8_t pb[4];
;     FY_QK(sc, lds);
;     FY_BMAX(sc, lds, 0, true);
;     int bc = 0, bn = FX_BUF, bs = 2 * FX_BUF;
.LBB0_882:
	v_add_u32_e32 v2, s68, v172
	v_ashrrev_i32_e32 v3, 31, v2
	v_lshlrev_b64 v[4:5], 9, v[2:3]
	v_add_u32_e32 v2, 32, v2
	v_ashrrev_i32_e32 v3, 31, v2
	v_lshlrev_b64 v[2:3], 9, v[2:3]
	s_mov_b32 s23, s24
	v_lshl_add_u64 v[4:5], v[190:191], 0, v[4:5]
	v_lshl_add_u64 v[2:3], v[190:191], 0, v[2:3]
	s_lshl_b64 s[24:25], s[68:69], 1
	global_load_dwordx4 v[148:151], v[4:5], off
	global_load_dwordx4 v[152:155], v[2:3], off
	v_lshl_add_u64 v[2:3], v[186:187], 0, s[24:25]
	global_load_dwordx4 v[156:159], v[2:3], off
	v_lshl_add_u64 v[2:3], v[188:189], 0, s[24:25]
	global_load_dwordx4 v[160:163], v[2:3], off
	v_add_u32_e32 v2, s68, v241
	v_mov_b32_e32 v3, v0
	v_lshl_add_u64 v[2:3], v[2:3], 2, v[168:169]
	v_add_u32_e32 v15, s6, v244
	global_load_dword v2, v[2:3], off
	v_add_u32_e32 v3, v15, v247
	ds_read_b128 v[4:7], v3
	ds_read_b128 v[8:11], v3 offset:32
	s_waitcnt lgkmcnt(1)
	v_mfma_f32_32x32x16_bf16 v[96:111], v[4:7], v[112:115], 0
	ds_read_b128 v[4:7], v3 offset:64
	v_mov_b32_e32 v14, v248
	v_mov_b32_e32 v1, v175
	v_mul_f32_e64 v78, v78, v166
	v_mul_f32_e64 v79, v79, v166
	v_pk_mul_f32 v[76:77], v[76:77], v[166:167] op_sel_hi:[1,0]
	v_pk_mul_f32 v[74:75], v[74:75], v[166:167] op_sel_hi:[1,0]
	v_pk_mul_f32 v[72:73], v[72:73], v[166:167] op_sel_hi:[1,0]
	s_waitcnt lgkmcnt(1)
	v_mfma_f32_32x32x16_bf16 v[96:111], v[8:11], v[116:119], v[96:111]
	v_mul_f32_e64 v70, v70, v166
	v_mul_f32_e64 v71, v71, v166
	v_mul_f32_e64 v68, v68, v166
	v_mul_f32_e64 v69, v69, v166
	v_mul_f32_e64 v66, v66, v166
	v_mul_f32_e64 v67, v67, v166
	v_pk_mul_f32 v[64:65], v[64:65], v[166:167] op_sel_hi:[1,0]
	v_pk_mul_f32 v[62:63], v[62:63], v[166:167] op_sel_hi:[1,0]
	v_pk_mul_f32 v[60:61], v[60:61], v[166:167] op_sel_hi:[1,0]
	v_pk_mul_f32 v[58:59], v[58:59], v[166:167] op_sel_hi:[1,0]
	s_waitcnt lgkmcnt(0)
	v_mfma_f32_32x32x16_bf16 v[96:111], v[4:7], v[120:123], v[96:111]
	ds_read_b128 v[4:7], v3 offset:96
	v_mul_f32_e64 v56, v56, v166
	v_mul_f32_e64 v57, v57, v166
	v_mul_f32_e64 v54, v54, v166
	v_mul_f32_e64 v55, v55, v166
	v_pk_mul_f32 v[52:53], v[52:53], v[166:167] op_sel_hi:[1,0]
	v_pk_mul_f32 v[50:51], v[50:51], v[166:167] op_sel_hi:[1,0]
	v_pk_mul_f32 v[48:49], v[48:49], v[166:167] op_sel_hi:[1,0]
	v_pk_mul_f32 v[46:47], v[46:47], v[166:167] op_sel_hi:[1,0]
	s_waitcnt lgkmcnt(0)
	v_mfma_f32_32x32x16_bf16 v[96:111], v[4:7], v[124:127], v[96:111]
	ds_read_b128 v[4:7], v3 offset:128
	v_mul_f32_e64 v44, v44, v166
	v_mul_f32_e64 v45, v45, v166
	v_mul_f32_e64 v42, v42, v166
	v_mul_f32_e64 v43, v43, v166
	v_pk_mul_f32 v[40:41], v[40:41], v[166:167] op_sel_hi:[1,0]
	v_pk_mul_f32 v[38:39], v[38:39], v[166:167] op_sel_hi:[1,0]
	v_pk_mul_f32 v[36:37], v[36:37], v[166:167] op_sel_hi:[1,0]
	v_pk_mul_f32 v[34:35], v[34:35], v[166:167] op_sel_hi:[1,0]
	s_waitcnt lgkmcnt(0)
	v_mfma_f32_32x32x16_bf16 v[96:111], v[4:7], v[128:131], v[96:111]
	ds_read_b128 v[4:7], v3 offset:160
	v_mul_f32_e64 v32, v32, v166
	v_mul_f32_e64 v33, v33, v166
	v_mul_f32_e64 v30, v30, v166
	v_mul_f32_e64 v31, v31, v166
	v_pk_mul_f32 v[28:29], v[28:29], v[166:167] op_sel_hi:[1,0]
	v_pk_mul_f32 v[26:27], v[26:27], v[166:167] op_sel_hi:[1,0]
	v_pk_mul_f32 v[24:25], v[24:25], v[166:167] op_sel_hi:[1,0]
	v_pk_mul_f32 v[22:23], v[22:23], v[166:167] op_sel_hi:[1,0]
	s_waitcnt lgkmcnt(0)
	v_mfma_f32_32x32x16_bf16 v[96:111], v[4:7], v[132:135], v[96:111]
	ds_read_b128 v[4:7], v3 offset:192
	v_mul_f32_e64 v20, v20, v166
	v_mul_f32_e64 v21, v21, v166
	v_mul_f32_e64 v18, v18, v166
	v_mul_f32_e64 v19, v19, v166
	v_pk_mul_f32 v[16:17], v[16:17], v[166:167] op_sel_hi:[1,0]
	s_add_i32 s24, s22, 0
	s_add_i32 s7, s7, 1
	s_add_i32 s68, s68, 64
	s_waitcnt lgkmcnt(0)
	v_mfma_f32_32x32x16_bf16 v[96:111], v[4:7], v[136:139], v[96:111]
	ds_read_b128 v[4:7], v3 offset:224
	v_cmp_eq_u32_e32 vcc, s7, v226
	s_or_b64 s[4:5], vcc, s[4:5]
	v_mov_b32_e32 v252, s23
	v_mov_b32_e32 v251, s6
	v_mov_b32_e32 v253, s22
	s_waitcnt vmcnt(0)
	v_sub_f32_e32 v2, v242, v2
	s_waitcnt lgkmcnt(0)
	v_mfma_f32_32x32x16_bf16 v[96:111], v[4:7], v[140:143], v[96:111]
	ds_read_b128 v[4:7], v3 offset:8704
	v_mul_f32_e32 v228, 0x3fb8aa3b, v2
	s_waitcnt lgkmcnt(0)
	v_mfma_f32_32x32x16_bf16 v[80:95], v[4:7], v[112:115], 0
	ds_read_b128 v[4:7], v3 offset:8736
	s_waitcnt lgkmcnt(0)
	v_mfma_f32_32x32x16_bf16 v[80:95], v[4:7], v[116:119], v[80:95]
	ds_read_b128 v[4:7], v3 offset:8768
	s_waitcnt lgkmcnt(0)
	v_mfma_f32_32x32x16_bf16 v[80:95], v[4:7], v[120:123], v[80:95]
	ds_read_b128 v[4:7], v3 offset:8800
	s_waitcnt lgkmcnt(0)
	v_mfma_f32_32x32x16_bf16 v[80:95], v[4:7], v[124:127], v[80:95]
	ds_read_b128 v[4:7], v3 offset:8832
	s_waitcnt lgkmcnt(0)
	v_mfma_f32_32x32x16_bf16 v[80:95], v[4:7], v[128:131], v[80:95]
	ds_read_b128 v[4:7], v3 offset:8864
	s_waitcnt lgkmcnt(0)
	v_mfma_f32_32x32x16_bf16 v[80:95], v[4:7], v[132:135], v[80:95]
	ds_read_b128 v[4:7], v3 offset:8896
	s_waitcnt lgkmcnt(0)
	v_mfma_f32_32x32x16_bf16 v[80:95], v[4:7], v[136:139], v[80:95]
	ds_read_b128 v[4:7], v3 offset:8928
	v_sub_f32_e32 v3, v222, v14
	v_exp_f32_e32 v3, v3
	s_waitcnt lgkmcnt(0)
	v_mfma_f32_32x32x16_bf16 v[80:95], v[4:7], v[140:143], v[80:95]
	v_sub_f32_e32 v4, v223, v14
	v_exp_f32_e32 v4, v4
	v_add_f32_e32 v5, 0, v3
	v_add_f32_e32 v6, v4, v5
	v_sub_f32_e32 v5, v220, v14
	v_exp_f32_e32 v5, v5
	v_cvt_pk_bf16_f32 v2, v3, v4
	v_add_f32_e32 v7, v5, v6
	v_sub_f32_e32 v6, v221, v14
	v_exp_f32_e32 v6, v6
	s_nop 0
	v_add_f32_e32 v8, v6, v7
	v_sub_f32_e32 v7, v218, v14
	v_exp_f32_e32 v7, v7
	v_cvt_pk_bf16_f32 v3, v5, v6
	v_add_f32_e32 v9, v7, v8
	v_sub_f32_e32 v8, v219, v14
	v_exp_f32_e32 v8, v8
	s_nop 0
	v_add_f32_e32 v10, v8, v9
	v_sub_f32_e32 v9, v206, v14
	v_exp_f32_e32 v9, v9
	v_cvt_pk_bf16_f32 v4, v7, v8
	v_add_f32_e32 v11, v9, v10
	v_sub_f32_e32 v10, v207, v14
	v_exp_f32_e32 v10, v10
	s_nop 0
	v_add_f32_e32 v12, v10, v11
	v_sub_f32_e32 v11, v216, v14
	v_exp_f32_e32 v11, v11
	v_cvt_pk_bf16_f32 v5, v9, v10
	v_add_f32_e32 v13, v11, v12
	v_sub_f32_e32 v12, v217, v14
	v_exp_f32_e32 v12, v12
	s_nop 0
	v_add_f32_e32 v144, v12, v13
	v_sub_f32_e32 v13, v204, v14
	v_exp_f32_e32 v13, v13
	v_cvt_pk_bf16_f32 v6, v11, v12
	v_add_f32_e32 v145, v13, v144
	v_sub_f32_e32 v144, v205, v14
	v_exp_f32_e32 v144, v144
	s_nop 0
	v_add_f32_e32 v146, v144, v145
	v_sub_f32_e32 v145, v194, v14
	v_exp_f32_e32 v145, v145
	v_cvt_pk_bf16_f32 v7, v13, v144
	v_add_f32_e32 v147, v145, v146
	v_sub_f32_e32 v146, v195, v14
	v_exp_f32_e32 v146, v146
	s_nop 0
	v_add_f32_e32 v175, v146, v147
	v_sub_f32_e32 v147, v192, v14
	v_exp_f32_e32 v147, v147
	v_cvt_pk_bf16_f32 v8, v145, v146
	v_add_f32_e32 v180, v147, v175
	v_sub_f32_e32 v175, v193, v14
	v_exp_f32_e32 v175, v175
	s_nop 0
	v_add_f32_e32 v207, v175, v180
	v_sub_f32_e32 v180, v200, v14
	v_exp_f32_e32 v192, v180
	v_sub_f32_e32 v180, v201, v14
	v_exp_f32_e32 v193, v180
	v_sub_f32_e32 v180, v196, v14
	v_exp_f32_e32 v194, v180
	v_sub_f32_e32 v180, v197, v14
	v_exp_f32_e32 v195, v180
	v_sub_f32_e32 v180, v198, v14
	v_exp_f32_e32 v196, v180
	v_sub_f32_e32 v180, v199, v14
	v_exp_f32_e32 v197, v180
	v_sub_f32_e32 v180, v202, v14
	v_exp_f32_e32 v198, v180
	v_sub_f32_e32 v180, v203, v14
	v_exp_f32_e32 v199, v180
	v_sub_f32_e32 v180, v212, v14
	v_exp_f32_e32 v200, v180
	v_sub_f32_e32 v180, v213, v14
	v_exp_f32_e32 v201, v180
	v_sub_f32_e32 v180, v208, v14
	v_exp_f32_e32 v202, v180
	v_sub_f32_e32 v180, v209, v14
	v_exp_f32_e32 v203, v180
	v_sub_f32_e32 v180, v210, v14
	v_exp_f32_e32 v204, v180
	v_sub_f32_e32 v180, v211, v14
	v_exp_f32_e32 v205, v180
	v_sub_f32_e32 v180, v214, v14
	v_exp_f32_e32 v206, v180
	v_sub_f32_e32 v180, v215, v14
	v_exp_f32_e32 v208, v180
	v_add_f32_e32 v180, v192, v207
	v_add_f32_e32 v180, v193, v180
	v_add_f32_e32 v180, v194, v180
	v_add_f32_e32 v180, v195, v180
	v_add_f32_e32 v180, v196, v180
	v_add_f32_e32 v180, v197, v180
	v_add_f32_e32 v180, v198, v180
	v_add_f32_e32 v180, v199, v180
	v_add_f32_e32 v180, v200, v180
	v_add_f32_e32 v180, v201, v180
	v_add_f32_e32 v180, v202, v180
	v_add_f32_e32 v180, v203, v180
	v_add_f32_e32 v180, v204, v180
	v_add_f32_e32 v180, v205, v180
	v_add_f32_e32 v180, v206, v180
	v_cvt_pk_bf16_f32 v9, v147, v175
	v_add_f32_e32 v175, v208, v180
	v_add3_u32 v180, v244, s23, v173
	v_cvt_pk_bf16_f32 v10, v192, v193
	v_cvt_pk_bf16_f32 v11, v194, v195
	v_cvt_pk_bf16_f32 v12, v196, v197
	v_cvt_pk_bf16_f32 v13, v198, v199
	ds_read_b128 v[192:195], v180 offset:17408
	ds_read_b128 v[196:199], v180 offset:17440
	s_waitcnt lgkmcnt(1)
	v_mfma_f32_32x32x16_bf16 v[64:79], v[192:195], v[2:5], v[64:79]
	ds_read_b128 v[192:195], v180 offset:17472
	v_cvt_pk_bf16_f32 v144, v200, v201
	v_cvt_pk_bf16_f32 v145, v202, v203
	v_cvt_pk_bf16_f32 v146, v204, v205
	v_cvt_pk_bf16_f32 v147, v206, v208
	v_fmac_f32_e32 v175, v1, v166
	s_waitcnt lgkmcnt(1)
	v_mfma_f32_32x32x16_bf16 v[64:79], v[196:199], v[6:9], v[64:79]
	s_waitcnt lgkmcnt(0)
	v_mfma_f32_32x32x16_bf16 v[64:79], v[192:195], v[10:13], v[64:79]
	ds_read_b128 v[192:195], v180 offset:17504
	s_waitcnt lgkmcnt(0)
	v_mfma_f32_32x32x16_bf16 v[64:79], v[192:195], v[144:147], v[64:79]
	ds_read_b128 v[192:195], v180 offset:22016
	s_waitcnt lgkmcnt(0)
	v_mfma_f32_32x32x16_bf16 v[48:63], v[192:195], v[2:5], v[48:63]
	ds_read_b128 v[192:195], v180 offset:22048
	s_waitcnt lgkmcnt(0)
	v_mfma_f32_32x32x16_bf16 v[48:63], v[192:195], v[6:9], v[48:63]
	ds_read_b128 v[192:195], v180 offset:22080
	s_waitcnt lgkmcnt(0)
	v_mfma_f32_32x32x16_bf16 v[48:63], v[192:195], v[10:13], v[48:63]
	ds_read_b128 v[192:195], v180 offset:22112
	s_waitcnt lgkmcnt(0)
; #define FY_STORE(bb) do { *(u32x4*)((bb) + kr0 * FX_KROW + kc * 16) = kreg[0]; *(u32x4*)((bb) + (kr0 + 32) * FX_KROW + kc * 16) = kreg[1]; \
;         *(u32x4*)((bb) + FX_KBYTES + vd0 * FX_VROW + vc * 16) = vreg[0]; *(u32x4*)((bb) + FX_KBYTES + (vd0 + 64) * FX_VROW + vc * 16) = vreg[1]; \
;         ((float*)((bb) + FX_KBYTES + FX_VBYTES))[lane] = breg; } while (0)
; __device__ __forceinline__ void fox_unit2(ArgsP a, int bh, int qb, unsigned char* lds) {
;     ...
;     __syncthreads();
;     FY_LOAD(0); FY_STORE(lds);
;     FY_LOAD(1); FY_STORE(lds + FX_BUF);
;     __syncthreads();
;     f32x16 sc[2], sn[2]; bf16x8_t pb[4];
;     FY_QK(sc, lds);
;     FY_BMAX(sc, lds, 0, true);
;     int bc = 0, bn = FX_BUF, bs = 2 * FX_BUF;
;     ...
;     const int tqw_max = qb * 256 + wave * 32 + 31;
;     int t = 0;
;     for (; t + 1 < 4 * qb; ++t) FY_ITER(false);
;     for (; t + 1 < nt; ++t) FY_ITER(true);
;     if (64 * (nt - 1) <= tqw_max) { FY_EXP(sc); FY_PV(lds + bc); }
	v_mfma_f32_32x32x16_bf16 v[48:63], v[192:195], v[144:147], v[48:63]
	ds_read_b128 v[192:195], v180 offset:26624
	s_waitcnt lgkmcnt(0)
	v_mfma_f32_32x32x16_bf16 v[32:47], v[192:195], v[2:5], v[32:47]
	ds_read_b128 v[192:195], v180 offset:26656
	s_waitcnt lgkmcnt(0)
	v_mfma_f32_32x32x16_bf16 v[32:47], v[192:195], v[6:9], v[32:47]
	ds_read_b128 v[192:195], v180 offset:26688
	s_waitcnt lgkmcnt(0)
	v_mfma_f32_32x32x16_bf16 v[32:47], v[192:195], v[10:13], v[32:47]
	ds_read_b128 v[192:195], v180 offset:26720
	s_waitcnt lgkmcnt(0)
	v_mfma_f32_32x32x16_bf16 v[32:47], v[192:195], v[144:147], v[32:47]
	ds_read_b128 v[192:195], v180 offset:31232
	s_waitcnt lgkmcnt(0)
	v_mfma_f32_32x32x16_bf16 v[16:31], v[192:195], v[2:5], v[16:31]
	ds_read_b128 v[192:195], v180 offset:31264
	s_waitcnt lgkmcnt(0)
	v_mfma_f32_32x32x16_bf16 v[16:31], v[192:195], v[6:9], v[16:31]
	ds_read_b128 v[192:195], v180 offset:31296
	s_waitcnt lgkmcnt(0)
	v_mfma_f32_32x32x16_bf16 v[16:31], v[192:195], v[10:13], v[16:31]
	ds_read_b128 v[192:195], v180 offset:31328
	s_waitcnt lgkmcnt(0)
	v_mfma_f32_32x32x16_bf16 v[16:31], v[192:195], v[144:147], v[16:31]
	ds_read_b128 v[192:195], v15 offset:35840
	ds_read_b128 v[196:199], v15 offset:35872
	s_waitcnt lgkmcnt(1)
	v_add_f32_e64 v222, v96, v192
	v_add_f32_e64 v223, v97, v193
	v_max3_f32 v96, v222, s59, v223
	v_pk_add_f32 v[220:221], v[98:99], v[194:195]
	s_waitcnt lgkmcnt(0)
	v_pk_add_f32 v[218:219], v[100:101], v[196:197]
	v_max3_f32 v96, v96, v220, v221
	v_max3_f32 v96, v96, v218, v219
	v_pk_add_f32 v[206:207], v[102:103], v[198:199]
	s_nop 0
	v_max3_f32 v100, v96, v206, v207
	ds_read_b128 v[96:99], v15 offset:35904
	s_waitcnt lgkmcnt(0)
	v_pk_add_f32 v[216:217], v[104:105], v[96:97]
	s_nop 0
	v_max3_f32 v96, v100, v216, v217
	v_pk_add_f32 v[204:205], v[106:107], v[98:99]
	s_nop 0
	v_max3_f32 v100, v96, v204, v205
	ds_read_b128 v[96:99], v15 offset:35936
	s_waitcnt lgkmcnt(0)
	v_pk_add_f32 v[194:195], v[108:109], v[96:97]
	s_nop 0
	v_max3_f32 v96, v100, v194, v195
	v_pk_add_f32 v[192:193], v[110:111], v[98:99]
	s_nop 0
	v_max3_f32 v100, v96, v192, v193
	ds_read_b128 v[96:99], v15 offset:35968
	s_waitcnt lgkmcnt(0)
	v_pk_add_f32 v[200:201], v[80:81], v[96:97]
	s_nop 0
	v_max3_f32 v80, v100, v200, v201
	v_pk_add_f32 v[196:197], v[82:83], v[98:99]
	s_nop 0
	v_max3_f32 v96, v80, v196, v197
	ds_read_b128 v[80:83], v15 offset:36000
	s_waitcnt lgkmcnt(0)
	v_pk_add_f32 v[198:199], v[84:85], v[80:81]
	s_nop 0
	v_max3_f32 v80, v96, v198, v199
	v_pk_add_f32 v[202:203], v[86:87], v[82:83]
	s_nop 0
	v_max3_f32 v84, v80, v202, v203
	ds_read_b128 v[80:83], v15 offset:36032
	s_waitcnt lgkmcnt(0)
	v_pk_add_f32 v[212:213], v[88:89], v[80:81]
	s_nop 0
	v_max3_f32 v80, v84, v212, v213
	v_pk_add_f32 v[208:209], v[90:91], v[82:83]
	s_nop 0
	v_max3_f32 v84, v80, v208, v209
	ds_read_b128 v[80:83], v15 offset:36064
	s_waitcnt lgkmcnt(0)
	v_pk_add_f32 v[210:211], v[92:93], v[80:81]
	s_nop 0
	v_max3_f32 v15, v84, v210, v211
	v_pk_add_f32 v[214:215], v[94:95], v[82:83]
	s_nop 0
	v_max3_f32 v15, v15, v214, v215
	ds_bpermute_b32 v1, v171, v15
	s_waitcnt lgkmcnt(0)
	v_max3_f32 v248, v14, v15, v1
	v_sub_f32_e32 v1, v14, v248
	v_exp_f32_e32 v166, v1
	v_add3_u32 v1, s24, v177, v174
	ds_write_b128 v1, v[148:151]
	v_add3_u32 v1, s24, v245, v174
	ds_write_b128 v1, v[152:155]
	v_add3_u32 v1, s24, v243, v176
	ds_write_b128 v1, v[156:159] offset:17408
	v_add3_u32 v1, s24, v246, v176
	ds_write_b128 v1, v[160:163] offset:17408
	v_lshl_add_u32 v1, v241, 2, s24
	s_mov_b32 s24, s6
	s_mov_b32 s6, s22
	s_mov_b32 s22, s23
	ds_write_b32 v1, v228 offset:35840
	s_waitcnt lgkmcnt(0)
	s_barrier
	s_andn2_b64 exec, exec, s[4:5]
	s_cbranch_execnz .LBB0_882
	s_or_b64 exec, exec, s[4:5]
	v_mov_b32_e32 v95, v215
	v_mov_b32_e32 v94, v214
	v_mov_b32_e32 v93, v211
	v_mov_b32_e32 v92, v210
	v_mov_b32_e32 v91, v209
	v_mov_b32_e32 v90, v208
	v_mov_b32_e32 v89, v213
	v_mov_b32_e32 v88, v212
	v_mov_b32_e32 v87, v203
	v_mov_b32_e32 v86, v202
	v_mov_b32_e32 v85, v199
	v_mov_b32_e32 v84, v198
	v_mov_b32_e32 v83, v197
	v_mov_b32_e32 v82, v196
	v_mov_b32_e32 v81, v201
	v_mov_b32_e32 v80, v200
	v_mov_b32_e32 v111, v193
	v_mov_b32_e32 v110, v192
	v_mov_b32_e32 v109, v195
	v_mov_b32_e32 v108, v194
	v_mov_b32_e32 v107, v205
	v_mov_b32_e32 v106, v204
	v_mov_b32_e32 v105, v217
	v_mov_b32_e32 v104, v216
	v_mov_b32_e32 v103, v207
	v_mov_b32_e32 v102, v206
	v_mov_b32_e32 v101, v219
	v_mov_b32_e32 v100, v218
	v_mov_b32_e32 v99, v221
	v_mov_b32_e32 v98, v220
	v_mov_b32_e32 v97, v223
	v_mov_b32_e32 v96, v222

; #define PG8_STAGE(bufoff, gbase, voff) do { _Pragma("unroll") for (int _i = 0; _i < 2; ++_i) \
;         __builtin_amdgcn_global_load_lds((const unsigned*)((const char*)(gbase) + (voff)[_i]), (PG8_LAS unsigned*)(lds + (bufoff) + ldsw + _i * 8192), 16, 0, 0); } while (0)
; #define PG8_LDA(dst, b, h) do { _Pragma("unroll") for (int m = 0; m < 4; ++m) _Pragma("unroll") for (int k = 0; k < 2; ++k) dst[m][k] = *(const PG8_LAS bf16x8*)(lds + PG8_SA(b, h) + aoff + m * 2048 + k * 1024); } while (0)
; #define PG8_LDB(dst, b, h) do { _Pragma("unroll") for (int n = 0; n < 2; ++n) _Pragma("unroll") for (int k = 0; k < 2; ++k) dst[n][k] = *(const PG8_LAS bf16x8*)(lds + PG8_SB(b, h) + boff + n * 2048 + k * 1024); } while (0)
; #define PG8_MMA(ai, bj, At, Bt) do { __builtin_amdgcn_s_setprio(1); _Pragma("unroll") for (int m = 0; m < 4; ++m) _Pragma("unroll") for (int n = 0; n < 2; ++n) _Pragma("unroll") for (int k = 0; k < 2; ++k) \
;         acc[ai][bj][m][n] = __builtin_amdgcn_mfma_f32_16x16x32_bf16(Bt[n][k], At[m][k], acc[ai][bj][m][n], 0, 0, 0); __builtin_amdgcn_s_setprio(0); } while (0)
; #define PG8_WAIT_V(n) asm volatile("s_waitcnt vmcnt(" #n ")" ::: "memory")
; #define PG8_BAR __builtin_amdgcn_s_barrier()
; template <class Epi, class Sched, bool ALIGN_EPI = false, bool SP2 = false>
; __device__ __forceinline__ void gemm_phase(PG8_LAS unsigned char* lds, const Gemm g, const Sched& S, const Epi& E) {
;     ...
;         for (int t = 0; t < nt; t += 2) {
;             const bool last = (t == nt - 2);
;             const char* a1 = cA + (size_t)(t + 1) * kstep;
;             const char* a2 = last ? nA : cA + (size_t)(t + 2) * kstep; const char* b2 = last ? nB : cB + (size_t)(t + 2) * kstep;
;             const char* a3 = a2 + kstep; const char* b3 = b2 + kstep;
;             if (last && has_next) S.a_ready(nxt);
;             if constexpr (SP2) {
;             PG8_LDB(B0, 0, 0); PG8_LDB(B1, 0, 1); PG8_SCHED; PG8_LDA(At, 0, 0); PG8_STAGE(PG8_SA(1, 1), a1 + hstep, voffA);
;             PG8_WAIT_V(8); PG8_WAIT_L(0); PG8_BAR; PG8_MMA(0, 0, At, B0); PG8_MMA(0, 1, At, B1); PG8_BAR; PG8_SCHED;
;             PG8_LDA(At, 0, 1); PG8_STAGE(PG8_SB(0, 0), b2, voffB); PG8_STAGE(PG8_SB(0, 1), b2 + hstep, voffB); PG8_STAGE(PG8_SA(0, 0), a2, voffA);
;             PG8_WAIT_V(8); PG8_WAIT_L(0); PG8_BAR; PG8_MMA(1, 0, At, B0); PG8_MMA(1, 1, At, B1); PG8_BAR; PG8_SCHED;
.LBB0_1062:
	s_add_u32 s36, s34, 0xfffc0080
	s_addc_u32 s37, s35, -1
	s_add_i32 s59, 0, 0x10000
	s_cmp_eq_u32 s58, 12
	s_cselect_b32 s39, s23, s37
	s_cselect_b32 s38, s29, s36
	s_cselect_b32 s37, s21, s57
	s_cselect_b32 s36, s31, s56
	s_add_i32 s62, 0, 0x14000
	v_add_u32_e32 v142, s59, v179
	v_add_u32_e32 v170, s62, v179
	ds_read_b128 v[130:133], v142
	ds_read_b128 v[134:137], v142 offset:1024
	ds_read_b128 v[138:141], v142 offset:2048
	ds_read_b128 v[142:145], v142 offset:3072
	ds_read_b128 v[146:149], v170
	ds_read_b128 v[150:153], v170 offset:1024
	ds_read_b128 v[166:169], v170 offset:2048
	ds_read_b128 v[170:173], v170 offset:3072
	v_lshl_add_u64 v[212:213], s[34:35], 0, v[162:163]
	s_add_i32 m0, s46, 0xc000
	ds_read_b128 v[174:177], v187
	ds_read_b128 v[180:183], v187 offset:1024
	ds_read_b128 v[188:191], v187 offset:2048
	ds_read_b128 v[192:195], v187 offset:3072
	ds_read_b128 v[196:199], v187 offset:4096
	ds_read_b128 v[200:203], v187 offset:5120
	ds_read_b128 v[204:207], v187 offset:6144
	ds_read_b128 v[208:211], v187 offset:7168
	global_load_lds_dwordx4 v[212:213], off
	v_lshl_add_u64 v[212:213], s[34:35], 0, v[164:165]
	s_add_i32 m0, s46, 0xe000
	s_nop 0
	global_load_lds_dwordx4 v[212:213], off
	s_waitcnt vmcnt(8)
	s_waitcnt lgkmcnt(0)
	s_barrier
	s_setprio 1
	v_mfma_f32_16x16x32_bf16 v[126:129], v[130:133], v[174:177], v[126:129]
	v_mfma_f32_16x16x32_bf16 v[122:125], v[138:141], v[174:177], v[122:125]
	v_mfma_f32_16x16x32_bf16 v[110:113], v[130:133], v[188:191], v[110:113]
	v_mfma_f32_16x16x32_bf16 v[106:109], v[138:141], v[188:191], v[106:109]
	v_mfma_f32_16x16x32_bf16 v[94:97], v[130:133], v[196:199], v[94:97]
	v_mfma_f32_16x16x32_bf16 v[90:93], v[138:141], v[196:199], v[90:93]
	v_mfma_f32_16x16x32_bf16 v[78:81], v[130:133], v[204:207], v[78:81]
	v_mfma_f32_16x16x32_bf16 v[74:77], v[138:141], v[204:207], v[74:77]
	v_mfma_f32_16x16x32_bf16 v[126:129], v[134:137], v[180:183], v[126:129]
	v_mfma_f32_16x16x32_bf16 v[122:125], v[142:145], v[180:183], v[122:125]
	v_mfma_f32_16x16x32_bf16 v[110:113], v[134:137], v[192:195], v[110:113]
	v_mfma_f32_16x16x32_bf16 v[106:109], v[142:145], v[192:195], v[106:109]
	v_mfma_f32_16x16x32_bf16 v[94:97], v[134:137], v[200:203], v[94:97]
	v_mfma_f32_16x16x32_bf16 v[90:93], v[142:145], v[200:203], v[90:93]
	v_mfma_f32_16x16x32_bf16 v[78:81], v[134:137], v[208:211], v[78:81]
	v_mfma_f32_16x16x32_bf16 v[74:77], v[142:145], v[208:211], v[74:77]
	s_setprio 0
	s_setprio 1
	v_mfma_f32_16x16x32_bf16 v[118:121], v[146:149], v[174:177], v[118:121]
	v_mfma_f32_16x16x32_bf16 v[114:117], v[166:169], v[174:177], v[114:117]
	v_mfma_f32_16x16x32_bf16 v[102:105], v[146:149], v[188:191], v[102:105]
	v_mfma_f32_16x16x32_bf16 v[98:101], v[166:169], v[188:191], v[98:101]
	v_mfma_f32_16x16x32_bf16 v[86:89], v[146:149], v[196:199], v[86:89]
	v_mfma_f32_16x16x32_bf16 v[82:85], v[166:169], v[196:199], v[82:85]
	v_mfma_f32_16x16x32_bf16 v[70:73], v[146:149], v[204:207], v[70:73]
	v_mfma_f32_16x16x32_bf16 v[66:69], v[166:169], v[204:207], v[66:69]
	v_mfma_f32_16x16x32_bf16 v[118:121], v[150:153], v[180:183], v[118:121]
	v_mfma_f32_16x16x32_bf16 v[114:117], v[170:173], v[180:183], v[114:117]
	v_mfma_f32_16x16x32_bf16 v[102:105], v[150:153], v[192:195], v[102:105]
	v_mfma_f32_16x16x32_bf16 v[98:101], v[170:173], v[192:195], v[98:101]
	v_mfma_f32_16x16x32_bf16 v[86:89], v[150:153], v[200:203], v[86:89]
	v_mfma_f32_16x16x32_bf16 v[82:85], v[170:173], v[200:203], v[82:85]
	v_mfma_f32_16x16x32_bf16 v[70:73], v[150:153], v[208:211], v[70:73]
	v_mfma_f32_16x16x32_bf16 v[66:69], v[170:173], v[208:211], v[66:69]
	s_setprio 0
	s_barrier
	s_add_i32 s59, s59, s33
	v_lshl_add_u64 v[212:213], s[36:37], 0, v[156:157]
	s_mov_b32 m0, s59
	ds_read_b128 v[174:177], v187 offset:16384
	ds_read_b128 v[180:183], v187 offset:17408
	ds_read_b128 v[188:191], v187 offset:18432
	ds_read_b128 v[192:195], v187 offset:19456
	ds_read_b128 v[196:199], v187 offset:20480
	ds_read_b128 v[200:203], v187 offset:21504
	ds_read_b128 v[204:207], v187 offset:22528
	ds_read_b128 v[208:211], v187 offset:23552
	global_load_lds_dwordx4 v[212:213], off
	s_add_i32 m0, s59, 0x2000
	s_add_u32 s60, s36, 0x40000
	v_lshl_add_u64 v[214:215], s[36:37], 0, v[160:161]
	s_addc_u32 s61, s37, 0
	s_add_i32 s59, s62, s33
	global_load_lds_dwordx4 v[214:215], off
	v_lshl_add_u64 v[216:217], s[60:61], 0, v[156:157]
	s_mov_b32 m0, s59
	v_lshl_add_u64 v[218:219], s[38:39], 0, v[158:159]
	global_load_lds_dwordx4 v[216:217], off
	v_lshl_add_u64 v[216:217], s[60:61], 0, v[160:161]
	s_add_i32 m0, s59, 0x2000
	s_nop 0
	global_load_lds_dwordx4 v[216:217], off
	v_lshl_add_u64 v[216:217], s[38:39], 0, v[154:155]
	s_mov_b32 m0, s46
	s_nop 0
	global_load_lds_dwordx4 v[216:217], off
	s_mov_b32 m0, s47
	s_nop 0
	global_load_lds_dwordx4 v[218:219], off
	s_waitcnt vmcnt(8)
	s_waitcnt lgkmcnt(0)
	s_barrier
; #define PG8_STAGE(bufoff, gbase, voff) do { _Pragma("unroll") for (int _i = 0; _i < 2; ++_i) \
;         __builtin_amdgcn_global_load_lds((const unsigned*)((const char*)(gbase) + (voff)[_i]), (PG8_LAS unsigned*)(lds + (bufoff) + ldsw + _i * 8192), 16, 0, 0); } while (0)
; #define PG8_LDA(dst, b, h) do { _Pragma("unroll") for (int m = 0; m < 4; ++m) _Pragma("unroll") for (int k = 0; k < 2; ++k) dst[m][k] = *(const PG8_LAS bf16x8*)(lds + PG8_SA(b, h) + aoff + m * 2048 + k * 1024); } while (0)
; #define PG8_LDB(dst, b, h) do { _Pragma("unroll") for (int n = 0; n < 2; ++n) _Pragma("unroll") for (int k = 0; k < 2; ++k) dst[n][k] = *(const PG8_LAS bf16x8*)(lds + PG8_SB(b, h) + boff + n * 2048 + k * 1024); } while (0)
; #define PG8_MMA(ai, bj, At, Bt) do { __builtin_amdgcn_s_setprio(1); _Pragma("unroll") for (int m = 0; m < 4; ++m) _Pragma("unroll") for (int n = 0; n < 2; ++n) _Pragma("unroll") for (int k = 0; k < 2; ++k) \
;         acc[ai][bj][m][n] = __builtin_amdgcn_mfma_f32_16x16x32_bf16(Bt[n][k], At[m][k], acc[ai][bj][m][n], 0, 0, 0); __builtin_amdgcn_s_setprio(0); } while (0)
; #define PG8_WAIT_V(n) asm volatile("s_waitcnt vmcnt(" #n ")" ::: "memory")
; #define PG8_WAIT_L(n) asm volatile("s_waitcnt lgkmcnt(" #n ")" ::: "memory")
; #define PG8_BAR __builtin_amdgcn_s_barrier()
; #define PG8_SCHED __builtin_amdgcn_sched_barrier(0)
; template <class Epi, class Sched, bool ALIGN_EPI = false, bool SP2 = false>
; __device__ __forceinline__ void gemm_phase(PG8_LAS unsigned char* lds, const Gemm g, const Sched& S, const Epi& E) {
;     ...
;             PG8_WAIT_V(8); PG8_WAIT_L(0); PG8_BAR; PG8_MMA(1, 0, At, B0); PG8_MMA(1, 1, At, B1); PG8_BAR; PG8_SCHED;
;             PG8_LDB(B0, 1, 0); PG8_LDB(B1, 1, 1); PG8_SCHED; PG8_LDA(At, 1, 0); PG8_STAGE(PG8_SA(0, 1), a2 + hstep, voffA);
;             PG8_WAIT_V(8); PG8_WAIT_L(0); PG8_BAR; PG8_MMA(0, 0, At, B0); PG8_MMA(0, 1, At, B1); PG8_BAR; PG8_SCHED;
	s_setprio 1
	v_mfma_f32_16x16x32_bf16 v[62:65], v[130:133], v[174:177], v[62:65]
	v_mfma_f32_16x16x32_bf16 v[58:61], v[138:141], v[174:177], v[58:61]
	v_mfma_f32_16x16x32_bf16 v[46:49], v[130:133], v[188:191], v[46:49]
	v_mfma_f32_16x16x32_bf16 v[42:45], v[138:141], v[188:191], v[42:45]
	v_mfma_f32_16x16x32_bf16 v[30:33], v[130:133], v[196:199], v[30:33]
	v_mfma_f32_16x16x32_bf16 v[26:29], v[138:141], v[196:199], v[26:29]
	v_mfma_f32_16x16x32_bf16 v[14:17], v[130:133], v[204:207], v[14:17]
	v_mfma_f32_16x16x32_bf16 v[10:13], v[138:141], v[204:207], v[10:13]
	v_mfma_f32_16x16x32_bf16 v[62:65], v[134:137], v[180:183], v[62:65]
	v_mfma_f32_16x16x32_bf16 v[58:61], v[142:145], v[180:183], v[58:61]
	v_mfma_f32_16x16x32_bf16 v[46:49], v[134:137], v[192:195], v[46:49]
	v_mfma_f32_16x16x32_bf16 v[42:45], v[142:145], v[192:195], v[42:45]
	v_mfma_f32_16x16x32_bf16 v[30:33], v[134:137], v[200:203], v[30:33]
	v_mfma_f32_16x16x32_bf16 v[26:29], v[142:145], v[200:203], v[26:29]
	v_mfma_f32_16x16x32_bf16 v[14:17], v[134:137], v[208:211], v[14:17]
	v_mfma_f32_16x16x32_bf16 v[10:13], v[142:145], v[208:211], v[10:13]
	s_setprio 0
	s_setprio 1
	v_mfma_f32_16x16x32_bf16 v[54:57], v[146:149], v[174:177], v[54:57]
	v_mfma_f32_16x16x32_bf16 v[50:53], v[166:169], v[174:177], v[50:53]
	v_mfma_f32_16x16x32_bf16 v[38:41], v[146:149], v[188:191], v[38:41]
	v_mfma_f32_16x16x32_bf16 v[34:37], v[166:169], v[188:191], v[34:37]
	v_mfma_f32_16x16x32_bf16 v[22:25], v[146:149], v[196:199], v[22:25]
	v_mfma_f32_16x16x32_bf16 v[18:21], v[166:169], v[196:199], v[18:21]
	v_mfma_f32_16x16x32_bf16 v[6:9], v[146:149], v[204:207], v[6:9]
	v_mfma_f32_16x16x32_bf16 v[2:5], v[166:169], v[204:207], v[2:5]
	v_mfma_f32_16x16x32_bf16 v[54:57], v[150:153], v[180:183], v[54:57]
	v_mfma_f32_16x16x32_bf16 v[50:53], v[170:173], v[180:183], v[50:53]
	v_mfma_f32_16x16x32_bf16 v[38:41], v[150:153], v[192:195], v[38:41]
	v_mfma_f32_16x16x32_bf16 v[34:37], v[170:173], v[192:195], v[34:37]
	v_mfma_f32_16x16x32_bf16 v[22:25], v[150:153], v[200:203], v[22:25]
	v_mfma_f32_16x16x32_bf16 v[18:21], v[170:173], v[200:203], v[18:21]
	v_mfma_f32_16x16x32_bf16 v[6:9], v[150:153], v[208:211], v[6:9]
	v_mfma_f32_16x16x32_bf16 v[2:5], v[170:173], v[208:211], v[2:5]
	s_setprio 0
	s_barrier
	s_add_i32 s59, 0, 0x18000
	s_add_i32 s60, 0, 0x1c000
	v_add_u32_e32 v142, s59, v179
	v_add_u32_e32 v170, s60, v179
	ds_read_b128 v[130:133], v142
	ds_read_b128 v[134:137], v142 offset:1024
	ds_read_b128 v[138:141], v142 offset:2048
	ds_read_b128 v[142:145], v142 offset:3072
	ds_read_b128 v[146:149], v170
	ds_read_b128 v[150:153], v170 offset:1024
	ds_read_b128 v[166:169], v170 offset:2048
	ds_read_b128 v[170:173], v170 offset:3072
	s_add_u32 s38, s38, 0x40000
	s_addc_u32 s39, s39, 0
	s_mov_b32 m0, s48
	v_lshl_add_u64 v[220:221], s[38:39], 0, v[154:155]
	ds_read_b128 v[174:177], v187 offset:32768
	ds_read_b128 v[180:183], v187 offset:33792
	ds_read_b128 v[188:191], v187 offset:34816
	ds_read_b128 v[192:195], v187 offset:35840
	ds_read_b128 v[196:199], v187 offset:36864
	ds_read_b128 v[200:203], v187 offset:37888
	ds_read_b128 v[204:207], v187 offset:38912
	ds_read_b128 v[208:211], v187 offset:39936
	global_load_lds_dwordx4 v[220:221], off
	v_lshl_add_u64 v[220:221], s[38:39], 0, v[158:159]
	s_mov_b32 m0, s49
	s_nop 0
	global_load_lds_dwordx4 v[220:221], off
	s_waitcnt vmcnt(8)
	s_waitcnt lgkmcnt(0)
	s_barrier
	s_setprio 1
	v_mfma_f32_16x16x32_bf16 v[126:129], v[130:133], v[174:177], v[126:129]
	v_mfma_f32_16x16x32_bf16 v[122:125], v[138:141], v[174:177], v[122:125]
	v_mfma_f32_16x16x32_bf16 v[110:113], v[130:133], v[188:191], v[110:113]
	v_mfma_f32_16x16x32_bf16 v[106:109], v[138:141], v[188:191], v[106:109]
	v_mfma_f32_16x16x32_bf16 v[94:97], v[130:133], v[196:199], v[94:97]
	v_mfma_f32_16x16x32_bf16 v[90:93], v[138:141], v[196:199], v[90:93]
	v_mfma_f32_16x16x32_bf16 v[78:81], v[130:133], v[204:207], v[78:81]
	v_mfma_f32_16x16x32_bf16 v[74:77], v[138:141], v[204:207], v[74:77]
	v_mfma_f32_16x16x32_bf16 v[126:129], v[134:137], v[180:183], v[126:129]
	v_mfma_f32_16x16x32_bf16 v[122:125], v[142:145], v[180:183], v[122:125]
	v_mfma_f32_16x16x32_bf16 v[110:113], v[134:137], v[192:195], v[110:113]
	v_mfma_f32_16x16x32_bf16 v[106:109], v[142:145], v[192:195], v[106:109]
	v_mfma_f32_16x16x32_bf16 v[94:97], v[134:137], v[200:203], v[94:97]
	v_mfma_f32_16x16x32_bf16 v[90:93], v[142:145], v[200:203], v[90:93]
	v_mfma_f32_16x16x32_bf16 v[78:81], v[134:137], v[208:211], v[78:81]
	v_mfma_f32_16x16x32_bf16 v[74:77], v[142:145], v[208:211], v[74:77]
	s_setprio 0
	s_setprio 1
	v_mfma_f32_16x16x32_bf16 v[118:121], v[146:149], v[174:177], v[118:121]
	v_mfma_f32_16x16x32_bf16 v[114:117], v[166:169], v[174:177], v[114:117]
	v_mfma_f32_16x16x32_bf16 v[102:105], v[146:149], v[188:191], v[102:105]
	v_mfma_f32_16x16x32_bf16 v[98:101], v[166:169], v[188:191], v[98:101]
	v_mfma_f32_16x16x32_bf16 v[86:89], v[146:149], v[196:199], v[86:89]
	v_mfma_f32_16x16x32_bf16 v[82:85], v[166:169], v[196:199], v[82:85]
	v_mfma_f32_16x16x32_bf16 v[70:73], v[146:149], v[204:207], v[70:73]
	v_mfma_f32_16x16x32_bf16 v[66:69], v[166:169], v[204:207], v[66:69]
	v_mfma_f32_16x16x32_bf16 v[118:121], v[150:153], v[180:183], v[118:121]
	v_mfma_f32_16x16x32_bf16 v[114:117], v[170:173], v[180:183], v[114:117]
	v_mfma_f32_16x16x32_bf16 v[102:105], v[150:153], v[192:195], v[102:105]
	v_mfma_f32_16x16x32_bf16 v[98:101], v[170:173], v[192:195], v[98:101]
	v_mfma_f32_16x16x32_bf16 v[86:89], v[150:153], v[200:203], v[86:89]
	v_mfma_f32_16x16x32_bf16 v[82:85], v[170:173], v[200:203], v[82:85]
	v_mfma_f32_16x16x32_bf16 v[70:73], v[150:153], v[208:211], v[70:73]
	v_mfma_f32_16x16x32_bf16 v[66:69], v[170:173], v[208:211], v[66:69]
	s_setprio 0
	s_barrier
; #define PG8_STAGE(bufoff, gbase, voff) do { _Pragma("unroll") for (int _i = 0; _i < 2; ++_i) \
;         __builtin_amdgcn_global_load_lds((const unsigned*)((const char*)(gbase) + (voff)[_i]), (PG8_LAS unsigned*)(lds + (bufoff) + ldsw + _i * 8192), 16, 0, 0); } while (0)
; #define PG8_WAIT_V(n) asm volatile("s_waitcnt vmcnt(" #n ")" ::: "memory")
; #define PG8_WAIT_L(n) asm volatile("s_waitcnt lgkmcnt(" #n ")" ::: "memory")
; template <class Epi, class Sched, bool ALIGN_EPI = false, bool SP2 = false>
; __device__ __forceinline__ void gemm_phase(PG8_LAS unsigned char* lds, const Gemm g, const Sched& S, const Epi& E) {
;     ...
;             PG8_LDA(At, 1, 1); PG8_STAGE(PG8_SB(1, 0), b3, voffB); PG8_STAGE(PG8_SB(1, 1), b3 + hstep, voffB); PG8_STAGE(PG8_SA(1, 0), a3, voffA);
;             PG8_WAIT_V(8); PG8_WAIT_L(0); PG8_BAR; PG8_MMA(1, 0, At, B0); PG8_MMA(1, 1, At, B1); PG8_BAR; PG8_SCHED;
;             } else {
;             PG8_LDB(B0, 0, 0); PG8_SCHED; PG8_LDA(At, 0, 0); PG8_STAGE(PG8_SA(1, 1), a1 + hstep, voffA);
;             PG8_WAIT_L(8); PG8_BAR; PG8_WAIT_L(0); PG8_MMA(0, 0, At, B0); PG8_BAR; PG8_SCHED;
;             PG8_LDB(B1, 0, 1); PG8_STAGE(PG8_SB(0, 0), b2, voffB);
;             PG8_BAR; PG8_WAIT_L(0); PG8_MMA(0, 1, At, B1); PG8_BAR;
;             PG8_LDA(At, 0, 1); PG8_STAGE(PG8_SA(0, 0), a2, voffA);
;             PG8_BAR; PG8_WAIT_L(0); PG8_MMA(1, 0, At, B0); PG8_BAR; PG8_SCHED;
;             PG8_STAGE(PG8_SB(0, 1), b2 + hstep, voffB);
;             PG8_WAIT_V(6); PG8_BAR; PG8_MMA(1, 1, At, B1); PG8_BAR;
;             PG8_LDB(B0, 1, 0); PG8_SCHED; PG8_LDA(At, 1, 0); PG8_STAGE(PG8_SA(0, 1), a2 + hstep, voffA);
;             PG8_WAIT_L(8); PG8_BAR; PG8_WAIT_L(0); PG8_MMA(0, 0, At, B0); PG8_BAR; PG8_SCHED;
;             PG8_LDB(B1, 1, 1); PG8_STAGE(PG8_SB(1, 0), b3, voffB);
;             PG8_BAR; PG8_WAIT_L(0); PG8_MMA(0, 1, At, B1); PG8_BAR;
;             PG8_LDA(At, 1, 1); PG8_STAGE(PG8_SA(1, 0), a3, voffA);
;             PG8_BAR; PG8_WAIT_L(0); PG8_MMA(1, 0, At, B0); PG8_BAR; PG8_SCHED;
;             PG8_STAGE(PG8_SB(1, 1), b3 + hstep, voffB);
;             PG8_WAIT_V(6); PG8_BAR; PG8_MMA(1, 1, At, B1); PG8_BAR;
;             }
;         }
;         if constexpr (ALIGN_EPI) { if (wr == 0) PG8_BAR; }
;         if constexpr (!Epi::AFTER_DRAIN) { E(acc, cur, wr, wc, fr, fq); S.done(cur); }
;         if (!has_next) break;
	s_add_i32 s38, s59, s33
	v_lshl_add_u64 v[212:213], v[212:213], 0, s[80:81]
	s_mov_b32 m0, s38
	ds_read_b128 v[174:177], v187 offset:49152
	ds_read_b128 v[180:183], v187 offset:50176
	ds_read_b128 v[188:191], v187 offset:51200
	ds_read_b128 v[192:195], v187 offset:52224
	ds_read_b128 v[196:199], v187 offset:53248
	ds_read_b128 v[200:203], v187 offset:54272
	ds_read_b128 v[204:207], v187 offset:55296
	ds_read_b128 v[208:211], v187 offset:56320
	global_load_lds_dwordx4 v[212:213], off
	s_add_i32 m0, s38, 0x2000
	s_add_u32 s36, s36, 0x40080
	v_lshl_add_u64 v[212:213], v[214:215], 0, s[80:81]
	s_addc_u32 s37, s37, 0
	s_add_i32 s38, s60, s33
	global_load_lds_dwordx4 v[212:213], off
	v_lshl_add_u64 v[212:213], s[36:37], 0, v[156:157]
	s_mov_b32 m0, s38
	s_nop 0
	global_load_lds_dwordx4 v[212:213], off
	v_lshl_add_u64 v[212:213], s[36:37], 0, v[160:161]
	s_add_i32 m0, s38, 0x2000
	s_nop 0
	global_load_lds_dwordx4 v[212:213], off
	v_lshl_add_u64 v[212:213], v[216:217], 0, s[80:81]
	s_mov_b32 m0, s51
	s_nop 0
	global_load_lds_dwordx4 v[212:213], off
	v_lshl_add_u64 v[212:213], v[218:219], 0, s[80:81]
	s_mov_b32 m0, s52
	s_nop 0
	global_load_lds_dwordx4 v[212:213], off
	s_waitcnt vmcnt(8)
	s_waitcnt lgkmcnt(0)
	s_barrier
	s_setprio 1
	v_mfma_f32_16x16x32_bf16 v[62:65], v[130:133], v[174:177], v[62:65]
	v_mfma_f32_16x16x32_bf16 v[58:61], v[138:141], v[174:177], v[58:61]
	v_mfma_f32_16x16x32_bf16 v[46:49], v[130:133], v[188:191], v[46:49]
	v_mfma_f32_16x16x32_bf16 v[42:45], v[138:141], v[188:191], v[42:45]
	v_mfma_f32_16x16x32_bf16 v[30:33], v[130:133], v[196:199], v[30:33]
	v_mfma_f32_16x16x32_bf16 v[26:29], v[138:141], v[196:199], v[26:29]
	v_mfma_f32_16x16x32_bf16 v[14:17], v[130:133], v[204:207], v[14:17]
	v_mfma_f32_16x16x32_bf16 v[10:13], v[138:141], v[204:207], v[10:13]
	v_mfma_f32_16x16x32_bf16 v[62:65], v[134:137], v[180:183], v[62:65]
	v_mfma_f32_16x16x32_bf16 v[58:61], v[142:145], v[180:183], v[58:61]
	v_mfma_f32_16x16x32_bf16 v[46:49], v[134:137], v[192:195], v[46:49]
	v_mfma_f32_16x16x32_bf16 v[42:45], v[142:145], v[192:195], v[42:45]
	v_mfma_f32_16x16x32_bf16 v[30:33], v[134:137], v[200:203], v[30:33]
	v_mfma_f32_16x16x32_bf16 v[26:29], v[142:145], v[200:203], v[26:29]
	v_mfma_f32_16x16x32_bf16 v[14:17], v[134:137], v[208:211], v[14:17]
	v_mfma_f32_16x16x32_bf16 v[10:13], v[142:145], v[208:211], v[10:13]
	s_setprio 0
	s_setprio 1
	v_mfma_f32_16x16x32_bf16 v[54:57], v[146:149], v[174:177], v[54:57]
	v_mfma_f32_16x16x32_bf16 v[50:53], v[166:169], v[174:177], v[50:53]
	v_mfma_f32_16x16x32_bf16 v[38:41], v[146:149], v[188:191], v[38:41]
	v_mfma_f32_16x16x32_bf16 v[34:37], v[166:169], v[188:191], v[34:37]
	v_mfma_f32_16x16x32_bf16 v[22:25], v[146:149], v[196:199], v[22:25]
	v_mfma_f32_16x16x32_bf16 v[18:21], v[166:169], v[196:199], v[18:21]
	v_mfma_f32_16x16x32_bf16 v[6:9], v[146:149], v[204:207], v[6:9]
	v_mfma_f32_16x16x32_bf16 v[2:5], v[166:169], v[204:207], v[2:5]
	v_mfma_f32_16x16x32_bf16 v[54:57], v[150:153], v[180:183], v[54:57]
	v_mfma_f32_16x16x32_bf16 v[50:53], v[170:173], v[180:183], v[50:53]
	v_mfma_f32_16x16x32_bf16 v[38:41], v[150:153], v[192:195], v[38:41]
	v_mfma_f32_16x16x32_bf16 v[34:37], v[170:173], v[192:195], v[34:37]
	v_mfma_f32_16x16x32_bf16 v[22:25], v[150:153], v[200:203], v[22:25]
	v_mfma_f32_16x16x32_bf16 v[18:21], v[170:173], v[200:203], v[18:21]
	v_mfma_f32_16x16x32_bf16 v[6:9], v[150:153], v[208:211], v[6:9]
	v_mfma_f32_16x16x32_bf16 v[2:5], v[170:173], v[208:211], v[2:5]
	s_setprio 0
	s_barrier
	s_add_i32 s58, s58, 2
	s_add_u32 s34, s34, 0x100
	s_addc_u32 s35, s35, 0
	s_add_u32 s56, s56, 0x100
	s_addc_u32 s57, s57, 0
	s_cmp_gt_u32 s58, 13
	s_cbranch_scc0 .LBB0_1062
	s_and_b64 vcc, exec, s[18:19]
	s_cbranch_vccz .LBB0_1065
	s_barrier

; #define PG8_STAGE(bufoff, gbase, voff) do { _Pragma("unroll") for (int _i = 0; _i < 2; ++_i) \
;         __builtin_amdgcn_global_load_lds((const unsigned*)((const char*)(gbase) + (voff)[_i]), (PG8_LAS unsigned*)(lds + (bufoff) + ldsw + _i * 8192), 16, 0, 0); } while (0)
; #define PG8_LDA(dst, b, h) do { _Pragma("unroll") for (int m = 0; m < 4; ++m) _Pragma("unroll") for (int k = 0; k < 2; ++k) dst[m][k] = *(const PG8_LAS bf16x8*)(lds + PG8_SA(b, h) + aoff + m * 2048 + k * 1024); } while (0)
; #define PG8_LDB(dst, b, h) do { _Pragma("unroll") for (int n = 0; n < 2; ++n) _Pragma("unroll") for (int k = 0; k < 2; ++k) dst[n][k] = *(const PG8_LAS bf16x8*)(lds + PG8_SB(b, h) + boff + n * 2048 + k * 1024); } while (0)
; #define PG8_MMA(ai, bj, At, Bt) do { __builtin_amdgcn_s_setprio(1); _Pragma("unroll") for (int m = 0; m < 4; ++m) _Pragma("unroll") for (int n = 0; n < 2; ++n) _Pragma("unroll") for (int k = 0; k < 2; ++k) \
;         acc[ai][bj][m][n] = __builtin_amdgcn_mfma_f32_16x16x32_bf16(Bt[n][k], At[m][k], acc[ai][bj][m][n], 0, 0, 0); __builtin_amdgcn_s_setprio(0); } while (0)
; #define PG8_WAIT_V(n) asm volatile("s_waitcnt vmcnt(" #n ")" ::: "memory")
; #define PG8_BAR __builtin_amdgcn_s_barrier()
; template <class Epi, class Sched, bool ALIGN_EPI = false, bool SP2 = false>
; __device__ __forceinline__ void gemm_phase(PG8_LAS unsigned char* lds, const Gemm g, const Sched& S, const Epi& E) {
;     ...
;         for (int t = 0; t < nt; t += 2) {
;             const bool last = (t == nt - 2);
;             const char* a1 = cA + (size_t)(t + 1) * kstep;
;             const char* a2 = last ? nA : cA + (size_t)(t + 2) * kstep; const char* b2 = last ? nB : cB + (size_t)(t + 2) * kstep;
;             const char* a3 = a2 + kstep; const char* b3 = b2 + kstep;
;             if (last && has_next) S.a_ready(nxt);
;             if constexpr (SP2) {
;             PG8_LDB(B0, 0, 0); PG8_LDB(B1, 0, 1); PG8_SCHED; PG8_LDA(At, 0, 0); PG8_STAGE(PG8_SA(1, 1), a1 + hstep, voffA);
;             PG8_WAIT_V(8); PG8_WAIT_L(0); PG8_BAR; PG8_MMA(0, 0, At, B0); PG8_MMA(0, 1, At, B1); PG8_BAR; PG8_SCHED;
;             PG8_LDA(At, 0, 1); PG8_STAGE(PG8_SB(0, 0), b2, voffB); PG8_STAGE(PG8_SB(0, 1), b2 + hstep, voffB); PG8_STAGE(PG8_SA(0, 0), a2, voffA);
;             PG8_WAIT_V(8); PG8_WAIT_L(0); PG8_BAR; PG8_MMA(1, 0, At, B0); PG8_MMA(1, 1, At, B1); PG8_BAR; PG8_SCHED;
.LBB0_1106:
	s_add_u32 s30, s28, 0xfffc0080
	s_addc_u32 s31, s29, -1
	s_add_i32 s55, 0, 0x10000
	s_cmp_eq_u32 s54, 12
	s_cselect_b32 s35, s19, s31
	s_cselect_b32 s34, s25, s30
	s_cselect_b32 s31, s17, s53
	s_cselect_b32 s30, s27, s52
	s_add_i32 s58, 0, 0x14000
	v_add_u32_e32 v142, s55, v179
	v_add_u32_e32 v158, s58, v179
	ds_read_b128 v[130:133], v142
	ds_read_b128 v[134:137], v142 offset:1024
	ds_read_b128 v[138:141], v142 offset:2048
	ds_read_b128 v[142:145], v142 offset:3072
	ds_read_b128 v[146:149], v158
	ds_read_b128 v[150:153], v158 offset:1024
	ds_read_b128 v[154:157], v158 offset:2048
	ds_read_b128 v[158:161], v158 offset:3072
	v_lshl_add_u64 v[212:213], s[28:29], 0, v[194:195]
	s_add_i32 m0, s36, 0xc000
	ds_read_b128 v[162:165], v211
	ds_read_b128 v[166:169], v211 offset:1024
	ds_read_b128 v[170:173], v211 offset:2048
	ds_read_b128 v[174:177], v211 offset:3072
	ds_read_b128 v[180:183], v211 offset:4096
	ds_read_b128 v[198:201], v211 offset:5120
	ds_read_b128 v[202:205], v211 offset:6144
	ds_read_b128 v[206:209], v211 offset:7168
	global_load_lds_dwordx4 v[212:213], off
	v_lshl_add_u64 v[212:213], s[28:29], 0, v[196:197]
	s_add_i32 m0, s36, 0xe000
	s_nop 0
	global_load_lds_dwordx4 v[212:213], off
	s_waitcnt vmcnt(8)
	s_waitcnt lgkmcnt(0)
	s_barrier
	s_setprio 1
	v_mfma_f32_16x16x32_bf16 v[126:129], v[130:133], v[162:165], v[126:129]
	v_mfma_f32_16x16x32_bf16 v[122:125], v[138:141], v[162:165], v[122:125]
	v_mfma_f32_16x16x32_bf16 v[110:113], v[130:133], v[170:173], v[110:113]
	v_mfma_f32_16x16x32_bf16 v[106:109], v[138:141], v[170:173], v[106:109]
	v_mfma_f32_16x16x32_bf16 v[94:97], v[130:133], v[180:183], v[94:97]
	v_mfma_f32_16x16x32_bf16 v[90:93], v[138:141], v[180:183], v[90:93]
	v_mfma_f32_16x16x32_bf16 v[78:81], v[130:133], v[202:205], v[78:81]
	v_mfma_f32_16x16x32_bf16 v[74:77], v[138:141], v[202:205], v[74:77]
	v_mfma_f32_16x16x32_bf16 v[126:129], v[134:137], v[166:169], v[126:129]
	v_mfma_f32_16x16x32_bf16 v[122:125], v[142:145], v[166:169], v[122:125]
	v_mfma_f32_16x16x32_bf16 v[110:113], v[134:137], v[174:177], v[110:113]
	v_mfma_f32_16x16x32_bf16 v[106:109], v[142:145], v[174:177], v[106:109]
	v_mfma_f32_16x16x32_bf16 v[94:97], v[134:137], v[198:201], v[94:97]
	v_mfma_f32_16x16x32_bf16 v[90:93], v[142:145], v[198:201], v[90:93]
	v_mfma_f32_16x16x32_bf16 v[78:81], v[134:137], v[206:209], v[78:81]
	v_mfma_f32_16x16x32_bf16 v[74:77], v[142:145], v[206:209], v[74:77]
	s_setprio 0
	s_setprio 1
	v_mfma_f32_16x16x32_bf16 v[118:121], v[146:149], v[162:165], v[118:121]
	v_mfma_f32_16x16x32_bf16 v[114:117], v[154:157], v[162:165], v[114:117]
	v_mfma_f32_16x16x32_bf16 v[102:105], v[146:149], v[170:173], v[102:105]
	v_mfma_f32_16x16x32_bf16 v[98:101], v[154:157], v[170:173], v[98:101]
	v_mfma_f32_16x16x32_bf16 v[86:89], v[146:149], v[180:183], v[86:89]
	v_mfma_f32_16x16x32_bf16 v[82:85], v[154:157], v[180:183], v[82:85]
	v_mfma_f32_16x16x32_bf16 v[70:73], v[146:149], v[202:205], v[70:73]
	v_mfma_f32_16x16x32_bf16 v[66:69], v[154:157], v[202:205], v[66:69]
	v_mfma_f32_16x16x32_bf16 v[118:121], v[150:153], v[166:169], v[118:121]
	v_mfma_f32_16x16x32_bf16 v[114:117], v[158:161], v[166:169], v[114:117]
	v_mfma_f32_16x16x32_bf16 v[102:105], v[150:153], v[174:177], v[102:105]
	v_mfma_f32_16x16x32_bf16 v[98:101], v[158:161], v[174:177], v[98:101]
	v_mfma_f32_16x16x32_bf16 v[86:89], v[150:153], v[198:201], v[86:89]
	v_mfma_f32_16x16x32_bf16 v[82:85], v[158:161], v[198:201], v[82:85]
	v_mfma_f32_16x16x32_bf16 v[70:73], v[150:153], v[206:209], v[70:73]
	v_mfma_f32_16x16x32_bf16 v[66:69], v[158:161], v[206:209], v[66:69]
	s_setprio 0
	s_barrier
	s_add_i32 s55, s55, s33
	v_lshl_add_u64 v[212:213], s[30:31], 0, v[188:189]
	s_mov_b32 m0, s55
	ds_read_b128 v[162:165], v211 offset:16384
	ds_read_b128 v[166:169], v211 offset:17408
	ds_read_b128 v[170:173], v211 offset:18432
	ds_read_b128 v[174:177], v211 offset:19456
	ds_read_b128 v[180:183], v211 offset:20480
	ds_read_b128 v[198:201], v211 offset:21504
	ds_read_b128 v[202:205], v211 offset:22528
	ds_read_b128 v[206:209], v211 offset:23552
	global_load_lds_dwordx4 v[212:213], off
	s_add_i32 m0, s55, 0x2000
	s_add_u32 s56, s30, 0x40000
	v_lshl_add_u64 v[214:215], s[30:31], 0, v[192:193]
	s_addc_u32 s57, s31, 0
	s_add_i32 s55, s58, s33
	global_load_lds_dwordx4 v[214:215], off
	v_lshl_add_u64 v[216:217], s[56:57], 0, v[188:189]
	s_mov_b32 m0, s55
	v_lshl_add_u64 v[218:219], s[34:35], 0, v[190:191]
	global_load_lds_dwordx4 v[216:217], off
	v_lshl_add_u64 v[216:217], s[56:57], 0, v[192:193]
	s_add_i32 m0, s55, 0x2000
	s_nop 0
	global_load_lds_dwordx4 v[216:217], off
	v_lshl_add_u64 v[216:217], s[34:35], 0, v[186:187]
	s_mov_b32 m0, s36
	s_nop 0
	global_load_lds_dwordx4 v[216:217], off
	s_mov_b32 m0, s37
	s_nop 0
	global_load_lds_dwordx4 v[218:219], off
	s_waitcnt vmcnt(8)
	s_waitcnt lgkmcnt(0)
	s_barrier
; #define PG8_STAGE(bufoff, gbase, voff) do { _Pragma("unroll") for (int _i = 0; _i < 2; ++_i) \
;         __builtin_amdgcn_global_load_lds((const unsigned*)((const char*)(gbase) + (voff)[_i]), (PG8_LAS unsigned*)(lds + (bufoff) + ldsw + _i * 8192), 16, 0, 0); } while (0)
; #define PG8_LDA(dst, b, h) do { _Pragma("unroll") for (int m = 0; m < 4; ++m) _Pragma("unroll") for (int k = 0; k < 2; ++k) dst[m][k] = *(const PG8_LAS bf16x8*)(lds + PG8_SA(b, h) + aoff + m * 2048 + k * 1024); } while (0)
; #define PG8_LDB(dst, b, h) do { _Pragma("unroll") for (int n = 0; n < 2; ++n) _Pragma("unroll") for (int k = 0; k < 2; ++k) dst[n][k] = *(const PG8_LAS bf16x8*)(lds + PG8_SB(b, h) + boff + n * 2048 + k * 1024); } while (0)
; #define PG8_MMA(ai, bj, At, Bt) do { __builtin_amdgcn_s_setprio(1); _Pragma("unroll") for (int m = 0; m < 4; ++m) _Pragma("unroll") for (int n = 0; n < 2; ++n) _Pragma("unroll") for (int k = 0; k < 2; ++k) \
;         acc[ai][bj][m][n] = __builtin_amdgcn_mfma_f32_16x16x32_bf16(Bt[n][k], At[m][k], acc[ai][bj][m][n], 0, 0, 0); __builtin_amdgcn_s_setprio(0); } while (0)
; #define PG8_WAIT_V(n) asm volatile("s_waitcnt vmcnt(" #n ")" ::: "memory")
; #define PG8_WAIT_L(n) asm volatile("s_waitcnt lgkmcnt(" #n ")" ::: "memory")
; #define PG8_BAR __builtin_amdgcn_s_barrier()
; #define PG8_SCHED __builtin_amdgcn_sched_barrier(0)
; template <class Epi, class Sched, bool ALIGN_EPI = false, bool SP2 = false>
; __device__ __forceinline__ void gemm_phase(PG8_LAS unsigned char* lds, const Gemm g, const Sched& S, const Epi& E) {
;     ...
;             PG8_WAIT_V(8); PG8_WAIT_L(0); PG8_BAR; PG8_MMA(1, 0, At, B0); PG8_MMA(1, 1, At, B1); PG8_BAR; PG8_SCHED;
;             PG8_LDB(B0, 1, 0); PG8_LDB(B1, 1, 1); PG8_SCHED; PG8_LDA(At, 1, 0); PG8_STAGE(PG8_SA(0, 1), a2 + hstep, voffA);
;             PG8_WAIT_V(8); PG8_WAIT_L(0); PG8_BAR; PG8_MMA(0, 0, At, B0); PG8_MMA(0, 1, At, B1); PG8_BAR; PG8_SCHED;
	s_setprio 1
	v_mfma_f32_16x16x32_bf16 v[62:65], v[130:133], v[162:165], v[62:65]
	v_mfma_f32_16x16x32_bf16 v[58:61], v[138:141], v[162:165], v[58:61]
	v_mfma_f32_16x16x32_bf16 v[46:49], v[130:133], v[170:173], v[46:49]
	v_mfma_f32_16x16x32_bf16 v[42:45], v[138:141], v[170:173], v[42:45]
	v_mfma_f32_16x16x32_bf16 v[30:33], v[130:133], v[180:183], v[30:33]
	v_mfma_f32_16x16x32_bf16 v[26:29], v[138:141], v[180:183], v[26:29]
	v_mfma_f32_16x16x32_bf16 v[14:17], v[130:133], v[202:205], v[14:17]
	v_mfma_f32_16x16x32_bf16 v[10:13], v[138:141], v[202:205], v[10:13]
	v_mfma_f32_16x16x32_bf16 v[62:65], v[134:137], v[166:169], v[62:65]
	v_mfma_f32_16x16x32_bf16 v[58:61], v[142:145], v[166:169], v[58:61]
	v_mfma_f32_16x16x32_bf16 v[46:49], v[134:137], v[174:177], v[46:49]
	v_mfma_f32_16x16x32_bf16 v[42:45], v[142:145], v[174:177], v[42:45]
	v_mfma_f32_16x16x32_bf16 v[30:33], v[134:137], v[198:201], v[30:33]
	v_mfma_f32_16x16x32_bf16 v[26:29], v[142:145], v[198:201], v[26:29]
	v_mfma_f32_16x16x32_bf16 v[14:17], v[134:137], v[206:209], v[14:17]
	v_mfma_f32_16x16x32_bf16 v[10:13], v[142:145], v[206:209], v[10:13]
	s_setprio 0
	s_setprio 1
	v_mfma_f32_16x16x32_bf16 v[54:57], v[146:149], v[162:165], v[54:57]
	v_mfma_f32_16x16x32_bf16 v[50:53], v[154:157], v[162:165], v[50:53]
	v_mfma_f32_16x16x32_bf16 v[38:41], v[146:149], v[170:173], v[38:41]
	v_mfma_f32_16x16x32_bf16 v[34:37], v[154:157], v[170:173], v[34:37]
	v_mfma_f32_16x16x32_bf16 v[22:25], v[146:149], v[180:183], v[22:25]
	v_mfma_f32_16x16x32_bf16 v[18:21], v[154:157], v[180:183], v[18:21]
	v_mfma_f32_16x16x32_bf16 v[6:9], v[146:149], v[202:205], v[6:9]
	v_mfma_f32_16x16x32_bf16 v[2:5], v[154:157], v[202:205], v[2:5]
	v_mfma_f32_16x16x32_bf16 v[54:57], v[150:153], v[166:169], v[54:57]
	v_mfma_f32_16x16x32_bf16 v[50:53], v[158:161], v[166:169], v[50:53]
	v_mfma_f32_16x16x32_bf16 v[38:41], v[150:153], v[174:177], v[38:41]
	v_mfma_f32_16x16x32_bf16 v[34:37], v[158:161], v[174:177], v[34:37]
	v_mfma_f32_16x16x32_bf16 v[22:25], v[150:153], v[198:201], v[22:25]
	v_mfma_f32_16x16x32_bf16 v[18:21], v[158:161], v[198:201], v[18:21]
	v_mfma_f32_16x16x32_bf16 v[6:9], v[150:153], v[206:209], v[6:9]
	v_mfma_f32_16x16x32_bf16 v[2:5], v[158:161], v[206:209], v[2:5]
	s_setprio 0
	s_barrier
	s_add_i32 s55, 0, 0x18000
	s_add_i32 s56, 0, 0x1c000
	v_add_u32_e32 v142, s55, v179
	v_add_u32_e32 v158, s56, v179
	ds_read_b128 v[130:133], v142
	ds_read_b128 v[134:137], v142 offset:1024
	ds_read_b128 v[138:141], v142 offset:2048
	ds_read_b128 v[142:145], v142 offset:3072
	ds_read_b128 v[146:149], v158
	ds_read_b128 v[150:153], v158 offset:1024
	ds_read_b128 v[154:157], v158 offset:2048
	ds_read_b128 v[158:161], v158 offset:3072
	s_add_u32 s34, s34, 0x40000
	s_addc_u32 s35, s35, 0
	s_mov_b32 m0, s38
	v_lshl_add_u64 v[220:221], s[34:35], 0, v[186:187]
	ds_read_b128 v[162:165], v211 offset:32768
	ds_read_b128 v[166:169], v211 offset:33792
	ds_read_b128 v[170:173], v211 offset:34816
	ds_read_b128 v[174:177], v211 offset:35840
	ds_read_b128 v[180:183], v211 offset:36864
	ds_read_b128 v[198:201], v211 offset:37888
	ds_read_b128 v[202:205], v211 offset:38912
	ds_read_b128 v[206:209], v211 offset:39936
	global_load_lds_dwordx4 v[220:221], off
	v_lshl_add_u64 v[220:221], s[34:35], 0, v[190:191]
	s_mov_b32 m0, s39
	s_nop 0
	global_load_lds_dwordx4 v[220:221], off
	s_waitcnt vmcnt(8)
	s_waitcnt lgkmcnt(0)
	s_barrier
	s_setprio 1
	v_mfma_f32_16x16x32_bf16 v[126:129], v[130:133], v[162:165], v[126:129]
	v_mfma_f32_16x16x32_bf16 v[122:125], v[138:141], v[162:165], v[122:125]
	v_mfma_f32_16x16x32_bf16 v[110:113], v[130:133], v[170:173], v[110:113]
	v_mfma_f32_16x16x32_bf16 v[106:109], v[138:141], v[170:173], v[106:109]
	v_mfma_f32_16x16x32_bf16 v[94:97], v[130:133], v[180:183], v[94:97]
	v_mfma_f32_16x16x32_bf16 v[90:93], v[138:141], v[180:183], v[90:93]
	v_mfma_f32_16x16x32_bf16 v[78:81], v[130:133], v[202:205], v[78:81]
	v_mfma_f32_16x16x32_bf16 v[74:77], v[138:141], v[202:205], v[74:77]
	v_mfma_f32_16x16x32_bf16 v[126:129], v[134:137], v[166:169], v[126:129]
	v_mfma_f32_16x16x32_bf16 v[122:125], v[142:145], v[166:169], v[122:125]
	v_mfma_f32_16x16x32_bf16 v[110:113], v[134:137], v[174:177], v[110:113]
	v_mfma_f32_16x16x32_bf16 v[106:109], v[142:145], v[174:177], v[106:109]
	v_mfma_f32_16x16x32_bf16 v[94:97], v[134:137], v[198:201], v[94:97]
	v_mfma_f32_16x16x32_bf16 v[90:93], v[142:145], v[198:201], v[90:93]
	v_mfma_f32_16x16x32_bf16 v[78:81], v[134:137], v[206:209], v[78:81]
	v_mfma_f32_16x16x32_bf16 v[74:77], v[142:145], v[206:209], v[74:77]
	s_setprio 0
	s_setprio 1
	v_mfma_f32_16x16x32_bf16 v[118:121], v[146:149], v[162:165], v[118:121]
	v_mfma_f32_16x16x32_bf16 v[114:117], v[154:157], v[162:165], v[114:117]
	v_mfma_f32_16x16x32_bf16 v[102:105], v[146:149], v[170:173], v[102:105]
	v_mfma_f32_16x16x32_bf16 v[98:101], v[154:157], v[170:173], v[98:101]
	v_mfma_f32_16x16x32_bf16 v[86:89], v[146:149], v[180:183], v[86:89]
	v_mfma_f32_16x16x32_bf16 v[82:85], v[154:157], v[180:183], v[82:85]
	v_mfma_f32_16x16x32_bf16 v[70:73], v[146:149], v[202:205], v[70:73]
	v_mfma_f32_16x16x32_bf16 v[66:69], v[154:157], v[202:205], v[66:69]
	v_mfma_f32_16x16x32_bf16 v[118:121], v[150:153], v[166:169], v[118:121]
	v_mfma_f32_16x16x32_bf16 v[114:117], v[158:161], v[166:169], v[114:117]
	v_mfma_f32_16x16x32_bf16 v[102:105], v[150:153], v[174:177], v[102:105]
	v_mfma_f32_16x16x32_bf16 v[98:101], v[158:161], v[174:177], v[98:101]
	v_mfma_f32_16x16x32_bf16 v[86:89], v[150:153], v[198:201], v[86:89]
	v_mfma_f32_16x16x32_bf16 v[82:85], v[158:161], v[198:201], v[82:85]
	v_mfma_f32_16x16x32_bf16 v[70:73], v[150:153], v[206:209], v[70:73]
	v_mfma_f32_16x16x32_bf16 v[66:69], v[158:161], v[206:209], v[66:69]
	s_setprio 0
	s_barrier
; #define PG8_STAGE(bufoff, gbase, voff) do { _Pragma("unroll") for (int _i = 0; _i < 2; ++_i) \
;         __builtin_amdgcn_global_load_lds((const unsigned*)((const char*)(gbase) + (voff)[_i]), (PG8_LAS unsigned*)(lds + (bufoff) + ldsw + _i * 8192), 16, 0, 0); } while (0)
; #define PG8_WAIT_V(n) asm volatile("s_waitcnt vmcnt(" #n ")" ::: "memory")
; #define PG8_WAIT_L(n) asm volatile("s_waitcnt lgkmcnt(" #n ")" ::: "memory")
; template <class Epi, class Sched, bool ALIGN_EPI = false, bool SP2 = false>
; __device__ __forceinline__ void gemm_phase(PG8_LAS unsigned char* lds, const Gemm g, const Sched& S, const Epi& E) {
;     ...
;             PG8_LDA(At, 1, 1); PG8_STAGE(PG8_SB(1, 0), b3, voffB); PG8_STAGE(PG8_SB(1, 1), b3 + hstep, voffB); PG8_STAGE(PG8_SA(1, 0), a3, voffA);
;             PG8_WAIT_V(8); PG8_WAIT_L(0); PG8_BAR; PG8_MMA(1, 0, At, B0); PG8_MMA(1, 1, At, B1); PG8_BAR; PG8_SCHED;
;             } else {
;             PG8_LDB(B0, 0, 0); PG8_SCHED; PG8_LDA(At, 0, 0); PG8_STAGE(PG8_SA(1, 1), a1 + hstep, voffA);
;             PG8_WAIT_L(8); PG8_BAR; PG8_WAIT_L(0); PG8_MMA(0, 0, At, B0); PG8_BAR; PG8_SCHED;
;             PG8_LDB(B1, 0, 1); PG8_STAGE(PG8_SB(0, 0), b2, voffB);
;             PG8_BAR; PG8_WAIT_L(0); PG8_MMA(0, 1, At, B1); PG8_BAR;
;             PG8_LDA(At, 0, 1); PG8_STAGE(PG8_SA(0, 0), a2, voffA);
;             PG8_BAR; PG8_WAIT_L(0); PG8_MMA(1, 0, At, B0); PG8_BAR; PG8_SCHED;
;             PG8_STAGE(PG8_SB(0, 1), b2 + hstep, voffB);
;             PG8_WAIT_V(6); PG8_BAR; PG8_MMA(1, 1, At, B1); PG8_BAR;
;             PG8_LDB(B0, 1, 0); PG8_SCHED; PG8_LDA(At, 1, 0); PG8_STAGE(PG8_SA(0, 1), a2 + hstep, voffA);
;             PG8_WAIT_L(8); PG8_BAR; PG8_WAIT_L(0); PG8_MMA(0, 0, At, B0); PG8_BAR; PG8_SCHED;
;             PG8_LDB(B1, 1, 1); PG8_STAGE(PG8_SB(1, 0), b3, voffB);
;             PG8_BAR; PG8_WAIT_L(0); PG8_MMA(0, 1, At, B1); PG8_BAR;
;             PG8_LDA(At, 1, 1); PG8_STAGE(PG8_SA(1, 0), a3, voffA);
;             PG8_BAR; PG8_WAIT_L(0); PG8_MMA(1, 0, At, B0); PG8_BAR; PG8_SCHED;
;             PG8_STAGE(PG8_SB(1, 1), b3 + hstep, voffB);
;             PG8_WAIT_V(6); PG8_BAR; PG8_MMA(1, 1, At, B1); PG8_BAR;
;             }
;         }
;         if constexpr (ALIGN_EPI) { if (wr == 0) PG8_BAR; }
;         if constexpr (!Epi::AFTER_DRAIN) { E(acc, cur, wr, wc, fr, fq); S.done(cur); }
;         if (!has_next) break;
	s_add_i32 s34, s55, s33
	v_lshl_add_u64 v[212:213], v[212:213], 0, s[80:81]
	s_mov_b32 m0, s34
	ds_read_b128 v[162:165], v211 offset:49152
	ds_read_b128 v[166:169], v211 offset:50176
	ds_read_b128 v[170:173], v211 offset:51200
	ds_read_b128 v[174:177], v211 offset:52224
	ds_read_b128 v[180:183], v211 offset:53248
	ds_read_b128 v[198:201], v211 offset:54272
	ds_read_b128 v[202:205], v211 offset:55296
	ds_read_b128 v[206:209], v211 offset:56320
	global_load_lds_dwordx4 v[212:213], off
	s_add_i32 m0, s34, 0x2000
	s_add_u32 s30, s30, 0x40080
	v_lshl_add_u64 v[212:213], v[214:215], 0, s[80:81]
	s_addc_u32 s31, s31, 0
	s_add_i32 s34, s56, s33
	global_load_lds_dwordx4 v[212:213], off
	v_lshl_add_u64 v[212:213], s[30:31], 0, v[188:189]
	s_mov_b32 m0, s34
	s_nop 0
	global_load_lds_dwordx4 v[212:213], off
	v_lshl_add_u64 v[212:213], s[30:31], 0, v[192:193]
	s_add_i32 m0, s34, 0x2000
	s_nop 0
	global_load_lds_dwordx4 v[212:213], off
	v_lshl_add_u64 v[212:213], v[216:217], 0, s[80:81]
	s_mov_b32 m0, s47
	s_nop 0
	global_load_lds_dwordx4 v[212:213], off
	v_lshl_add_u64 v[212:213], v[218:219], 0, s[80:81]
	s_mov_b32 m0, s48
	s_nop 0
	global_load_lds_dwordx4 v[212:213], off
	s_waitcnt vmcnt(8)
	s_waitcnt lgkmcnt(0)
	s_barrier
	s_setprio 1
	v_mfma_f32_16x16x32_bf16 v[62:65], v[130:133], v[162:165], v[62:65]
	v_mfma_f32_16x16x32_bf16 v[58:61], v[138:141], v[162:165], v[58:61]
	v_mfma_f32_16x16x32_bf16 v[46:49], v[130:133], v[170:173], v[46:49]
	v_mfma_f32_16x16x32_bf16 v[42:45], v[138:141], v[170:173], v[42:45]
	v_mfma_f32_16x16x32_bf16 v[30:33], v[130:133], v[180:183], v[30:33]
	v_mfma_f32_16x16x32_bf16 v[26:29], v[138:141], v[180:183], v[26:29]
	v_mfma_f32_16x16x32_bf16 v[14:17], v[130:133], v[202:205], v[14:17]
	v_mfma_f32_16x16x32_bf16 v[10:13], v[138:141], v[202:205], v[10:13]
	v_mfma_f32_16x16x32_bf16 v[62:65], v[134:137], v[166:169], v[62:65]
	v_mfma_f32_16x16x32_bf16 v[58:61], v[142:145], v[166:169], v[58:61]
	v_mfma_f32_16x16x32_bf16 v[46:49], v[134:137], v[174:177], v[46:49]
	v_mfma_f32_16x16x32_bf16 v[42:45], v[142:145], v[174:177], v[42:45]
	v_mfma_f32_16x16x32_bf16 v[30:33], v[134:137], v[198:201], v[30:33]
	v_mfma_f32_16x16x32_bf16 v[26:29], v[142:145], v[198:201], v[26:29]
	v_mfma_f32_16x16x32_bf16 v[14:17], v[134:137], v[206:209], v[14:17]
	v_mfma_f32_16x16x32_bf16 v[10:13], v[142:145], v[206:209], v[10:13]
	s_setprio 0
	s_setprio 1
	v_mfma_f32_16x16x32_bf16 v[54:57], v[146:149], v[162:165], v[54:57]
	v_mfma_f32_16x16x32_bf16 v[50:53], v[154:157], v[162:165], v[50:53]
	v_mfma_f32_16x16x32_bf16 v[38:41], v[146:149], v[170:173], v[38:41]
	v_mfma_f32_16x16x32_bf16 v[34:37], v[154:157], v[170:173], v[34:37]
	v_mfma_f32_16x16x32_bf16 v[22:25], v[146:149], v[180:183], v[22:25]
	v_mfma_f32_16x16x32_bf16 v[18:21], v[154:157], v[180:183], v[18:21]
	v_mfma_f32_16x16x32_bf16 v[6:9], v[146:149], v[202:205], v[6:9]
	v_mfma_f32_16x16x32_bf16 v[2:5], v[154:157], v[202:205], v[2:5]
	v_mfma_f32_16x16x32_bf16 v[54:57], v[150:153], v[166:169], v[54:57]
	v_mfma_f32_16x16x32_bf16 v[50:53], v[158:161], v[166:169], v[50:53]
	v_mfma_f32_16x16x32_bf16 v[38:41], v[150:153], v[174:177], v[38:41]
	v_mfma_f32_16x16x32_bf16 v[34:37], v[158:161], v[174:177], v[34:37]
	v_mfma_f32_16x16x32_bf16 v[22:25], v[150:153], v[198:201], v[22:25]
	v_mfma_f32_16x16x32_bf16 v[18:21], v[158:161], v[198:201], v[18:21]
	v_mfma_f32_16x16x32_bf16 v[6:9], v[150:153], v[206:209], v[6:9]
	v_mfma_f32_16x16x32_bf16 v[2:5], v[158:161], v[206:209], v[2:5]
	s_setprio 0
	s_barrier
	s_add_i32 s54, s54, 2
	s_add_u32 s28, s28, 0x100
	s_addc_u32 s29, s29, 0
	s_add_u32 s52, s52, 0x100
	s_addc_u32 s53, s53, 0
	s_cmp_gt_u32 s54, 13
	s_cbranch_scc0 .LBB0_1106
	s_and_b64 vcc, exec, s[14:15]
	s_cbranch_vccz .LBB0_1109
	s_barrier

; #define PG8_STAGE(bufoff, gbase, voff) do { _Pragma("unroll") for (int _i = 0; _i < 2; ++_i) \
;         __builtin_amdgcn_global_load_lds((const unsigned*)((const char*)(gbase) + (voff)[_i]), (PG8_LAS unsigned*)(lds + (bufoff) + ldsw + _i * 8192), 16, 0, 0); } while (0)
; #define PG8_LDA(dst, b, h) do { _Pragma("unroll") for (int m = 0; m < 4; ++m) _Pragma("unroll") for (int k = 0; k < 2; ++k) dst[m][k] = *(const PG8_LAS bf16x8*)(lds + PG8_SA(b, h) + aoff + m * 2048 + k * 1024); } while (0)
; #define PG8_LDB(dst, b, h) do { _Pragma("unroll") for (int n = 0; n < 2; ++n) _Pragma("unroll") for (int k = 0; k < 2; ++k) dst[n][k] = *(const PG8_LAS bf16x8*)(lds + PG8_SB(b, h) + boff + n * 2048 + k * 1024); } while (0)
; #define PG8_MMA(ai, bj, At, Bt) do { __builtin_amdgcn_s_setprio(1); _Pragma("unroll") for (int m = 0; m < 4; ++m) _Pragma("unroll") for (int n = 0; n < 2; ++n) _Pragma("unroll") for (int k = 0; k < 2; ++k) \
;         acc[ai][bj][m][n] = __builtin_amdgcn_mfma_f32_16x16x32_bf16(Bt[n][k], At[m][k], acc[ai][bj][m][n], 0, 0, 0); __builtin_amdgcn_s_setprio(0); } while (0)
; #define PG8_WAIT_V(n) asm volatile("s_waitcnt vmcnt(" #n ")" ::: "memory")
; #define PG8_BAR __builtin_amdgcn_s_barrier()
; template <class Epi, class Sched, bool ALIGN_EPI = false, bool SP2 = false>
; __device__ __forceinline__ void gemm_phase(PG8_LAS unsigned char* lds, const Gemm g, const Sched& S, const Epi& E) {
;     ...
;         for (int t = 0; t < nt; t += 2) {
;             const bool last = (t == nt - 2);
;             const char* a1 = cA + (size_t)(t + 1) * kstep;
;             const char* a2 = last ? nA : cA + (size_t)(t + 2) * kstep; const char* b2 = last ? nB : cB + (size_t)(t + 2) * kstep;
;             const char* a3 = a2 + kstep; const char* b3 = b2 + kstep;
;             if (last && has_next) S.a_ready(nxt);
;             if constexpr (SP2) {
;             PG8_LDB(B0, 0, 0); PG8_LDB(B1, 0, 1); PG8_SCHED; PG8_LDA(At, 0, 0); PG8_STAGE(PG8_SA(1, 1), a1 + hstep, voffA);
;             PG8_WAIT_V(8); PG8_WAIT_L(0); PG8_BAR; PG8_MMA(0, 0, At, B0); PG8_MMA(0, 1, At, B1); PG8_BAR; PG8_SCHED;
;             PG8_LDA(At, 0, 1); PG8_STAGE(PG8_SB(0, 0), b2, voffB); PG8_STAGE(PG8_SB(0, 1), b2 + hstep, voffB); PG8_STAGE(PG8_SA(0, 0), a2, voffA);
;             PG8_WAIT_V(8); PG8_WAIT_L(0); PG8_BAR; PG8_MMA(1, 0, At, B0); PG8_MMA(1, 1, At, B1); PG8_BAR; PG8_SCHED;
.LBB0_1249:
	s_add_u32 s26, s24, 0xfffc0080
	s_addc_u32 s27, s25, -1
	s_add_i32 s50, 0, 0x10000
	s_cmp_eq_u32 s49, 12
	s_cselect_b32 s29, s17, s27
	s_cselect_b32 s28, s45, s26
	v_add_u32_e32 v156, s50, v158
	s_cselect_b32 s27, s15, s48
	s_cselect_b32 s26, s46, s47
	s_add_i32 s52, 0, 0x14000
	ds_read_b128 v[66:69], v156
	ds_read_b128 v[118:121], v156 offset:1024
	ds_read_b128 v[152:155], v156 offset:2048
	ds_read_b128 v[162:165], v156 offset:3072
	v_add_u32_e32 v156, s52, v158
	ds_read_b128 v[166:169], v156
	ds_read_b128 v[170:173], v156 offset:1024
	ds_read_b128 v[174:177], v156 offset:2048
	ds_read_b128 v[180:183], v156 offset:3072
	v_lshl_add_u64 v[156:157], s[24:25], 0, v[148:149]
	s_add_i32 m0, s33, 0xc000
	ds_read_b128 v[186:189], v160
	ds_read_b128 v[190:193], v160 offset:1024
	ds_read_b128 v[194:197], v160 offset:2048
	ds_read_b128 v[198:201], v160 offset:3072
	ds_read_b128 v[202:205], v160 offset:4096
	ds_read_b128 v[206:209], v160 offset:5120
	ds_read_b128 v[210:213], v160 offset:6144
	ds_read_b128 v[214:217], v160 offset:7168
	global_load_lds_dwordx4 v[156:157], off
	v_lshl_add_u64 v[156:157], s[24:25], 0, v[150:151]
	s_add_i32 m0, s33, 0xe000
	s_nop 0
	global_load_lds_dwordx4 v[156:157], off
	s_waitcnt vmcnt(8)
	s_waitcnt lgkmcnt(0)
	s_barrier
	s_setprio 1
	v_mfma_f32_16x16x32_bf16 v[134:137], v[66:69], v[186:189], v[134:137]
	v_mfma_f32_16x16x32_bf16 v[126:129], v[152:155], v[186:189], v[126:129]
	v_mfma_f32_16x16x32_bf16 v[114:117], v[66:69], v[194:197], v[114:117]
	v_mfma_f32_16x16x32_bf16 v[110:113], v[152:155], v[194:197], v[110:113]
	v_mfma_f32_16x16x32_bf16 v[98:101], v[66:69], v[202:205], v[98:101]
	v_mfma_f32_16x16x32_bf16 v[94:97], v[152:155], v[202:205], v[94:97]
	v_mfma_f32_16x16x32_bf16 v[82:85], v[66:69], v[210:213], v[82:85]
	v_mfma_f32_16x16x32_bf16 v[78:81], v[152:155], v[210:213], v[78:81]
	v_mfma_f32_16x16x32_bf16 v[134:137], v[118:121], v[190:193], v[134:137]
	v_mfma_f32_16x16x32_bf16 v[126:129], v[162:165], v[190:193], v[126:129]
	v_mfma_f32_16x16x32_bf16 v[114:117], v[118:121], v[198:201], v[114:117]
	v_mfma_f32_16x16x32_bf16 v[110:113], v[162:165], v[198:201], v[110:113]
	v_mfma_f32_16x16x32_bf16 v[98:101], v[118:121], v[206:209], v[98:101]
	v_mfma_f32_16x16x32_bf16 v[94:97], v[162:165], v[206:209], v[94:97]
	v_mfma_f32_16x16x32_bf16 v[82:85], v[118:121], v[214:217], v[82:85]
	v_mfma_f32_16x16x32_bf16 v[78:81], v[162:165], v[214:217], v[78:81]
	s_setprio 0
	s_setprio 1
	v_mfma_f32_16x16x32_bf16 v[130:133], v[166:169], v[186:189], v[130:133]
	v_mfma_f32_16x16x32_bf16 v[122:125], v[174:177], v[186:189], v[122:125]
	v_mfma_f32_16x16x32_bf16 v[106:109], v[166:169], v[194:197], v[106:109]
	v_mfma_f32_16x16x32_bf16 v[102:105], v[174:177], v[194:197], v[102:105]
	v_mfma_f32_16x16x32_bf16 v[90:93], v[166:169], v[202:205], v[90:93]
	v_mfma_f32_16x16x32_bf16 v[86:89], v[174:177], v[202:205], v[86:89]
	v_mfma_f32_16x16x32_bf16 v[74:77], v[166:169], v[210:213], v[74:77]
	v_mfma_f32_16x16x32_bf16 v[70:73], v[174:177], v[210:213], v[70:73]
	v_mfma_f32_16x16x32_bf16 v[130:133], v[170:173], v[190:193], v[130:133]
	v_mfma_f32_16x16x32_bf16 v[122:125], v[180:183], v[190:193], v[122:125]
	v_mfma_f32_16x16x32_bf16 v[106:109], v[170:173], v[198:201], v[106:109]
	v_mfma_f32_16x16x32_bf16 v[102:105], v[180:183], v[198:201], v[102:105]
	v_mfma_f32_16x16x32_bf16 v[90:93], v[170:173], v[206:209], v[90:93]
	v_mfma_f32_16x16x32_bf16 v[86:89], v[180:183], v[206:209], v[86:89]
	v_mfma_f32_16x16x32_bf16 v[74:77], v[170:173], v[214:217], v[74:77]
	v_mfma_f32_16x16x32_bf16 v[70:73], v[180:183], v[214:217], v[70:73]
	s_setprio 0
	s_barrier
	s_add_i32 s50, s50, s36
	v_lshl_add_u64 v[156:157], s[26:27], 0, v[142:143]
	s_mov_b32 m0, s50
	ds_read_b128 v[186:189], v160 offset:16384
	ds_read_b128 v[190:193], v160 offset:17408
	ds_read_b128 v[194:197], v160 offset:18432
	ds_read_b128 v[198:201], v160 offset:19456
	ds_read_b128 v[202:205], v160 offset:20480
	ds_read_b128 v[206:209], v160 offset:21504
	ds_read_b128 v[210:213], v160 offset:22528
	ds_read_b128 v[214:217], v160 offset:23552
	global_load_lds_dwordx4 v[156:157], off
	s_add_i32 m0, s50, 0x2000
	s_add_u32 s50, s26, 0x40000
	v_lshl_add_u64 v[218:219], s[26:27], 0, v[138:139]
	s_addc_u32 s51, s27, 0
	s_add_i32 s52, s52, s36
	global_load_lds_dwordx4 v[218:219], off
	v_lshl_add_u64 v[220:221], s[50:51], 0, v[142:143]
	s_mov_b32 m0, s52
	v_lshl_add_u64 v[222:223], s[28:29], 0, v[140:141]
	global_load_lds_dwordx4 v[220:221], off
	v_lshl_add_u64 v[220:221], s[50:51], 0, v[138:139]
	s_add_i32 m0, s52, 0x2000
	s_nop 0
	global_load_lds_dwordx4 v[220:221], off
	v_lshl_add_u64 v[220:221], s[28:29], 0, v[144:145]
	s_mov_b32 m0, s33
	s_nop 0
	global_load_lds_dwordx4 v[220:221], off
	s_mov_b32 m0, s38
	s_nop 0
	global_load_lds_dwordx4 v[222:223], off
	s_waitcnt vmcnt(8)
	s_waitcnt lgkmcnt(0)
	s_barrier
; #define PG8_STAGE(bufoff, gbase, voff) do { _Pragma("unroll") for (int _i = 0; _i < 2; ++_i) \
;         __builtin_amdgcn_global_load_lds((const unsigned*)((const char*)(gbase) + (voff)[_i]), (PG8_LAS unsigned*)(lds + (bufoff) + ldsw + _i * 8192), 16, 0, 0); } while (0)
; #define PG8_LDA(dst, b, h) do { _Pragma("unroll") for (int m = 0; m < 4; ++m) _Pragma("unroll") for (int k = 0; k < 2; ++k) dst[m][k] = *(const PG8_LAS bf16x8*)(lds + PG8_SA(b, h) + aoff + m * 2048 + k * 1024); } while (0)
; #define PG8_LDB(dst, b, h) do { _Pragma("unroll") for (int n = 0; n < 2; ++n) _Pragma("unroll") for (int k = 0; k < 2; ++k) dst[n][k] = *(const PG8_LAS bf16x8*)(lds + PG8_SB(b, h) + boff + n * 2048 + k * 1024); } while (0)
; #define PG8_MMA(ai, bj, At, Bt) do { __builtin_amdgcn_s_setprio(1); _Pragma("unroll") for (int m = 0; m < 4; ++m) _Pragma("unroll") for (int n = 0; n < 2; ++n) _Pragma("unroll") for (int k = 0; k < 2; ++k) \
;         acc[ai][bj][m][n] = __builtin_amdgcn_mfma_f32_16x16x32_bf16(Bt[n][k], At[m][k], acc[ai][bj][m][n], 0, 0, 0); __builtin_amdgcn_s_setprio(0); } while (0)
; #define PG8_WAIT_V(n) asm volatile("s_waitcnt vmcnt(" #n ")" ::: "memory")
; #define PG8_WAIT_L(n) asm volatile("s_waitcnt lgkmcnt(" #n ")" ::: "memory")
; #define PG8_BAR __builtin_amdgcn_s_barrier()
; #define PG8_SCHED __builtin_amdgcn_sched_barrier(0)
; template <class Epi, class Sched, bool ALIGN_EPI = false, bool SP2 = false>
; __device__ __forceinline__ void gemm_phase(PG8_LAS unsigned char* lds, const Gemm g, const Sched& S, const Epi& E) {
;     ...
;             PG8_WAIT_V(8); PG8_WAIT_L(0); PG8_BAR; PG8_MMA(1, 0, At, B0); PG8_MMA(1, 1, At, B1); PG8_BAR; PG8_SCHED;
;             PG8_LDB(B0, 1, 0); PG8_LDB(B1, 1, 1); PG8_SCHED; PG8_LDA(At, 1, 0); PG8_STAGE(PG8_SA(0, 1), a2 + hstep, voffA);
;             PG8_WAIT_V(8); PG8_WAIT_L(0); PG8_BAR; PG8_MMA(0, 0, At, B0); PG8_MMA(0, 1, At, B1); PG8_BAR; PG8_SCHED;
	s_setprio 1
	v_mfma_f32_16x16x32_bf16 v[62:65], v[66:69], v[186:189], v[62:65]
	v_mfma_f32_16x16x32_bf16 v[58:61], v[152:155], v[186:189], v[58:61]
	v_mfma_f32_16x16x32_bf16 v[46:49], v[66:69], v[194:197], v[46:49]
	v_mfma_f32_16x16x32_bf16 v[42:45], v[152:155], v[194:197], v[42:45]
	v_mfma_f32_16x16x32_bf16 v[30:33], v[66:69], v[202:205], v[30:33]
	v_mfma_f32_16x16x32_bf16 v[26:29], v[152:155], v[202:205], v[26:29]
	v_mfma_f32_16x16x32_bf16 v[14:17], v[66:69], v[210:213], v[14:17]
	v_mfma_f32_16x16x32_bf16 v[10:13], v[152:155], v[210:213], v[10:13]
	v_mfma_f32_16x16x32_bf16 v[62:65], v[118:121], v[190:193], v[62:65]
	v_mfma_f32_16x16x32_bf16 v[58:61], v[162:165], v[190:193], v[58:61]
	v_mfma_f32_16x16x32_bf16 v[46:49], v[118:121], v[198:201], v[46:49]
	v_mfma_f32_16x16x32_bf16 v[42:45], v[162:165], v[198:201], v[42:45]
	v_mfma_f32_16x16x32_bf16 v[30:33], v[118:121], v[206:209], v[30:33]
	v_mfma_f32_16x16x32_bf16 v[26:29], v[162:165], v[206:209], v[26:29]
	v_mfma_f32_16x16x32_bf16 v[14:17], v[118:121], v[214:217], v[14:17]
	v_mfma_f32_16x16x32_bf16 v[10:13], v[162:165], v[214:217], v[10:13]
	s_setprio 0
	s_setprio 1
	v_mfma_f32_16x16x32_bf16 v[54:57], v[166:169], v[186:189], v[54:57]
	v_mfma_f32_16x16x32_bf16 v[50:53], v[174:177], v[186:189], v[50:53]
	v_mfma_f32_16x16x32_bf16 v[38:41], v[166:169], v[194:197], v[38:41]
	v_mfma_f32_16x16x32_bf16 v[34:37], v[174:177], v[194:197], v[34:37]
	v_mfma_f32_16x16x32_bf16 v[22:25], v[166:169], v[202:205], v[22:25]
	v_mfma_f32_16x16x32_bf16 v[18:21], v[174:177], v[202:205], v[18:21]
	v_mfma_f32_16x16x32_bf16 v[6:9], v[166:169], v[210:213], v[6:9]
	v_mfma_f32_16x16x32_bf16 v[2:5], v[174:177], v[210:213], v[2:5]
	v_mfma_f32_16x16x32_bf16 v[54:57], v[170:173], v[190:193], v[54:57]
	v_mfma_f32_16x16x32_bf16 v[50:53], v[180:183], v[190:193], v[50:53]
	v_mfma_f32_16x16x32_bf16 v[38:41], v[170:173], v[198:201], v[38:41]
	v_mfma_f32_16x16x32_bf16 v[34:37], v[180:183], v[198:201], v[34:37]
	v_mfma_f32_16x16x32_bf16 v[22:25], v[170:173], v[206:209], v[22:25]
	v_mfma_f32_16x16x32_bf16 v[18:21], v[180:183], v[206:209], v[18:21]
	v_mfma_f32_16x16x32_bf16 v[6:9], v[170:173], v[214:217], v[6:9]
	v_mfma_f32_16x16x32_bf16 v[2:5], v[180:183], v[214:217], v[2:5]
	s_setprio 0
	s_barrier
	s_add_i32 s50, 0, 0x18000
	v_add_u32_e32 v161, s50, v158
	s_add_i32 s51, 0, 0x1c000
	ds_read_b128 v[66:69], v161
	ds_read_b128 v[118:121], v161 offset:1024
	ds_read_b128 v[152:155], v161 offset:2048
	ds_read_b128 v[162:165], v161 offset:3072
	v_add_u32_e32 v161, s51, v158
	ds_read_b128 v[166:169], v161
	ds_read_b128 v[170:173], v161 offset:1024
	ds_read_b128 v[174:177], v161 offset:2048
	ds_read_b128 v[180:183], v161 offset:3072
	s_add_u32 s28, s28, 0x40000
	s_addc_u32 s29, s29, 0
	s_mov_b32 m0, s39
	v_lshl_add_u64 v[240:241], s[28:29], 0, v[144:145]
	ds_read_b128 v[186:189], v160 offset:32768
	ds_read_b128 v[190:193], v160 offset:33792
	ds_read_b128 v[194:197], v160 offset:34816
	ds_read_b128 v[198:201], v160 offset:35840
	ds_read_b128 v[202:205], v160 offset:36864
	ds_read_b128 v[206:209], v160 offset:37888
	ds_read_b128 v[210:213], v160 offset:38912
	ds_read_b128 v[214:217], v160 offset:39936
	global_load_lds_dwordx4 v[240:241], off
	v_lshl_add_u64 v[240:241], s[28:29], 0, v[140:141]
	s_mov_b32 m0, s40
	s_nop 0
	global_load_lds_dwordx4 v[240:241], off
	s_waitcnt vmcnt(8)
	s_waitcnt lgkmcnt(0)
	s_barrier
	s_setprio 1
	v_mfma_f32_16x16x32_bf16 v[134:137], v[66:69], v[186:189], v[134:137]
	v_mfma_f32_16x16x32_bf16 v[126:129], v[152:155], v[186:189], v[126:129]
	v_mfma_f32_16x16x32_bf16 v[114:117], v[66:69], v[194:197], v[114:117]
	v_mfma_f32_16x16x32_bf16 v[110:113], v[152:155], v[194:197], v[110:113]
	v_mfma_f32_16x16x32_bf16 v[98:101], v[66:69], v[202:205], v[98:101]
	v_mfma_f32_16x16x32_bf16 v[94:97], v[152:155], v[202:205], v[94:97]
	v_mfma_f32_16x16x32_bf16 v[82:85], v[66:69], v[210:213], v[82:85]
	v_mfma_f32_16x16x32_bf16 v[78:81], v[152:155], v[210:213], v[78:81]
	v_mfma_f32_16x16x32_bf16 v[134:137], v[118:121], v[190:193], v[134:137]
	v_mfma_f32_16x16x32_bf16 v[126:129], v[162:165], v[190:193], v[126:129]
	v_mfma_f32_16x16x32_bf16 v[114:117], v[118:121], v[198:201], v[114:117]
	v_mfma_f32_16x16x32_bf16 v[110:113], v[162:165], v[198:201], v[110:113]
	v_mfma_f32_16x16x32_bf16 v[98:101], v[118:121], v[206:209], v[98:101]
	v_mfma_f32_16x16x32_bf16 v[94:97], v[162:165], v[206:209], v[94:97]
	v_mfma_f32_16x16x32_bf16 v[82:85], v[118:121], v[214:217], v[82:85]
	v_mfma_f32_16x16x32_bf16 v[78:81], v[162:165], v[214:217], v[78:81]
	s_setprio 0
	s_setprio 1
	v_mfma_f32_16x16x32_bf16 v[130:133], v[166:169], v[186:189], v[130:133]
	v_mfma_f32_16x16x32_bf16 v[122:125], v[174:177], v[186:189], v[122:125]
	v_mfma_f32_16x16x32_bf16 v[106:109], v[166:169], v[194:197], v[106:109]
	v_mfma_f32_16x16x32_bf16 v[102:105], v[174:177], v[194:197], v[102:105]
	v_mfma_f32_16x16x32_bf16 v[90:93], v[166:169], v[202:205], v[90:93]
	v_mfma_f32_16x16x32_bf16 v[86:89], v[174:177], v[202:205], v[86:89]
	v_mfma_f32_16x16x32_bf16 v[74:77], v[166:169], v[210:213], v[74:77]
	v_mfma_f32_16x16x32_bf16 v[70:73], v[174:177], v[210:213], v[70:73]
	v_mfma_f32_16x16x32_bf16 v[130:133], v[170:173], v[190:193], v[130:133]
	v_mfma_f32_16x16x32_bf16 v[122:125], v[180:183], v[190:193], v[122:125]
	v_mfma_f32_16x16x32_bf16 v[106:109], v[170:173], v[198:201], v[106:109]
	v_mfma_f32_16x16x32_bf16 v[102:105], v[180:183], v[198:201], v[102:105]
	v_mfma_f32_16x16x32_bf16 v[90:93], v[170:173], v[206:209], v[90:93]
	v_mfma_f32_16x16x32_bf16 v[86:89], v[180:183], v[206:209], v[86:89]
	v_mfma_f32_16x16x32_bf16 v[74:77], v[170:173], v[214:217], v[74:77]
	v_mfma_f32_16x16x32_bf16 v[70:73], v[180:183], v[214:217], v[70:73]
	s_setprio 0
	s_barrier
; #define PG8_STAGE(bufoff, gbase, voff) do { _Pragma("unroll") for (int _i = 0; _i < 2; ++_i) \
;         __builtin_amdgcn_global_load_lds((const unsigned*)((const char*)(gbase) + (voff)[_i]), (PG8_LAS unsigned*)(lds + (bufoff) + ldsw + _i * 8192), 16, 0, 0); } while (0)
; #define PG8_WAIT_V(n) asm volatile("s_waitcnt vmcnt(" #n ")" ::: "memory")
; #define PG8_WAIT_L(n) asm volatile("s_waitcnt lgkmcnt(" #n ")" ::: "memory")
; template <class Epi, class Sched, bool ALIGN_EPI = false, bool SP2 = false>
; __device__ __forceinline__ void gemm_phase(PG8_LAS unsigned char* lds, const Gemm g, const Sched& S, const Epi& E) {
;     ...
;             PG8_LDA(At, 1, 1); PG8_STAGE(PG8_SB(1, 0), b3, voffB); PG8_STAGE(PG8_SB(1, 1), b3 + hstep, voffB); PG8_STAGE(PG8_SA(1, 0), a3, voffA);
;             PG8_WAIT_V(8); PG8_WAIT_L(0); PG8_BAR; PG8_MMA(1, 0, At, B0); PG8_MMA(1, 1, At, B1); PG8_BAR; PG8_SCHED;
;             } else {
;             PG8_LDB(B0, 0, 0); PG8_SCHED; PG8_LDA(At, 0, 0); PG8_STAGE(PG8_SA(1, 1), a1 + hstep, voffA);
;             PG8_WAIT_L(8); PG8_BAR; PG8_WAIT_L(0); PG8_MMA(0, 0, At, B0); PG8_BAR; PG8_SCHED;
;             PG8_LDB(B1, 0, 1); PG8_STAGE(PG8_SB(0, 0), b2, voffB);
;             PG8_BAR; PG8_WAIT_L(0); PG8_MMA(0, 1, At, B1); PG8_BAR;
;             PG8_LDA(At, 0, 1); PG8_STAGE(PG8_SA(0, 0), a2, voffA);
;             PG8_BAR; PG8_WAIT_L(0); PG8_MMA(1, 0, At, B0); PG8_BAR; PG8_SCHED;
;             PG8_STAGE(PG8_SB(0, 1), b2 + hstep, voffB);
;             PG8_WAIT_V(6); PG8_BAR; PG8_MMA(1, 1, At, B1); PG8_BAR;
;             PG8_LDB(B0, 1, 0); PG8_SCHED; PG8_LDA(At, 1, 0); PG8_STAGE(PG8_SA(0, 1), a2 + hstep, voffA);
;             PG8_WAIT_L(8); PG8_BAR; PG8_WAIT_L(0); PG8_MMA(0, 0, At, B0); PG8_BAR; PG8_SCHED;
;             PG8_LDB(B1, 1, 1); PG8_STAGE(PG8_SB(1, 0), b3, voffB);
;             PG8_BAR; PG8_WAIT_L(0); PG8_MMA(0, 1, At, B1); PG8_BAR;
;             PG8_LDA(At, 1, 1); PG8_STAGE(PG8_SA(1, 0), a3, voffA);
;             PG8_BAR; PG8_WAIT_L(0); PG8_MMA(1, 0, At, B0); PG8_BAR; PG8_SCHED;
;             PG8_STAGE(PG8_SB(1, 1), b3 + hstep, voffB);
;             PG8_WAIT_V(6); PG8_BAR; PG8_MMA(1, 1, At, B1); PG8_BAR;
;             }
;         }
;         if constexpr (ALIGN_EPI) { if (wr == 0) PG8_BAR; }
;         if constexpr (!Epi::AFTER_DRAIN) { E(acc, cur, wr, wc, fr, fq); S.done(cur); }
;         if (!has_next) break;
	s_add_i32 s28, s50, s36
	v_lshl_add_u64 v[156:157], v[156:157], 0, s[80:81]
	s_mov_b32 m0, s28
	ds_read_b128 v[186:189], v160 offset:49152
	ds_read_b128 v[190:193], v160 offset:50176
	ds_read_b128 v[194:197], v160 offset:51200
	ds_read_b128 v[198:201], v160 offset:52224
	ds_read_b128 v[202:205], v160 offset:53248
	ds_read_b128 v[206:209], v160 offset:54272
	ds_read_b128 v[210:213], v160 offset:55296
	ds_read_b128 v[214:217], v160 offset:56320
	global_load_lds_dwordx4 v[156:157], off
	s_add_i32 m0, s28, 0x2000
	s_add_u32 s26, s26, 0x40080
	v_lshl_add_u64 v[156:157], v[218:219], 0, s[80:81]
	s_addc_u32 s27, s27, 0
	s_add_i32 s28, s51, s36
	global_load_lds_dwordx4 v[156:157], off
	v_lshl_add_u64 v[156:157], s[26:27], 0, v[142:143]
	s_mov_b32 m0, s28
	s_nop 0
	global_load_lds_dwordx4 v[156:157], off
	v_lshl_add_u64 v[156:157], s[26:27], 0, v[138:139]
	s_add_i32 m0, s28, 0x2000
	s_nop 0
	global_load_lds_dwordx4 v[156:157], off
	v_lshl_add_u64 v[156:157], v[220:221], 0, s[80:81]
	s_mov_b32 m0, s41
	s_nop 0
	global_load_lds_dwordx4 v[156:157], off
	v_lshl_add_u64 v[156:157], v[222:223], 0, s[80:81]
	s_mov_b32 m0, s42
	s_nop 0
	global_load_lds_dwordx4 v[156:157], off
	s_waitcnt vmcnt(8)
	s_waitcnt lgkmcnt(0)
	s_barrier
	s_setprio 1
	v_mfma_f32_16x16x32_bf16 v[62:65], v[66:69], v[186:189], v[62:65]
	v_mfma_f32_16x16x32_bf16 v[58:61], v[152:155], v[186:189], v[58:61]
	v_mfma_f32_16x16x32_bf16 v[46:49], v[66:69], v[194:197], v[46:49]
	v_mfma_f32_16x16x32_bf16 v[42:45], v[152:155], v[194:197], v[42:45]
	v_mfma_f32_16x16x32_bf16 v[30:33], v[66:69], v[202:205], v[30:33]
	v_mfma_f32_16x16x32_bf16 v[26:29], v[152:155], v[202:205], v[26:29]
	v_mfma_f32_16x16x32_bf16 v[14:17], v[66:69], v[210:213], v[14:17]
	v_mfma_f32_16x16x32_bf16 v[10:13], v[152:155], v[210:213], v[10:13]
	v_mfma_f32_16x16x32_bf16 v[62:65], v[118:121], v[190:193], v[62:65]
	v_mfma_f32_16x16x32_bf16 v[58:61], v[162:165], v[190:193], v[58:61]
	v_mfma_f32_16x16x32_bf16 v[46:49], v[118:121], v[198:201], v[46:49]
	v_mfma_f32_16x16x32_bf16 v[42:45], v[162:165], v[198:201], v[42:45]
	v_mfma_f32_16x16x32_bf16 v[30:33], v[118:121], v[206:209], v[30:33]
	v_mfma_f32_16x16x32_bf16 v[26:29], v[162:165], v[206:209], v[26:29]
	v_mfma_f32_16x16x32_bf16 v[14:17], v[118:121], v[214:217], v[14:17]
	v_mfma_f32_16x16x32_bf16 v[10:13], v[162:165], v[214:217], v[10:13]
	s_setprio 0
	s_setprio 1
	v_mfma_f32_16x16x32_bf16 v[54:57], v[166:169], v[186:189], v[54:57]
	v_mfma_f32_16x16x32_bf16 v[50:53], v[174:177], v[186:189], v[50:53]
	v_mfma_f32_16x16x32_bf16 v[38:41], v[166:169], v[194:197], v[38:41]
	v_mfma_f32_16x16x32_bf16 v[34:37], v[174:177], v[194:197], v[34:37]
	v_mfma_f32_16x16x32_bf16 v[22:25], v[166:169], v[202:205], v[22:25]
	v_mfma_f32_16x16x32_bf16 v[18:21], v[174:177], v[202:205], v[18:21]
	v_mfma_f32_16x16x32_bf16 v[6:9], v[166:169], v[210:213], v[6:9]
	v_mfma_f32_16x16x32_bf16 v[2:5], v[174:177], v[210:213], v[2:5]
	v_mfma_f32_16x16x32_bf16 v[54:57], v[170:173], v[190:193], v[54:57]
	v_mfma_f32_16x16x32_bf16 v[50:53], v[180:183], v[190:193], v[50:53]
	v_mfma_f32_16x16x32_bf16 v[38:41], v[170:173], v[198:201], v[38:41]
	v_mfma_f32_16x16x32_bf16 v[34:37], v[180:183], v[198:201], v[34:37]
	v_mfma_f32_16x16x32_bf16 v[22:25], v[170:173], v[206:209], v[22:25]
	v_mfma_f32_16x16x32_bf16 v[18:21], v[180:183], v[206:209], v[18:21]
	v_mfma_f32_16x16x32_bf16 v[6:9], v[170:173], v[214:217], v[6:9]
	v_mfma_f32_16x16x32_bf16 v[2:5], v[180:183], v[214:217], v[2:5]
	s_setprio 0
	s_barrier
	s_add_i32 s49, s49, 2
	s_add_u32 s24, s24, 0x100
	s_addc_u32 s25, s25, 0
	s_add_u32 s47, s47, 0x100
	s_addc_u32 s48, s48, 0
	s_cmp_gt_u32 s49, 13
	s_cbranch_scc0 .LBB0_1249
	s_and_b64 vcc, exec, s[12:13]
	s_cbranch_vccz .LBB0_1252
	s_barrier

; #define PG8_STAGE(bufoff, gbase, voff) do { _Pragma("unroll") for (int _i = 0; _i < 2; ++_i) \
;         __builtin_amdgcn_global_load_lds((const unsigned*)((const char*)(gbase) + (voff)[_i]), (PG8_LAS unsigned*)(lds + (bufoff) + ldsw + _i * 8192), 16, 0, 0); } while (0)
; #define PG8_LDA(dst, b, h) do { _Pragma("unroll") for (int m = 0; m < 4; ++m) _Pragma("unroll") for (int k = 0; k < 2; ++k) dst[m][k] = *(const PG8_LAS bf16x8*)(lds + PG8_SA(b, h) + aoff + m * 2048 + k * 1024); } while (0)
; #define PG8_LDB(dst, b, h) do { _Pragma("unroll") for (int n = 0; n < 2; ++n) _Pragma("unroll") for (int k = 0; k < 2; ++k) dst[n][k] = *(const PG8_LAS bf16x8*)(lds + PG8_SB(b, h) + boff + n * 2048 + k * 1024); } while (0)
; #define PG8_MMA(ai, bj, At, Bt) do { __builtin_amdgcn_s_setprio(1); _Pragma("unroll") for (int m = 0; m < 4; ++m) _Pragma("unroll") for (int n = 0; n < 2; ++n) _Pragma("unroll") for (int k = 0; k < 2; ++k) \
;         acc[ai][bj][m][n] = __builtin_amdgcn_mfma_f32_16x16x32_bf16(Bt[n][k], At[m][k], acc[ai][bj][m][n], 0, 0, 0); __builtin_amdgcn_s_setprio(0); } while (0)
; #define PG8_WAIT_V(n) asm volatile("s_waitcnt vmcnt(" #n ")" ::: "memory")
; #define PG8_BAR __builtin_amdgcn_s_barrier()
; template <class Epi, class Sched, bool ALIGN_EPI = false, bool SP2 = false>
; __device__ __forceinline__ void gemm_phase(PG8_LAS unsigned char* lds, const Gemm g, const Sched& S, const Epi& E) {
;     ...
;         for (int t = 0; t < nt; t += 2) {
;             const bool last = (t == nt - 2);
;             const char* a1 = cA + (size_t)(t + 1) * kstep;
;             const char* a2 = last ? nA : cA + (size_t)(t + 2) * kstep; const char* b2 = last ? nB : cB + (size_t)(t + 2) * kstep;
;             const char* a3 = a2 + kstep; const char* b3 = b2 + kstep;
;             if (last && has_next) S.a_ready(nxt);
;             if constexpr (SP2) {
;             PG8_LDB(B0, 0, 0); PG8_LDB(B1, 0, 1); PG8_SCHED; PG8_LDA(At, 0, 0); PG8_STAGE(PG8_SA(1, 1), a1 + hstep, voffA);
;             PG8_WAIT_V(8); PG8_WAIT_L(0); PG8_BAR; PG8_MMA(0, 0, At, B0); PG8_MMA(0, 1, At, B1); PG8_BAR; PG8_SCHED;
;             PG8_LDA(At, 0, 1); PG8_STAGE(PG8_SB(0, 0), b2, voffB); PG8_STAGE(PG8_SB(0, 1), b2 + hstep, voffB); PG8_STAGE(PG8_SA(0, 0), a2, voffA);
;             PG8_WAIT_V(8); PG8_WAIT_L(0); PG8_BAR; PG8_MMA(1, 0, At, B0); PG8_MMA(1, 1, At, B1); PG8_BAR; PG8_SCHED;
.LBB0_1330:
	s_add_u32 s22, s20, 0x100
	s_addc_u32 s23, s21, 0
	s_add_i32 s52, 0, 0x10000
	s_cmp_eq_u32 s51, 40
	s_cselect_b32 s27, s7, s23
	s_cselect_b32 s26, s6, s22
	v_add_u32_e32 v157, s52, v154
	s_cselect_b32 s25, s19, s50
	s_cselect_b32 s24, s18, s49
	s_add_i32 s53, 0, 0x14000
	ds_read_b128 v[142:145], v157
	ds_read_b128 v[146:149], v157 offset:1024
	ds_read_b128 v[150:153], v157 offset:2048
	ds_read_b128 v[158:161], v157 offset:3072
	v_add_u32_e32 v157, s53, v154
	ds_read_b128 v[162:165], v157
	ds_read_b128 v[166:169], v157 offset:1024
	ds_read_b128 v[170:173], v157 offset:2048
	ds_read_b128 v[174:177], v157 offset:3072
	v_lshl_add_u64 v[214:215], s[20:21], 0, v[138:139]
	s_add_i32 m0, s37, 0xc000
	ds_read_b128 v[180:183], v156
	ds_read_b128 v[186:189], v156 offset:1024
	ds_read_b128 v[190:193], v156 offset:2048
	ds_read_b128 v[194:197], v156 offset:3072
	ds_read_b128 v[198:201], v156 offset:4096
	ds_read_b128 v[202:205], v156 offset:5120
	ds_read_b128 v[206:209], v156 offset:6144
	ds_read_b128 v[210:213], v156 offset:7168
	global_load_lds_dwordx4 v[214:215], off
	v_lshl_add_u64 v[214:215], s[20:21], 0, v[140:141]
	s_add_i32 m0, s37, 0xe000
	s_nop 0
	global_load_lds_dwordx4 v[214:215], off
	s_waitcnt vmcnt(8)
	s_waitcnt lgkmcnt(0)
	s_barrier
	s_setprio 1
	v_mfma_f32_16x16x32_bf16 v[126:129], v[142:145], v[180:183], v[126:129]
	v_mfma_f32_16x16x32_bf16 v[122:125], v[150:153], v[180:183], v[122:125]
	v_mfma_f32_16x16x32_bf16 v[114:117], v[142:145], v[190:193], v[114:117]
	v_mfma_f32_16x16x32_bf16 v[106:109], v[150:153], v[190:193], v[106:109]
	v_mfma_f32_16x16x32_bf16 v[98:101], v[142:145], v[198:201], v[98:101]
	v_mfma_f32_16x16x32_bf16 v[90:93], v[150:153], v[198:201], v[90:93]
	v_mfma_f32_16x16x32_bf16 v[82:85], v[142:145], v[206:209], v[82:85]
	v_mfma_f32_16x16x32_bf16 v[74:77], v[150:153], v[206:209], v[74:77]
	v_mfma_f32_16x16x32_bf16 v[126:129], v[146:149], v[186:189], v[126:129]
	v_mfma_f32_16x16x32_bf16 v[122:125], v[158:161], v[186:189], v[122:125]
	v_mfma_f32_16x16x32_bf16 v[114:117], v[146:149], v[194:197], v[114:117]
	v_mfma_f32_16x16x32_bf16 v[106:109], v[158:161], v[194:197], v[106:109]
	v_mfma_f32_16x16x32_bf16 v[98:101], v[146:149], v[202:205], v[98:101]
	v_mfma_f32_16x16x32_bf16 v[90:93], v[158:161], v[202:205], v[90:93]
	v_mfma_f32_16x16x32_bf16 v[82:85], v[146:149], v[210:213], v[82:85]
	v_mfma_f32_16x16x32_bf16 v[74:77], v[158:161], v[210:213], v[74:77]
	s_setprio 0
	s_setprio 1
	v_mfma_f32_16x16x32_bf16 v[118:121], v[162:165], v[180:183], v[118:121]
	v_mfma_f32_16x16x32_bf16 v[110:113], v[170:173], v[180:183], v[110:113]
	v_mfma_f32_16x16x32_bf16 v[102:105], v[162:165], v[190:193], v[102:105]
	v_mfma_f32_16x16x32_bf16 v[94:97], v[170:173], v[190:193], v[94:97]
	v_mfma_f32_16x16x32_bf16 v[86:89], v[162:165], v[198:201], v[86:89]
	v_mfma_f32_16x16x32_bf16 v[78:81], v[170:173], v[198:201], v[78:81]
	v_mfma_f32_16x16x32_bf16 v[70:73], v[162:165], v[206:209], v[70:73]
	v_mfma_f32_16x16x32_bf16 v[66:69], v[170:173], v[206:209], v[66:69]
	v_mfma_f32_16x16x32_bf16 v[118:121], v[166:169], v[186:189], v[118:121]
	v_mfma_f32_16x16x32_bf16 v[110:113], v[174:177], v[186:189], v[110:113]
	v_mfma_f32_16x16x32_bf16 v[102:105], v[166:169], v[194:197], v[102:105]
	v_mfma_f32_16x16x32_bf16 v[94:97], v[174:177], v[194:197], v[94:97]
	v_mfma_f32_16x16x32_bf16 v[86:89], v[166:169], v[202:205], v[86:89]
	v_mfma_f32_16x16x32_bf16 v[78:81], v[174:177], v[202:205], v[78:81]
	v_mfma_f32_16x16x32_bf16 v[70:73], v[166:169], v[210:213], v[70:73]
	v_mfma_f32_16x16x32_bf16 v[66:69], v[174:177], v[210:213], v[66:69]
	s_setprio 0
	s_barrier
	s_add_i32 s20, s52, s36
	v_lshl_add_u64 v[214:215], s[24:25], 0, v[132:133]
	s_mov_b32 m0, s20
	ds_read_b128 v[180:183], v156 offset:16384
	ds_read_b128 v[186:189], v156 offset:17408
	ds_read_b128 v[190:193], v156 offset:18432
	ds_read_b128 v[194:197], v156 offset:19456
	ds_read_b128 v[198:201], v156 offset:20480
	ds_read_b128 v[202:205], v156 offset:21504
	ds_read_b128 v[206:209], v156 offset:22528
	ds_read_b128 v[210:213], v156 offset:23552
	global_load_lds_dwordx4 v[214:215], off
	s_add_i32 m0, s20, 0x2000
	s_add_u32 s20, s24, 0xb0000
	v_lshl_add_u64 v[216:217], s[24:25], 0, v[136:137]
	s_addc_u32 s21, s25, 0
	s_add_i32 s52, s53, s36
	global_load_lds_dwordx4 v[216:217], off
	v_lshl_add_u64 v[218:219], s[20:21], 0, v[132:133]
	s_mov_b32 m0, s52
	v_lshl_add_u64 v[220:221], s[26:27], 0, v[134:135]
	global_load_lds_dwordx4 v[218:219], off
	v_lshl_add_u64 v[218:219], s[20:21], 0, v[136:137]
	s_add_i32 m0, s52, 0x2000
	s_nop 0
	global_load_lds_dwordx4 v[218:219], off
	v_lshl_add_u64 v[218:219], s[26:27], 0, v[130:131]
	s_mov_b32 m0, s37
	s_nop 0
	global_load_lds_dwordx4 v[218:219], off
	s_mov_b32 m0, s38
	s_nop 0
	global_load_lds_dwordx4 v[220:221], off
	s_waitcnt vmcnt(8)
	s_waitcnt lgkmcnt(0)
	s_barrier
; #define PG8_STAGE(bufoff, gbase, voff) do { _Pragma("unroll") for (int _i = 0; _i < 2; ++_i) \
;         __builtin_amdgcn_global_load_lds((const unsigned*)((const char*)(gbase) + (voff)[_i]), (PG8_LAS unsigned*)(lds + (bufoff) + ldsw + _i * 8192), 16, 0, 0); } while (0)
; #define PG8_LDA(dst, b, h) do { _Pragma("unroll") for (int m = 0; m < 4; ++m) _Pragma("unroll") for (int k = 0; k < 2; ++k) dst[m][k] = *(const PG8_LAS bf16x8*)(lds + PG8_SA(b, h) + aoff + m * 2048 + k * 1024); } while (0)
; #define PG8_LDB(dst, b, h) do { _Pragma("unroll") for (int n = 0; n < 2; ++n) _Pragma("unroll") for (int k = 0; k < 2; ++k) dst[n][k] = *(const PG8_LAS bf16x8*)(lds + PG8_SB(b, h) + boff + n * 2048 + k * 1024); } while (0)
; #define PG8_MMA(ai, bj, At, Bt) do { __builtin_amdgcn_s_setprio(1); _Pragma("unroll") for (int m = 0; m < 4; ++m) _Pragma("unroll") for (int n = 0; n < 2; ++n) _Pragma("unroll") for (int k = 0; k < 2; ++k) \
;         acc[ai][bj][m][n] = __builtin_amdgcn_mfma_f32_16x16x32_bf16(Bt[n][k], At[m][k], acc[ai][bj][m][n], 0, 0, 0); __builtin_amdgcn_s_setprio(0); } while (0)
; #define PG8_WAIT_V(n) asm volatile("s_waitcnt vmcnt(" #n ")" ::: "memory")
; #define PG8_WAIT_L(n) asm volatile("s_waitcnt lgkmcnt(" #n ")" ::: "memory")
; #define PG8_BAR __builtin_amdgcn_s_barrier()
; #define PG8_SCHED __builtin_amdgcn_sched_barrier(0)
; template <class Epi, class Sched, bool ALIGN_EPI = false, bool SP2 = false>
; __device__ __forceinline__ void gemm_phase(PG8_LAS unsigned char* lds, const Gemm g, const Sched& S, const Epi& E) {
;     ...
;             PG8_WAIT_V(8); PG8_WAIT_L(0); PG8_BAR; PG8_MMA(1, 0, At, B0); PG8_MMA(1, 1, At, B1); PG8_BAR; PG8_SCHED;
;             PG8_LDB(B0, 1, 0); PG8_LDB(B1, 1, 1); PG8_SCHED; PG8_LDA(At, 1, 0); PG8_STAGE(PG8_SA(0, 1), a2 + hstep, voffA);
;             PG8_WAIT_V(8); PG8_WAIT_L(0); PG8_BAR; PG8_MMA(0, 0, At, B0); PG8_MMA(0, 1, At, B1); PG8_BAR; PG8_SCHED;
	s_setprio 1
	v_mfma_f32_16x16x32_bf16 v[62:65], v[142:145], v[180:183], v[62:65]
	v_mfma_f32_16x16x32_bf16 v[58:61], v[150:153], v[180:183], v[58:61]
	v_mfma_f32_16x16x32_bf16 v[50:53], v[142:145], v[190:193], v[50:53]
	v_mfma_f32_16x16x32_bf16 v[42:45], v[150:153], v[190:193], v[42:45]
	v_mfma_f32_16x16x32_bf16 v[34:37], v[142:145], v[198:201], v[34:37]
	v_mfma_f32_16x16x32_bf16 v[26:29], v[150:153], v[198:201], v[26:29]
	v_mfma_f32_16x16x32_bf16 v[18:21], v[142:145], v[206:209], v[18:21]
	v_mfma_f32_16x16x32_bf16 v[10:13], v[150:153], v[206:209], v[10:13]
	v_mfma_f32_16x16x32_bf16 v[62:65], v[146:149], v[186:189], v[62:65]
	v_mfma_f32_16x16x32_bf16 v[58:61], v[158:161], v[186:189], v[58:61]
	v_mfma_f32_16x16x32_bf16 v[50:53], v[146:149], v[194:197], v[50:53]
	v_mfma_f32_16x16x32_bf16 v[42:45], v[158:161], v[194:197], v[42:45]
	v_mfma_f32_16x16x32_bf16 v[34:37], v[146:149], v[202:205], v[34:37]
	v_mfma_f32_16x16x32_bf16 v[26:29], v[158:161], v[202:205], v[26:29]
	v_mfma_f32_16x16x32_bf16 v[18:21], v[146:149], v[210:213], v[18:21]
	v_mfma_f32_16x16x32_bf16 v[10:13], v[158:161], v[210:213], v[10:13]
	s_setprio 0
	s_setprio 1
	v_mfma_f32_16x16x32_bf16 v[54:57], v[162:165], v[180:183], v[54:57]
	v_mfma_f32_16x16x32_bf16 v[46:49], v[170:173], v[180:183], v[46:49]
	v_mfma_f32_16x16x32_bf16 v[38:41], v[162:165], v[190:193], v[38:41]
	v_mfma_f32_16x16x32_bf16 v[30:33], v[170:173], v[190:193], v[30:33]
	v_mfma_f32_16x16x32_bf16 v[22:25], v[162:165], v[198:201], v[22:25]
	v_mfma_f32_16x16x32_bf16 v[14:17], v[170:173], v[198:201], v[14:17]
	v_mfma_f32_16x16x32_bf16 v[6:9], v[162:165], v[206:209], v[6:9]
	v_mfma_f32_16x16x32_bf16 v[2:5], v[170:173], v[206:209], v[2:5]
	v_mfma_f32_16x16x32_bf16 v[54:57], v[166:169], v[186:189], v[54:57]
	v_mfma_f32_16x16x32_bf16 v[46:49], v[174:177], v[186:189], v[46:49]
	v_mfma_f32_16x16x32_bf16 v[38:41], v[166:169], v[194:197], v[38:41]
	v_mfma_f32_16x16x32_bf16 v[30:33], v[174:177], v[194:197], v[30:33]
	v_mfma_f32_16x16x32_bf16 v[22:25], v[166:169], v[202:205], v[22:25]
	v_mfma_f32_16x16x32_bf16 v[14:17], v[174:177], v[202:205], v[14:17]
	v_mfma_f32_16x16x32_bf16 v[6:9], v[166:169], v[210:213], v[6:9]
	v_mfma_f32_16x16x32_bf16 v[2:5], v[174:177], v[210:213], v[2:5]
	s_setprio 0
	s_barrier
	s_add_i32 s52, 0, 0x18000
	v_add_u32_e32 v157, s52, v154
	s_add_i32 s53, 0, 0x1c000
	ds_read_b128 v[142:145], v157
	ds_read_b128 v[146:149], v157 offset:1024
	ds_read_b128 v[150:153], v157 offset:2048
	ds_read_b128 v[158:161], v157 offset:3072
	v_add_u32_e32 v157, s53, v154
	ds_read_b128 v[162:165], v157
	ds_read_b128 v[166:169], v157 offset:1024
	ds_read_b128 v[170:173], v157 offset:2048
	ds_read_b128 v[174:177], v157 offset:3072
	s_add_u32 s20, s26, 0xb0000
	s_addc_u32 s21, s27, 0
	s_mov_b32 m0, s39
	v_lshl_add_u64 v[222:223], s[20:21], 0, v[130:131]
	ds_read_b128 v[180:183], v156 offset:32768
	ds_read_b128 v[186:189], v156 offset:33792
	ds_read_b128 v[190:193], v156 offset:34816
	ds_read_b128 v[194:197], v156 offset:35840
	ds_read_b128 v[198:201], v156 offset:36864
	ds_read_b128 v[202:205], v156 offset:37888
	ds_read_b128 v[206:209], v156 offset:38912
	ds_read_b128 v[210:213], v156 offset:39936
	global_load_lds_dwordx4 v[222:223], off
	v_lshl_add_u64 v[222:223], s[20:21], 0, v[134:135]
	s_mov_b32 m0, s40
	s_nop 0
	global_load_lds_dwordx4 v[222:223], off
	s_waitcnt vmcnt(8)
	s_waitcnt lgkmcnt(0)
	s_barrier
	s_setprio 1
	v_mfma_f32_16x16x32_bf16 v[126:129], v[142:145], v[180:183], v[126:129]
	v_mfma_f32_16x16x32_bf16 v[122:125], v[150:153], v[180:183], v[122:125]
	v_mfma_f32_16x16x32_bf16 v[114:117], v[142:145], v[190:193], v[114:117]
	v_mfma_f32_16x16x32_bf16 v[106:109], v[150:153], v[190:193], v[106:109]
	v_mfma_f32_16x16x32_bf16 v[98:101], v[142:145], v[198:201], v[98:101]
	v_mfma_f32_16x16x32_bf16 v[90:93], v[150:153], v[198:201], v[90:93]
	v_mfma_f32_16x16x32_bf16 v[82:85], v[142:145], v[206:209], v[82:85]
	v_mfma_f32_16x16x32_bf16 v[74:77], v[150:153], v[206:209], v[74:77]
	v_mfma_f32_16x16x32_bf16 v[126:129], v[146:149], v[186:189], v[126:129]
	v_mfma_f32_16x16x32_bf16 v[122:125], v[158:161], v[186:189], v[122:125]
	v_mfma_f32_16x16x32_bf16 v[114:117], v[146:149], v[194:197], v[114:117]
	v_mfma_f32_16x16x32_bf16 v[106:109], v[158:161], v[194:197], v[106:109]
	v_mfma_f32_16x16x32_bf16 v[98:101], v[146:149], v[202:205], v[98:101]
	v_mfma_f32_16x16x32_bf16 v[90:93], v[158:161], v[202:205], v[90:93]
	v_mfma_f32_16x16x32_bf16 v[82:85], v[146:149], v[210:213], v[82:85]
	v_mfma_f32_16x16x32_bf16 v[74:77], v[158:161], v[210:213], v[74:77]
	s_setprio 0
	s_setprio 1
	v_mfma_f32_16x16x32_bf16 v[118:121], v[162:165], v[180:183], v[118:121]
	v_mfma_f32_16x16x32_bf16 v[110:113], v[170:173], v[180:183], v[110:113]
	v_mfma_f32_16x16x32_bf16 v[102:105], v[162:165], v[190:193], v[102:105]
	v_mfma_f32_16x16x32_bf16 v[94:97], v[170:173], v[190:193], v[94:97]
	v_mfma_f32_16x16x32_bf16 v[86:89], v[162:165], v[198:201], v[86:89]
	v_mfma_f32_16x16x32_bf16 v[78:81], v[170:173], v[198:201], v[78:81]
	v_mfma_f32_16x16x32_bf16 v[70:73], v[162:165], v[206:209], v[70:73]
	v_mfma_f32_16x16x32_bf16 v[66:69], v[170:173], v[206:209], v[66:69]
	v_mfma_f32_16x16x32_bf16 v[118:121], v[166:169], v[186:189], v[118:121]
	v_mfma_f32_16x16x32_bf16 v[110:113], v[174:177], v[186:189], v[110:113]
	v_mfma_f32_16x16x32_bf16 v[102:105], v[166:169], v[194:197], v[102:105]
	v_mfma_f32_16x16x32_bf16 v[94:97], v[174:177], v[194:197], v[94:97]
	v_mfma_f32_16x16x32_bf16 v[86:89], v[166:169], v[202:205], v[86:89]
	v_mfma_f32_16x16x32_bf16 v[78:81], v[174:177], v[202:205], v[78:81]
	v_mfma_f32_16x16x32_bf16 v[70:73], v[166:169], v[210:213], v[70:73]
	v_mfma_f32_16x16x32_bf16 v[66:69], v[174:177], v[210:213], v[66:69]
	s_setprio 0
	s_barrier
; #define PG8_STAGE(bufoff, gbase, voff) do { _Pragma("unroll") for (int _i = 0; _i < 2; ++_i) \
;         __builtin_amdgcn_global_load_lds((const unsigned*)((const char*)(gbase) + (voff)[_i]), (PG8_LAS unsigned*)(lds + (bufoff) + ldsw + _i * 8192), 16, 0, 0); } while (0)
; #define PG8_WAIT_V(n) asm volatile("s_waitcnt vmcnt(" #n ")" ::: "memory")
; #define PG8_WAIT_L(n) asm volatile("s_waitcnt lgkmcnt(" #n ")" ::: "memory")
; template <class Epi, class Sched, bool ALIGN_EPI = false, bool SP2 = false>
; __device__ __forceinline__ void gemm_phase(PG8_LAS unsigned char* lds, const Gemm g, const Sched& S, const Epi& E) {
;     ...
;             PG8_LDA(At, 1, 1); PG8_STAGE(PG8_SB(1, 0), b3, voffB); PG8_STAGE(PG8_SB(1, 1), b3 + hstep, voffB); PG8_STAGE(PG8_SA(1, 0), a3, voffA);
;             PG8_WAIT_V(8); PG8_WAIT_L(0); PG8_BAR; PG8_MMA(1, 0, At, B0); PG8_MMA(1, 1, At, B1); PG8_BAR; PG8_SCHED;
;             } else {
;             PG8_LDB(B0, 0, 0); PG8_SCHED; PG8_LDA(At, 0, 0); PG8_STAGE(PG8_SA(1, 1), a1 + hstep, voffA);
;             PG8_WAIT_L(8); PG8_BAR; PG8_WAIT_L(0); PG8_MMA(0, 0, At, B0); PG8_BAR; PG8_SCHED;
;             PG8_LDB(B1, 0, 1); PG8_STAGE(PG8_SB(0, 0), b2, voffB);
;             PG8_BAR; PG8_WAIT_L(0); PG8_MMA(0, 1, At, B1); PG8_BAR;
;             PG8_LDA(At, 0, 1); PG8_STAGE(PG8_SA(0, 0), a2, voffA);
;             PG8_BAR; PG8_WAIT_L(0); PG8_MMA(1, 0, At, B0); PG8_BAR; PG8_SCHED;
;             PG8_STAGE(PG8_SB(0, 1), b2 + hstep, voffB);
;             PG8_WAIT_V(6); PG8_BAR; PG8_MMA(1, 1, At, B1); PG8_BAR;
;             PG8_LDB(B0, 1, 0); PG8_SCHED; PG8_LDA(At, 1, 0); PG8_STAGE(PG8_SA(0, 1), a2 + hstep, voffA);
;             PG8_WAIT_L(8); PG8_BAR; PG8_WAIT_L(0); PG8_MMA(0, 0, At, B0); PG8_BAR; PG8_SCHED;
;             PG8_LDB(B1, 1, 1); PG8_STAGE(PG8_SB(1, 0), b3, voffB);
;             PG8_BAR; PG8_WAIT_L(0); PG8_MMA(0, 1, At, B1); PG8_BAR;
;             PG8_LDA(At, 1, 1); PG8_STAGE(PG8_SA(1, 0), a3, voffA);
;             PG8_BAR; PG8_WAIT_L(0); PG8_MMA(1, 0, At, B0); PG8_BAR; PG8_SCHED;
;             PG8_STAGE(PG8_SB(1, 1), b3 + hstep, voffB);
;             PG8_WAIT_V(6); PG8_BAR; PG8_MMA(1, 1, At, B1); PG8_BAR;
;             }
;         }
;         if constexpr (ALIGN_EPI) { if (wr == 0) PG8_BAR; }
;         if constexpr (!Epi::AFTER_DRAIN) { E(acc, cur, wr, wc, fr, fq); S.done(cur); }
;         if (!has_next) break;
	s_add_i32 s20, s52, s36
	v_lshl_add_u64 v[214:215], v[214:215], 0, s[80:81]
	s_mov_b32 m0, s20
	ds_read_b128 v[180:183], v156 offset:49152
	ds_read_b128 v[186:189], v156 offset:50176
	ds_read_b128 v[190:193], v156 offset:51200
	ds_read_b128 v[194:197], v156 offset:52224
	ds_read_b128 v[198:201], v156 offset:53248
	ds_read_b128 v[202:205], v156 offset:54272
	ds_read_b128 v[206:209], v156 offset:55296
	ds_read_b128 v[210:213], v156 offset:56320
	global_load_lds_dwordx4 v[214:215], off
	s_add_i32 m0, s20, 0x2000
	s_add_u32 s20, s24, 0xb0080
	v_lshl_add_u64 v[214:215], v[216:217], 0, s[80:81]
	s_addc_u32 s21, s25, 0
	s_add_i32 s24, s53, s36
	global_load_lds_dwordx4 v[214:215], off
	v_lshl_add_u64 v[214:215], s[20:21], 0, v[132:133]
	s_mov_b32 m0, s24
	s_nop 0
	global_load_lds_dwordx4 v[214:215], off
	v_lshl_add_u64 v[214:215], s[20:21], 0, v[136:137]
	s_add_i32 m0, s24, 0x2000
	s_nop 0
	global_load_lds_dwordx4 v[214:215], off
	v_lshl_add_u64 v[214:215], v[218:219], 0, s[80:81]
	s_mov_b32 m0, s41
	s_nop 0
	global_load_lds_dwordx4 v[214:215], off
	v_lshl_add_u64 v[214:215], v[220:221], 0, s[80:81]
	s_mov_b32 m0, s42
	s_nop 0
	global_load_lds_dwordx4 v[214:215], off
	s_waitcnt vmcnt(8)
	s_waitcnt lgkmcnt(0)
	s_barrier
	s_setprio 1
	v_mfma_f32_16x16x32_bf16 v[62:65], v[142:145], v[180:183], v[62:65]
	v_mfma_f32_16x16x32_bf16 v[58:61], v[150:153], v[180:183], v[58:61]
	v_mfma_f32_16x16x32_bf16 v[50:53], v[142:145], v[190:193], v[50:53]
	v_mfma_f32_16x16x32_bf16 v[42:45], v[150:153], v[190:193], v[42:45]
	v_mfma_f32_16x16x32_bf16 v[34:37], v[142:145], v[198:201], v[34:37]
	v_mfma_f32_16x16x32_bf16 v[26:29], v[150:153], v[198:201], v[26:29]
	v_mfma_f32_16x16x32_bf16 v[18:21], v[142:145], v[206:209], v[18:21]
	v_mfma_f32_16x16x32_bf16 v[10:13], v[150:153], v[206:209], v[10:13]
	v_mfma_f32_16x16x32_bf16 v[62:65], v[146:149], v[186:189], v[62:65]
	v_mfma_f32_16x16x32_bf16 v[58:61], v[158:161], v[186:189], v[58:61]
	v_mfma_f32_16x16x32_bf16 v[50:53], v[146:149], v[194:197], v[50:53]
	v_mfma_f32_16x16x32_bf16 v[42:45], v[158:161], v[194:197], v[42:45]
	v_mfma_f32_16x16x32_bf16 v[34:37], v[146:149], v[202:205], v[34:37]
	v_mfma_f32_16x16x32_bf16 v[26:29], v[158:161], v[202:205], v[26:29]
	v_mfma_f32_16x16x32_bf16 v[18:21], v[146:149], v[210:213], v[18:21]
	v_mfma_f32_16x16x32_bf16 v[10:13], v[158:161], v[210:213], v[10:13]
	s_setprio 0
	s_setprio 1
	v_mfma_f32_16x16x32_bf16 v[54:57], v[162:165], v[180:183], v[54:57]
	v_mfma_f32_16x16x32_bf16 v[46:49], v[170:173], v[180:183], v[46:49]
	v_mfma_f32_16x16x32_bf16 v[38:41], v[162:165], v[190:193], v[38:41]
	v_mfma_f32_16x16x32_bf16 v[30:33], v[170:173], v[190:193], v[30:33]
	v_mfma_f32_16x16x32_bf16 v[22:25], v[162:165], v[198:201], v[22:25]
	v_mfma_f32_16x16x32_bf16 v[14:17], v[170:173], v[198:201], v[14:17]
	v_mfma_f32_16x16x32_bf16 v[6:9], v[162:165], v[206:209], v[6:9]
	v_mfma_f32_16x16x32_bf16 v[2:5], v[170:173], v[206:209], v[2:5]
	v_mfma_f32_16x16x32_bf16 v[54:57], v[166:169], v[186:189], v[54:57]
	v_mfma_f32_16x16x32_bf16 v[46:49], v[174:177], v[186:189], v[46:49]
	v_mfma_f32_16x16x32_bf16 v[38:41], v[166:169], v[194:197], v[38:41]
	v_mfma_f32_16x16x32_bf16 v[30:33], v[174:177], v[194:197], v[30:33]
	v_mfma_f32_16x16x32_bf16 v[22:25], v[166:169], v[202:205], v[22:25]
	v_mfma_f32_16x16x32_bf16 v[14:17], v[174:177], v[202:205], v[14:17]
	v_mfma_f32_16x16x32_bf16 v[6:9], v[166:169], v[210:213], v[6:9]
	v_mfma_f32_16x16x32_bf16 v[2:5], v[174:177], v[210:213], v[2:5]
	s_setprio 0
	s_barrier
	s_add_i32 s51, s51, 2
	s_add_u32 s49, s49, 0x100
	s_addc_u32 s50, s50, 0
	s_cmp_gt_u32 s51, 41
	s_mov_b64 s[20:21], s[22:23]
	s_cbranch_scc0 .LBB0_1330
	s_and_b64 vcc, exec, s[16:17]
	s_cbranch_vccz .LBB0_1333
	s_barrier

; #define PG8_STAGE(bufoff, gbase, voff) do { _Pragma("unroll") for (int _i = 0; _i < 2; ++_i) \
;         __builtin_amdgcn_global_load_lds((const unsigned*)((const char*)(gbase) + (voff)[_i]), (PG8_LAS unsigned*)(lds + (bufoff) + ldsw + _i * 8192), 16, 0, 0); } while (0)
; #define PG8_LDA(dst, b, h) do { _Pragma("unroll") for (int m = 0; m < 4; ++m) _Pragma("unroll") for (int k = 0; k < 2; ++k) dst[m][k] = *(const PG8_LAS bf16x8*)(lds + PG8_SA(b, h) + aoff + m * 2048 + k * 1024); } while (0)
; #define PG8_LDB(dst, b, h) do { _Pragma("unroll") for (int n = 0; n < 2; ++n) _Pragma("unroll") for (int k = 0; k < 2; ++k) dst[n][k] = *(const PG8_LAS bf16x8*)(lds + PG8_SB(b, h) + boff + n * 2048 + k * 1024); } while (0)
; #define PG8_MMA(ai, bj, At, Bt) do { __builtin_amdgcn_s_setprio(1); _Pragma("unroll") for (int m = 0; m < 4; ++m) _Pragma("unroll") for (int n = 0; n < 2; ++n) _Pragma("unroll") for (int k = 0; k < 2; ++k) \
;         acc[ai][bj][m][n] = __builtin_amdgcn_mfma_f32_16x16x32_bf16(Bt[n][k], At[m][k], acc[ai][bj][m][n], 0, 0, 0); __builtin_amdgcn_s_setprio(0); } while (0)
; #define PG8_WAIT_V(n) asm volatile("s_waitcnt vmcnt(" #n ")" ::: "memory")
; #define PG8_BAR __builtin_amdgcn_s_barrier()
; template <class Epi, class Sched, bool ALIGN_EPI = false, bool SP2 = false>
; __device__ __forceinline__ void gemm_phase(PG8_LAS unsigned char* lds, const Gemm g, const Sched& S, const Epi& E) {
;     ...
;         for (int t = 0; t < nt; t += 2) {
;             const bool last = (t == nt - 2);
;             const char* a1 = cA + (size_t)(t + 1) * kstep;
;             const char* a2 = last ? nA : cA + (size_t)(t + 2) * kstep; const char* b2 = last ? nB : cB + (size_t)(t + 2) * kstep;
;             const char* a3 = a2 + kstep; const char* b3 = b2 + kstep;
;             if (last && has_next) S.a_ready(nxt);
;             if constexpr (SP2) {
;             PG8_LDB(B0, 0, 0); PG8_LDB(B1, 0, 1); PG8_SCHED; PG8_LDA(At, 0, 0); PG8_STAGE(PG8_SA(1, 1), a1 + hstep, voffA);
;             PG8_WAIT_V(8); PG8_WAIT_L(0); PG8_BAR; PG8_MMA(0, 0, At, B0); PG8_MMA(0, 1, At, B1); PG8_BAR; PG8_SCHED;
;             PG8_LDA(At, 0, 1); PG8_STAGE(PG8_SB(0, 0), b2, voffB); PG8_STAGE(PG8_SB(0, 1), b2 + hstep, voffB); PG8_STAGE(PG8_SA(0, 0), a2, voffA);
;             PG8_WAIT_V(8); PG8_WAIT_L(0); PG8_BAR; PG8_MMA(1, 0, At, B0); PG8_MMA(1, 1, At, B1); PG8_BAR; PG8_SCHED;
.LBB0_1360:
	s_add_u32 s20, s18, 0x100
	s_addc_u32 s21, s19, 0
	s_add_i32 s50, 0, 0x10000
	s_cmp_eq_u32 s49, 40
	s_cselect_b32 s25, s7, s21
	s_cselect_b32 s24, s6, s20
	v_add_u32_e32 v146, s50, v148
	s_cselect_b32 s23, s17, s48
	s_cselect_b32 s22, s16, s47
	s_add_i32 s51, 0, 0x14000
	ds_read_b128 v[142:145], v146
	ds_read_b128 v[152:155], v146 offset:1024
	ds_read_b128 v[156:159], v146 offset:2048
	ds_read_b128 v[160:163], v146 offset:3072
	v_add_u32_e32 v146, s51, v148
	ds_read_b128 v[164:167], v146
	ds_read_b128 v[168:171], v146 offset:1024
	ds_read_b128 v[172:175], v146 offset:2048
	ds_read_b128 v[180:183], v146 offset:3072
	v_lshl_add_u64 v[146:147], s[18:19], 0, v[138:139]
	s_add_i32 m0, s33, 0xc000
	ds_read_b128 v[186:189], v150
	ds_read_b128 v[190:193], v150 offset:1024
	ds_read_b128 v[194:197], v150 offset:2048
	ds_read_b128 v[198:201], v150 offset:3072
	ds_read_b128 v[202:205], v150 offset:4096
	ds_read_b128 v[206:209], v150 offset:5120
	ds_read_b128 v[210:213], v150 offset:6144
	ds_read_b128 v[214:217], v150 offset:7168
	global_load_lds_dwordx4 v[146:147], off
	v_lshl_add_u64 v[146:147], s[18:19], 0, v[140:141]
	s_add_i32 m0, s33, 0xe000
	s_nop 0
	global_load_lds_dwordx4 v[146:147], off
	s_waitcnt vmcnt(8)
	s_waitcnt lgkmcnt(0)
	s_barrier
	s_setprio 1
	v_mfma_f32_16x16x32_bf16 v[126:129], v[142:145], v[186:189], v[126:129]
	v_mfma_f32_16x16x32_bf16 v[122:125], v[156:159], v[186:189], v[122:125]
	v_mfma_f32_16x16x32_bf16 v[114:117], v[142:145], v[194:197], v[114:117]
	v_mfma_f32_16x16x32_bf16 v[106:109], v[156:159], v[194:197], v[106:109]
	v_mfma_f32_16x16x32_bf16 v[98:101], v[142:145], v[202:205], v[98:101]
	v_mfma_f32_16x16x32_bf16 v[90:93], v[156:159], v[202:205], v[90:93]
	v_mfma_f32_16x16x32_bf16 v[82:85], v[142:145], v[210:213], v[82:85]
	v_mfma_f32_16x16x32_bf16 v[74:77], v[156:159], v[210:213], v[74:77]
	v_mfma_f32_16x16x32_bf16 v[126:129], v[152:155], v[190:193], v[126:129]
	v_mfma_f32_16x16x32_bf16 v[122:125], v[160:163], v[190:193], v[122:125]
	v_mfma_f32_16x16x32_bf16 v[114:117], v[152:155], v[198:201], v[114:117]
	v_mfma_f32_16x16x32_bf16 v[106:109], v[160:163], v[198:201], v[106:109]
	v_mfma_f32_16x16x32_bf16 v[98:101], v[152:155], v[206:209], v[98:101]
	v_mfma_f32_16x16x32_bf16 v[90:93], v[160:163], v[206:209], v[90:93]
	v_mfma_f32_16x16x32_bf16 v[82:85], v[152:155], v[214:217], v[82:85]
	v_mfma_f32_16x16x32_bf16 v[74:77], v[160:163], v[214:217], v[74:77]
	s_setprio 0
	s_setprio 1
	v_mfma_f32_16x16x32_bf16 v[118:121], v[164:167], v[186:189], v[118:121]
	v_mfma_f32_16x16x32_bf16 v[110:113], v[172:175], v[186:189], v[110:113]
	v_mfma_f32_16x16x32_bf16 v[102:105], v[164:167], v[194:197], v[102:105]
	v_mfma_f32_16x16x32_bf16 v[94:97], v[172:175], v[194:197], v[94:97]
	v_mfma_f32_16x16x32_bf16 v[86:89], v[164:167], v[202:205], v[86:89]
	v_mfma_f32_16x16x32_bf16 v[78:81], v[172:175], v[202:205], v[78:81]
	v_mfma_f32_16x16x32_bf16 v[70:73], v[164:167], v[210:213], v[70:73]
	v_mfma_f32_16x16x32_bf16 v[66:69], v[172:175], v[210:213], v[66:69]
	v_mfma_f32_16x16x32_bf16 v[118:121], v[168:171], v[190:193], v[118:121]
	v_mfma_f32_16x16x32_bf16 v[110:113], v[180:183], v[190:193], v[110:113]
	v_mfma_f32_16x16x32_bf16 v[102:105], v[168:171], v[198:201], v[102:105]
	v_mfma_f32_16x16x32_bf16 v[94:97], v[180:183], v[198:201], v[94:97]
	v_mfma_f32_16x16x32_bf16 v[86:89], v[168:171], v[206:209], v[86:89]
	v_mfma_f32_16x16x32_bf16 v[78:81], v[180:183], v[206:209], v[78:81]
	v_mfma_f32_16x16x32_bf16 v[70:73], v[168:171], v[214:217], v[70:73]
	v_mfma_f32_16x16x32_bf16 v[66:69], v[180:183], v[214:217], v[66:69]
	s_setprio 0
	s_barrier
	s_add_i32 s18, s50, s27
	v_lshl_add_u64 v[146:147], s[22:23], 0, v[132:133]
	s_mov_b32 m0, s18
	ds_read_b128 v[186:189], v150 offset:16384
	ds_read_b128 v[190:193], v150 offset:17408
	ds_read_b128 v[194:197], v150 offset:18432
	ds_read_b128 v[198:201], v150 offset:19456
	ds_read_b128 v[202:205], v150 offset:20480
	ds_read_b128 v[206:209], v150 offset:21504
	ds_read_b128 v[210:213], v150 offset:22528
	ds_read_b128 v[214:217], v150 offset:23552
	global_load_lds_dwordx4 v[146:147], off
	s_add_i32 m0, s18, 0x2000
	s_add_u32 s18, s22, 0xb0000
	v_lshl_add_u64 v[176:177], s[22:23], 0, v[136:137]
	s_addc_u32 s19, s23, 0
	s_add_i32 s50, s51, s27
	global_load_lds_dwordx4 v[176:177], off
	v_lshl_add_u64 v[218:219], s[18:19], 0, v[132:133]
	s_mov_b32 m0, s50
	v_lshl_add_u64 v[220:221], s[24:25], 0, v[134:135]
	global_load_lds_dwordx4 v[218:219], off
	v_lshl_add_u64 v[218:219], s[18:19], 0, v[136:137]
	s_add_i32 m0, s50, 0x2000
	s_nop 0
	global_load_lds_dwordx4 v[218:219], off
	v_lshl_add_u64 v[218:219], s[24:25], 0, v[130:131]
	s_mov_b32 m0, s33
	s_nop 0
	global_load_lds_dwordx4 v[218:219], off
	s_mov_b32 m0, s36
	s_nop 0
	global_load_lds_dwordx4 v[220:221], off
	s_waitcnt vmcnt(8)
	s_waitcnt lgkmcnt(0)
	s_barrier
; #define PG8_STAGE(bufoff, gbase, voff) do { _Pragma("unroll") for (int _i = 0; _i < 2; ++_i) \
;         __builtin_amdgcn_global_load_lds((const unsigned*)((const char*)(gbase) + (voff)[_i]), (PG8_LAS unsigned*)(lds + (bufoff) + ldsw + _i * 8192), 16, 0, 0); } while (0)
; #define PG8_LDA(dst, b, h) do { _Pragma("unroll") for (int m = 0; m < 4; ++m) _Pragma("unroll") for (int k = 0; k < 2; ++k) dst[m][k] = *(const PG8_LAS bf16x8*)(lds + PG8_SA(b, h) + aoff + m * 2048 + k * 1024); } while (0)
; #define PG8_LDB(dst, b, h) do { _Pragma("unroll") for (int n = 0; n < 2; ++n) _Pragma("unroll") for (int k = 0; k < 2; ++k) dst[n][k] = *(const PG8_LAS bf16x8*)(lds + PG8_SB(b, h) + boff + n * 2048 + k * 1024); } while (0)
; #define PG8_MMA(ai, bj, At, Bt) do { __builtin_amdgcn_s_setprio(1); _Pragma("unroll") for (int m = 0; m < 4; ++m) _Pragma("unroll") for (int n = 0; n < 2; ++n) _Pragma("unroll") for (int k = 0; k < 2; ++k) \
;         acc[ai][bj][m][n] = __builtin_amdgcn_mfma_f32_16x16x32_bf16(Bt[n][k], At[m][k], acc[ai][bj][m][n], 0, 0, 0); __builtin_amdgcn_s_setprio(0); } while (0)
; #define PG8_WAIT_V(n) asm volatile("s_waitcnt vmcnt(" #n ")" ::: "memory")
; #define PG8_WAIT_L(n) asm volatile("s_waitcnt lgkmcnt(" #n ")" ::: "memory")
; #define PG8_BAR __builtin_amdgcn_s_barrier()
; #define PG8_SCHED __builtin_amdgcn_sched_barrier(0)
; template <class Epi, class Sched, bool ALIGN_EPI = false, bool SP2 = false>
; __device__ __forceinline__ void gemm_phase(PG8_LAS unsigned char* lds, const Gemm g, const Sched& S, const Epi& E) {
;     ...
;             PG8_WAIT_V(8); PG8_WAIT_L(0); PG8_BAR; PG8_MMA(1, 0, At, B0); PG8_MMA(1, 1, At, B1); PG8_BAR; PG8_SCHED;
;             PG8_LDB(B0, 1, 0); PG8_LDB(B1, 1, 1); PG8_SCHED; PG8_LDA(At, 1, 0); PG8_STAGE(PG8_SA(0, 1), a2 + hstep, voffA);
;             PG8_WAIT_V(8); PG8_WAIT_L(0); PG8_BAR; PG8_MMA(0, 0, At, B0); PG8_MMA(0, 1, At, B1); PG8_BAR; PG8_SCHED;
	s_setprio 1
	v_mfma_f32_16x16x32_bf16 v[62:65], v[142:145], v[186:189], v[62:65]
	v_mfma_f32_16x16x32_bf16 v[58:61], v[156:159], v[186:189], v[58:61]
	v_mfma_f32_16x16x32_bf16 v[50:53], v[142:145], v[194:197], v[50:53]
	v_mfma_f32_16x16x32_bf16 v[42:45], v[156:159], v[194:197], v[42:45]
	v_mfma_f32_16x16x32_bf16 v[34:37], v[142:145], v[202:205], v[34:37]
	v_mfma_f32_16x16x32_bf16 v[26:29], v[156:159], v[202:205], v[26:29]
	v_mfma_f32_16x16x32_bf16 v[18:21], v[142:145], v[210:213], v[18:21]
	v_mfma_f32_16x16x32_bf16 v[10:13], v[156:159], v[210:213], v[10:13]
	v_mfma_f32_16x16x32_bf16 v[62:65], v[152:155], v[190:193], v[62:65]
	v_mfma_f32_16x16x32_bf16 v[58:61], v[160:163], v[190:193], v[58:61]
	v_mfma_f32_16x16x32_bf16 v[50:53], v[152:155], v[198:201], v[50:53]
	v_mfma_f32_16x16x32_bf16 v[42:45], v[160:163], v[198:201], v[42:45]
	v_mfma_f32_16x16x32_bf16 v[34:37], v[152:155], v[206:209], v[34:37]
	v_mfma_f32_16x16x32_bf16 v[26:29], v[160:163], v[206:209], v[26:29]
	v_mfma_f32_16x16x32_bf16 v[18:21], v[152:155], v[214:217], v[18:21]
	v_mfma_f32_16x16x32_bf16 v[10:13], v[160:163], v[214:217], v[10:13]
	s_setprio 0
	s_setprio 1
	v_mfma_f32_16x16x32_bf16 v[54:57], v[164:167], v[186:189], v[54:57]
	v_mfma_f32_16x16x32_bf16 v[46:49], v[172:175], v[186:189], v[46:49]
	v_mfma_f32_16x16x32_bf16 v[38:41], v[164:167], v[194:197], v[38:41]
	v_mfma_f32_16x16x32_bf16 v[30:33], v[172:175], v[194:197], v[30:33]
	v_mfma_f32_16x16x32_bf16 v[22:25], v[164:167], v[202:205], v[22:25]
	v_mfma_f32_16x16x32_bf16 v[14:17], v[172:175], v[202:205], v[14:17]
	v_mfma_f32_16x16x32_bf16 v[6:9], v[164:167], v[210:213], v[6:9]
	v_mfma_f32_16x16x32_bf16 v[2:5], v[172:175], v[210:213], v[2:5]
	v_mfma_f32_16x16x32_bf16 v[54:57], v[168:171], v[190:193], v[54:57]
	v_mfma_f32_16x16x32_bf16 v[46:49], v[180:183], v[190:193], v[46:49]
	v_mfma_f32_16x16x32_bf16 v[38:41], v[168:171], v[198:201], v[38:41]
	v_mfma_f32_16x16x32_bf16 v[30:33], v[180:183], v[198:201], v[30:33]
	v_mfma_f32_16x16x32_bf16 v[22:25], v[168:171], v[206:209], v[22:25]
	v_mfma_f32_16x16x32_bf16 v[14:17], v[180:183], v[206:209], v[14:17]
	v_mfma_f32_16x16x32_bf16 v[6:9], v[168:171], v[214:217], v[6:9]
	v_mfma_f32_16x16x32_bf16 v[2:5], v[180:183], v[214:217], v[2:5]
	s_setprio 0
	s_barrier
	s_add_i32 s50, 0, 0x18000
	v_add_u32_e32 v151, s50, v148
	s_add_i32 s51, 0, 0x1c000
	ds_read_b128 v[142:145], v151
	ds_read_b128 v[152:155], v151 offset:1024
	ds_read_b128 v[156:159], v151 offset:2048
	ds_read_b128 v[160:163], v151 offset:3072
	v_add_u32_e32 v151, s51, v148
	ds_read_b128 v[164:167], v151
	ds_read_b128 v[168:171], v151 offset:1024
	ds_read_b128 v[172:175], v151 offset:2048
	ds_read_b128 v[180:183], v151 offset:3072
	s_add_u32 s18, s24, 0xb0000
	s_addc_u32 s19, s25, 0
	s_mov_b32 m0, s37
	v_lshl_add_u64 v[222:223], s[18:19], 0, v[130:131]
	ds_read_b128 v[186:189], v150 offset:32768
	ds_read_b128 v[190:193], v150 offset:33792
	ds_read_b128 v[194:197], v150 offset:34816
	ds_read_b128 v[198:201], v150 offset:35840
	ds_read_b128 v[202:205], v150 offset:36864
	ds_read_b128 v[206:209], v150 offset:37888
	ds_read_b128 v[210:213], v150 offset:38912
	ds_read_b128 v[214:217], v150 offset:39936
	global_load_lds_dwordx4 v[222:223], off
	v_lshl_add_u64 v[222:223], s[18:19], 0, v[134:135]
	s_mov_b32 m0, s38
	s_nop 0
	global_load_lds_dwordx4 v[222:223], off
	s_waitcnt vmcnt(8)
	s_waitcnt lgkmcnt(0)
	s_barrier
	s_setprio 1
	v_mfma_f32_16x16x32_bf16 v[126:129], v[142:145], v[186:189], v[126:129]
	v_mfma_f32_16x16x32_bf16 v[122:125], v[156:159], v[186:189], v[122:125]
	v_mfma_f32_16x16x32_bf16 v[114:117], v[142:145], v[194:197], v[114:117]
	v_mfma_f32_16x16x32_bf16 v[106:109], v[156:159], v[194:197], v[106:109]
	v_mfma_f32_16x16x32_bf16 v[98:101], v[142:145], v[202:205], v[98:101]
	v_mfma_f32_16x16x32_bf16 v[90:93], v[156:159], v[202:205], v[90:93]
	v_mfma_f32_16x16x32_bf16 v[82:85], v[142:145], v[210:213], v[82:85]
	v_mfma_f32_16x16x32_bf16 v[74:77], v[156:159], v[210:213], v[74:77]
	v_mfma_f32_16x16x32_bf16 v[126:129], v[152:155], v[190:193], v[126:129]
	v_mfma_f32_16x16x32_bf16 v[122:125], v[160:163], v[190:193], v[122:125]
	v_mfma_f32_16x16x32_bf16 v[114:117], v[152:155], v[198:201], v[114:117]
	v_mfma_f32_16x16x32_bf16 v[106:109], v[160:163], v[198:201], v[106:109]
	v_mfma_f32_16x16x32_bf16 v[98:101], v[152:155], v[206:209], v[98:101]
	v_mfma_f32_16x16x32_bf16 v[90:93], v[160:163], v[206:209], v[90:93]
	v_mfma_f32_16x16x32_bf16 v[82:85], v[152:155], v[214:217], v[82:85]
	v_mfma_f32_16x16x32_bf16 v[74:77], v[160:163], v[214:217], v[74:77]
	s_setprio 0
	s_setprio 1
	v_mfma_f32_16x16x32_bf16 v[118:121], v[164:167], v[186:189], v[118:121]
	v_mfma_f32_16x16x32_bf16 v[110:113], v[172:175], v[186:189], v[110:113]
	v_mfma_f32_16x16x32_bf16 v[102:105], v[164:167], v[194:197], v[102:105]
	v_mfma_f32_16x16x32_bf16 v[94:97], v[172:175], v[194:197], v[94:97]
	v_mfma_f32_16x16x32_bf16 v[86:89], v[164:167], v[202:205], v[86:89]
	v_mfma_f32_16x16x32_bf16 v[78:81], v[172:175], v[202:205], v[78:81]
	v_mfma_f32_16x16x32_bf16 v[70:73], v[164:167], v[210:213], v[70:73]
	v_mfma_f32_16x16x32_bf16 v[66:69], v[172:175], v[210:213], v[66:69]
	v_mfma_f32_16x16x32_bf16 v[118:121], v[168:171], v[190:193], v[118:121]
	v_mfma_f32_16x16x32_bf16 v[110:113], v[180:183], v[190:193], v[110:113]
	v_mfma_f32_16x16x32_bf16 v[102:105], v[168:171], v[198:201], v[102:105]
	v_mfma_f32_16x16x32_bf16 v[94:97], v[180:183], v[198:201], v[94:97]
	v_mfma_f32_16x16x32_bf16 v[86:89], v[168:171], v[206:209], v[86:89]
	v_mfma_f32_16x16x32_bf16 v[78:81], v[180:183], v[206:209], v[78:81]
	v_mfma_f32_16x16x32_bf16 v[70:73], v[168:171], v[214:217], v[70:73]
	v_mfma_f32_16x16x32_bf16 v[66:69], v[180:183], v[214:217], v[66:69]
	s_setprio 0
	s_barrier
; #define PG8_STAGE(bufoff, gbase, voff) do { _Pragma("unroll") for (int _i = 0; _i < 2; ++_i) \
;         __builtin_amdgcn_global_load_lds((const unsigned*)((const char*)(gbase) + (voff)[_i]), (PG8_LAS unsigned*)(lds + (bufoff) + ldsw + _i * 8192), 16, 0, 0); } while (0)
; #define PG8_WAIT_V(n) asm volatile("s_waitcnt vmcnt(" #n ")" ::: "memory")
; #define PG8_WAIT_L(n) asm volatile("s_waitcnt lgkmcnt(" #n ")" ::: "memory")
; template <class Epi, class Sched, bool ALIGN_EPI = false, bool SP2 = false>
; __device__ __forceinline__ void gemm_phase(PG8_LAS unsigned char* lds, const Gemm g, const Sched& S, const Epi& E) {
;     ...
;             PG8_LDA(At, 1, 1); PG8_STAGE(PG8_SB(1, 0), b3, voffB); PG8_STAGE(PG8_SB(1, 1), b3 + hstep, voffB); PG8_STAGE(PG8_SA(1, 0), a3, voffA);
;             PG8_WAIT_V(8); PG8_WAIT_L(0); PG8_BAR; PG8_MMA(1, 0, At, B0); PG8_MMA(1, 1, At, B1); PG8_BAR; PG8_SCHED;
;             } else {
;             PG8_LDB(B0, 0, 0); PG8_SCHED; PG8_LDA(At, 0, 0); PG8_STAGE(PG8_SA(1, 1), a1 + hstep, voffA);
;             PG8_WAIT_L(8); PG8_BAR; PG8_WAIT_L(0); PG8_MMA(0, 0, At, B0); PG8_BAR; PG8_SCHED;
;             PG8_LDB(B1, 0, 1); PG8_STAGE(PG8_SB(0, 0), b2, voffB);
;             PG8_BAR; PG8_WAIT_L(0); PG8_MMA(0, 1, At, B1); PG8_BAR;
;             PG8_LDA(At, 0, 1); PG8_STAGE(PG8_SA(0, 0), a2, voffA);
;             PG8_BAR; PG8_WAIT_L(0); PG8_MMA(1, 0, At, B0); PG8_BAR; PG8_SCHED;
;             PG8_STAGE(PG8_SB(0, 1), b2 + hstep, voffB);
;             PG8_WAIT_V(6); PG8_BAR; PG8_MMA(1, 1, At, B1); PG8_BAR;
;             PG8_LDB(B0, 1, 0); PG8_SCHED; PG8_LDA(At, 1, 0); PG8_STAGE(PG8_SA(0, 1), a2 + hstep, voffA);
;             PG8_WAIT_L(8); PG8_BAR; PG8_WAIT_L(0); PG8_MMA(0, 0, At, B0); PG8_BAR; PG8_SCHED;
;             PG8_LDB(B1, 1, 1); PG8_STAGE(PG8_SB(1, 0), b3, voffB);
;             PG8_BAR; PG8_WAIT_L(0); PG8_MMA(0, 1, At, B1); PG8_BAR;
;             PG8_LDA(At, 1, 1); PG8_STAGE(PG8_SA(1, 0), a3, voffA);
;             PG8_BAR; PG8_WAIT_L(0); PG8_MMA(1, 0, At, B0); PG8_BAR; PG8_SCHED;
;             PG8_STAGE(PG8_SB(1, 1), b3 + hstep, voffB);
;             PG8_WAIT_V(6); PG8_BAR; PG8_MMA(1, 1, At, B1); PG8_BAR;
;             }
;         }
;         if constexpr (ALIGN_EPI) { if (wr == 0) PG8_BAR; }
;         if constexpr (!Epi::AFTER_DRAIN) { E(acc, cur, wr, wc, fr, fq); S.done(cur); }
;         if (!has_next) break;
	s_add_i32 s18, s50, s27
	v_lshl_add_u64 v[146:147], v[146:147], 0, s[80:81]
	s_mov_b32 m0, s18
	ds_read_b128 v[186:189], v150 offset:49152
	ds_read_b128 v[190:193], v150 offset:50176
	ds_read_b128 v[194:197], v150 offset:51200
	ds_read_b128 v[198:201], v150 offset:52224
	ds_read_b128 v[202:205], v150 offset:53248
	ds_read_b128 v[206:209], v150 offset:54272
	ds_read_b128 v[210:213], v150 offset:55296
	ds_read_b128 v[214:217], v150 offset:56320
	global_load_lds_dwordx4 v[146:147], off
	s_add_i32 m0, s18, 0x2000
	s_add_u32 s18, s22, 0xb0080
	v_lshl_add_u64 v[146:147], v[176:177], 0, s[80:81]
	s_addc_u32 s19, s23, 0
	s_add_i32 s22, s51, s27
	global_load_lds_dwordx4 v[146:147], off
	v_lshl_add_u64 v[146:147], s[18:19], 0, v[132:133]
	s_mov_b32 m0, s22
	s_nop 0
	global_load_lds_dwordx4 v[146:147], off
	v_lshl_add_u64 v[146:147], s[18:19], 0, v[136:137]
	s_add_i32 m0, s22, 0x2000
	s_nop 0
	global_load_lds_dwordx4 v[146:147], off
	v_lshl_add_u64 v[146:147], v[218:219], 0, s[80:81]
	s_mov_b32 m0, s39
	s_nop 0
	global_load_lds_dwordx4 v[146:147], off
	v_lshl_add_u64 v[146:147], v[220:221], 0, s[80:81]
	s_mov_b32 m0, s40
	s_nop 0
	global_load_lds_dwordx4 v[146:147], off
	s_waitcnt vmcnt(8)
	s_waitcnt lgkmcnt(0)
	s_barrier
	s_setprio 1
	v_mfma_f32_16x16x32_bf16 v[62:65], v[142:145], v[186:189], v[62:65]
	v_mfma_f32_16x16x32_bf16 v[58:61], v[156:159], v[186:189], v[58:61]
	v_mfma_f32_16x16x32_bf16 v[50:53], v[142:145], v[194:197], v[50:53]
	v_mfma_f32_16x16x32_bf16 v[42:45], v[156:159], v[194:197], v[42:45]
	v_mfma_f32_16x16x32_bf16 v[34:37], v[142:145], v[202:205], v[34:37]
	v_mfma_f32_16x16x32_bf16 v[26:29], v[156:159], v[202:205], v[26:29]
	v_mfma_f32_16x16x32_bf16 v[18:21], v[142:145], v[210:213], v[18:21]
	v_mfma_f32_16x16x32_bf16 v[10:13], v[156:159], v[210:213], v[10:13]
	v_mfma_f32_16x16x32_bf16 v[62:65], v[152:155], v[190:193], v[62:65]
	v_mfma_f32_16x16x32_bf16 v[58:61], v[160:163], v[190:193], v[58:61]
	v_mfma_f32_16x16x32_bf16 v[50:53], v[152:155], v[198:201], v[50:53]
	v_mfma_f32_16x16x32_bf16 v[42:45], v[160:163], v[198:201], v[42:45]
	v_mfma_f32_16x16x32_bf16 v[34:37], v[152:155], v[206:209], v[34:37]
	v_mfma_f32_16x16x32_bf16 v[26:29], v[160:163], v[206:209], v[26:29]
	v_mfma_f32_16x16x32_bf16 v[18:21], v[152:155], v[214:217], v[18:21]
	v_mfma_f32_16x16x32_bf16 v[10:13], v[160:163], v[214:217], v[10:13]
	s_setprio 0
	s_setprio 1
	v_mfma_f32_16x16x32_bf16 v[54:57], v[164:167], v[186:189], v[54:57]
	v_mfma_f32_16x16x32_bf16 v[46:49], v[172:175], v[186:189], v[46:49]
	v_mfma_f32_16x16x32_bf16 v[38:41], v[164:167], v[194:197], v[38:41]
	v_mfma_f32_16x16x32_bf16 v[30:33], v[172:175], v[194:197], v[30:33]
	v_mfma_f32_16x16x32_bf16 v[22:25], v[164:167], v[202:205], v[22:25]
	v_mfma_f32_16x16x32_bf16 v[14:17], v[172:175], v[202:205], v[14:17]
	v_mfma_f32_16x16x32_bf16 v[6:9], v[164:167], v[210:213], v[6:9]
	v_mfma_f32_16x16x32_bf16 v[2:5], v[172:175], v[210:213], v[2:5]
	v_mfma_f32_16x16x32_bf16 v[54:57], v[168:171], v[190:193], v[54:57]
	v_mfma_f32_16x16x32_bf16 v[46:49], v[180:183], v[190:193], v[46:49]
	v_mfma_f32_16x16x32_bf16 v[38:41], v[168:171], v[198:201], v[38:41]
	v_mfma_f32_16x16x32_bf16 v[30:33], v[180:183], v[198:201], v[30:33]
	v_mfma_f32_16x16x32_bf16 v[22:25], v[168:171], v[206:209], v[22:25]
	v_mfma_f32_16x16x32_bf16 v[14:17], v[180:183], v[206:209], v[14:17]
	v_mfma_f32_16x16x32_bf16 v[6:9], v[168:171], v[214:217], v[6:9]
	v_mfma_f32_16x16x32_bf16 v[2:5], v[180:183], v[214:217], v[2:5]
	s_setprio 0
	s_barrier
	s_add_i32 s49, s49, 2
	s_add_u32 s47, s47, 0x100
	s_addc_u32 s48, s48, 0
	s_cmp_gt_u32 s49, 41
	s_mov_b64 s[18:19], s[20:21]
	s_cbranch_scc0 .LBB0_1360
	s_and_b64 vcc, exec, s[14:15]
	s_cbranch_vccz .LBB0_1363
	s_barrier
